# A/B: all per-cluster s_setprio flips deleted from the GEMM K-loops (on top of trimmed hand-off version)
# speedup vs baseline: 1.0027x; 1.0027x over previous
; #define PG8_STAGE(bufoff, gbase, voff) do { _Pragma("unroll") for (int _i = 0; _i < 2; ++_i) \
;         __builtin_amdgcn_global_load_lds((const unsigned*)((const char*)(gbase) + (voff)[_i]), (PG8_LAS unsigned*)(lds + (bufoff) + ldsw + _i * 8192), 16, 0, 0); } while (0)
; #define PG8_LDA(dst, b, h) do { _Pragma("unroll") for (int m = 0; m < 4; ++m) _Pragma("unroll") for (int k = 0; k < 2; ++k) dst[m][k] = *(const PG8_LAS bf16x8*)(lds + PG8_SA(b, h) + aoff + m * 2048 + k * 1024); } while (0)
; #define PG8_LDB(dst, b, h) do { _Pragma("unroll") for (int n = 0; n < 2; ++n) _Pragma("unroll") for (int k = 0; k < 2; ++k) dst[n][k] = *(const PG8_LAS bf16x8*)(lds + PG8_SB(b, h) + boff + n * 2048 + k * 1024); } while (0)
; #define PG8_MMA(ai, bj, At, Bt) do { __builtin_amdgcn_s_setprio(1); _Pragma("unroll") for (int m = 0; m < 4; ++m) _Pragma("unroll") for (int n = 0; n < 2; ++n) _Pragma("unroll") for (int k = 0; k < 2; ++k) \
;         acc[ai][bj][m][n] = __builtin_amdgcn_mfma_f32_16x16x32_bf16(Bt[n][k], At[m][k], acc[ai][bj][m][n], 0, 0, 0); __builtin_amdgcn_s_setprio(0); } while (0)
; #define PG8_WAIT_V(n) asm volatile("s_waitcnt vmcnt(" #n ")" ::: "memory")
; #define PG8_WAIT_L(n) asm volatile("s_waitcnt lgkmcnt(" #n ")" ::: "memory")
; #define PG8_BAR __builtin_amdgcn_s_barrier()
; #define PG8_SCHED __builtin_amdgcn_sched_barrier(0)
; template <class Epi, class Sched, bool ALIGN_EPI = false, bool SP2 = false>
; __device__ __forceinline__ void gemm_phase(PG8_LAS unsigned char* lds, const Gemm g, const Sched& S, const Epi& E) {
;     ...
;             if constexpr (SP2) {
;             PG8_LDB(B0, 0, 0); PG8_LDB(B1, 0, 1); PG8_SCHED; PG8_LDA(At, 0, 0); PG8_STAGE(PG8_SA(1, 1), a1 + hstepA, voffA);
;             PG8_WAIT_V(8); PG8_WAIT_L(0); PG8_BAR; PG8_MMA(0, 0, At, B0); PG8_MMA(0, 1, At, B1); PG8_BAR; PG8_SCHED;
;             PG8_LDA(At, 0, 1); PG8_STAGE(PG8_SB(0, 0), b2, voffB); PG8_STAGE(PG8_SB(0, 1), b2 + hstepB, voffB); PG8_STAGE(PG8_SA(0, 0), a2, voffA);
;             PG8_WAIT_V(8); PG8_WAIT_L(0); PG8_BAR; PG8_MMA(1, 0, At, B0); PG8_MMA(1, 1, At, B1); PG8_BAR; PG8_SCHED;
.LBB0_244:
	ds_read_b128 v[152:155], v147
	ds_read_b128 v[156:159], v147 offset:1024
	ds_read_b128 v[160:163], v147 offset:2048
	ds_read_b128 v[164:167], v147 offset:3072
	ds_read_b128 v[168:171], v148
	ds_read_b128 v[172:175], v148 offset:1024
	ds_read_b128 v[176:179], v148 offset:2048
	ds_read_b128 v[180:183], v148 offset:3072
	s_add_u32 s28, s26, 0xfffc0080
	s_addc_u32 s29, s27, -1
	s_cmp_eq_u32 s68, 12
	s_cselect_b32 s31, s15, s29
	s_cselect_b32 s30, s62, s28
	s_cselect_b32 s29, s13, s67
	s_cselect_b32 s28, s63, s66
	v_lshl_add_u64 v[184:185], s[26:27], 0, v[136:137]
	s_add_i32 m0, s25, 0xc000
	ds_read_b128 v[188:191], v149
	ds_read_b128 v[192:195], v149 offset:1024
	ds_read_b128 v[196:199], v149 offset:2048
	ds_read_b128 v[200:203], v149 offset:3072
	ds_read_b128 v[204:207], v149 offset:4096
	ds_read_b128 v[208:211], v149 offset:5120
	ds_read_b128 v[212:215], v149 offset:6144
	ds_read_b128 v[216:219], v149 offset:7168
	global_load_lds_dwordx4 v[184:185], off
	v_lshl_add_u64 v[184:185], s[26:27], 0, v[138:139]
	s_add_i32 m0, s25, 0xe000
	s_nop 0
	global_load_lds_dwordx4 v[184:185], off
	s_waitcnt vmcnt(8) lgkmcnt(0)
	s_barrier
	v_mfma_f32_16x16x32_bf16 v[116:119], v[152:155], v[188:191], v[116:119]
	v_mfma_f32_16x16x32_bf16 v[108:111], v[160:163], v[188:191], v[108:111]
	v_mfma_f32_16x16x32_bf16 v[104:107], v[152:155], v[196:199], v[104:107]
	v_mfma_f32_16x16x32_bf16 v[100:103], v[160:163], v[196:199], v[100:103]
	v_mfma_f32_16x16x32_bf16 v[92:95], v[152:155], v[204:207], v[92:95]
	v_mfma_f32_16x16x32_bf16 v[84:87], v[160:163], v[204:207], v[84:87]
	v_mfma_f32_16x16x32_bf16 v[76:79], v[152:155], v[212:215], v[76:79]
	v_mfma_f32_16x16x32_bf16 v[68:71], v[160:163], v[212:215], v[68:71]
	v_mfma_f32_16x16x32_bf16 v[116:119], v[156:159], v[192:195], v[116:119]
	v_mfma_f32_16x16x32_bf16 v[108:111], v[164:167], v[192:195], v[108:111]
	v_mfma_f32_16x16x32_bf16 v[104:107], v[156:159], v[200:203], v[104:107]
	v_mfma_f32_16x16x32_bf16 v[100:103], v[164:167], v[200:203], v[100:103]
	v_mfma_f32_16x16x32_bf16 v[92:95], v[156:159], v[208:211], v[92:95]
	v_mfma_f32_16x16x32_bf16 v[84:87], v[164:167], v[208:211], v[84:87]
	v_mfma_f32_16x16x32_bf16 v[76:79], v[156:159], v[216:219], v[76:79]
	v_mfma_f32_16x16x32_bf16 v[68:71], v[164:167], v[216:219], v[68:71]
	v_mfma_f32_16x16x32_bf16 v[124:127], v[168:171], v[188:191], v[124:127]
	v_mfma_f32_16x16x32_bf16 v[120:123], v[176:179], v[188:191], v[120:123]
	v_mfma_f32_16x16x32_bf16 v[112:115], v[168:171], v[196:199], v[112:115]
	v_mfma_f32_16x16x32_bf16 v[96:99], v[176:179], v[196:199], v[96:99]
	v_mfma_f32_16x16x32_bf16 v[88:91], v[168:171], v[204:207], v[88:91]
	v_mfma_f32_16x16x32_bf16 v[80:83], v[176:179], v[204:207], v[80:83]
	v_mfma_f32_16x16x32_bf16 v[72:75], v[168:171], v[212:215], v[72:75]
	v_mfma_f32_16x16x32_bf16 v[64:67], v[176:179], v[212:215], v[64:67]
	v_mfma_f32_16x16x32_bf16 v[124:127], v[172:175], v[192:195], v[124:127]
	v_mfma_f32_16x16x32_bf16 v[120:123], v[180:183], v[192:195], v[120:123]
	v_mfma_f32_16x16x32_bf16 v[112:115], v[172:175], v[200:203], v[112:115]
	v_mfma_f32_16x16x32_bf16 v[96:99], v[180:183], v[200:203], v[96:99]
	v_mfma_f32_16x16x32_bf16 v[88:91], v[172:175], v[208:211], v[88:91]
	v_mfma_f32_16x16x32_bf16 v[80:83], v[180:183], v[208:211], v[80:83]
	v_mfma_f32_16x16x32_bf16 v[72:75], v[172:175], v[216:219], v[72:75]
	v_mfma_f32_16x16x32_bf16 v[64:67], v[180:183], v[216:219], v[64:67]
	s_barrier
	s_add_i32 s58, s46, s36
	v_lshl_add_u64 v[184:185], s[28:29], 0, v[132:133]
	s_mov_b32 m0, s58
	ds_read_b128 v[188:191], v149 offset:16384
	ds_read_b128 v[192:195], v149 offset:17408
	ds_read_b128 v[196:199], v149 offset:18432
	ds_read_b128 v[200:203], v149 offset:19456
	ds_read_b128 v[204:207], v149 offset:20480
	ds_read_b128 v[208:211], v149 offset:21504
	ds_read_b128 v[212:215], v149 offset:22528
	ds_read_b128 v[216:219], v149 offset:23552
	global_load_lds_dwordx4 v[184:185], off
	s_add_i32 m0, s58, 0x2000
	s_add_u32 s58, s28, 0x40000
	v_lshl_add_u64 v[220:221], s[28:29], 0, v[128:129]
	s_addc_u32 s59, s29, 0
	s_add_i32 s69, s47, s36
	global_load_lds_dwordx4 v[220:221], off
	v_lshl_add_u64 v[222:223], s[58:59], 0, v[132:133]
	s_mov_b32 m0, s69
	v_lshl_add_u64 v[224:225], s[30:31], 0, v[130:131]
	global_load_lds_dwordx4 v[222:223], off
	v_lshl_add_u64 v[222:223], s[58:59], 0, v[128:129]
	s_add_i32 m0, s69, 0x2000
	s_nop 0
	global_load_lds_dwordx4 v[222:223], off
	v_lshl_add_u64 v[222:223], s[30:31], 0, v[134:135]
	s_mov_b32 m0, s25
	s_nop 0
	global_load_lds_dwordx4 v[222:223], off
	s_mov_b32 m0, s39
	s_nop 0
	global_load_lds_dwordx4 v[224:225], off
	s_waitcnt vmcnt(8) lgkmcnt(0)
	s_barrier
; #define PG8_STAGE(bufoff, gbase, voff) do { _Pragma("unroll") for (int _i = 0; _i < 2; ++_i) \
;         __builtin_amdgcn_global_load_lds((const unsigned*)((const char*)(gbase) + (voff)[_i]), (PG8_LAS unsigned*)(lds + (bufoff) + ldsw + _i * 8192), 16, 0, 0); } while (0)
; #define PG8_LDA(dst, b, h) do { _Pragma("unroll") for (int m = 0; m < 4; ++m) _Pragma("unroll") for (int k = 0; k < 2; ++k) dst[m][k] = *(const PG8_LAS bf16x8*)(lds + PG8_SA(b, h) + aoff + m * 2048 + k * 1024); } while (0)
; #define PG8_LDB(dst, b, h) do { _Pragma("unroll") for (int n = 0; n < 2; ++n) _Pragma("unroll") for (int k = 0; k < 2; ++k) dst[n][k] = *(const PG8_LAS bf16x8*)(lds + PG8_SB(b, h) + boff + n * 2048 + k * 1024); } while (0)
; #define PG8_MMA(ai, bj, At, Bt) do { __builtin_amdgcn_s_setprio(1); _Pragma("unroll") for (int m = 0; m < 4; ++m) _Pragma("unroll") for (int n = 0; n < 2; ++n) _Pragma("unroll") for (int k = 0; k < 2; ++k) \
;         acc[ai][bj][m][n] = __builtin_amdgcn_mfma_f32_16x16x32_bf16(Bt[n][k], At[m][k], acc[ai][bj][m][n], 0, 0, 0); __builtin_amdgcn_s_setprio(0); } while (0)
; #define PG8_WAIT_V(n) asm volatile("s_waitcnt vmcnt(" #n ")" ::: "memory")
; #define PG8_WAIT_L(n) asm volatile("s_waitcnt lgkmcnt(" #n ")" ::: "memory")
; #define PG8_BAR __builtin_amdgcn_s_barrier()
; #define PG8_SCHED __builtin_amdgcn_sched_barrier(0)
; template <class Epi, class Sched, bool ALIGN_EPI = false, bool SP2 = false>
; __device__ __forceinline__ void gemm_phase(PG8_LAS unsigned char* lds, const Gemm g, const Sched& S, const Epi& E) {
;     ...
;             PG8_WAIT_V(8); PG8_WAIT_L(0); PG8_BAR; PG8_MMA(1, 0, At, B0); PG8_MMA(1, 1, At, B1); PG8_BAR; PG8_SCHED;
;             PG8_LDB(B0, 1, 0); PG8_LDB(B1, 1, 1); PG8_SCHED; PG8_LDA(At, 1, 0); PG8_STAGE(PG8_SA(0, 1), a2 + hstepA, voffA);
;             PG8_WAIT_V(8); PG8_WAIT_L(0); PG8_BAR; PG8_MMA(0, 0, At, B0); PG8_MMA(0, 1, At, B1); PG8_BAR; PG8_SCHED;
	v_mfma_f32_16x16x32_bf16 v[60:63], v[152:155], v[188:191], v[60:63]
	v_mfma_f32_16x16x32_bf16 v[52:55], v[160:163], v[188:191], v[52:55]
	v_mfma_f32_16x16x32_bf16 v[44:47], v[152:155], v[196:199], v[44:47]
	v_mfma_f32_16x16x32_bf16 v[36:39], v[160:163], v[196:199], v[36:39]
	v_mfma_f32_16x16x32_bf16 v[28:31], v[152:155], v[204:207], v[28:31]
	v_mfma_f32_16x16x32_bf16 v[20:23], v[160:163], v[204:207], v[20:23]
	v_mfma_f32_16x16x32_bf16 v[12:15], v[152:155], v[212:215], v[12:15]
	v_mfma_f32_16x16x32_bf16 v[4:7], v[160:163], v[212:215], v[4:7]
	v_mfma_f32_16x16x32_bf16 v[60:63], v[156:159], v[192:195], v[60:63]
	v_mfma_f32_16x16x32_bf16 v[52:55], v[164:167], v[192:195], v[52:55]
	v_mfma_f32_16x16x32_bf16 v[44:47], v[156:159], v[200:203], v[44:47]
	v_mfma_f32_16x16x32_bf16 v[36:39], v[164:167], v[200:203], v[36:39]
	v_mfma_f32_16x16x32_bf16 v[28:31], v[156:159], v[208:211], v[28:31]
	v_mfma_f32_16x16x32_bf16 v[20:23], v[164:167], v[208:211], v[20:23]
	v_mfma_f32_16x16x32_bf16 v[12:15], v[156:159], v[216:219], v[12:15]
	v_mfma_f32_16x16x32_bf16 v[4:7], v[164:167], v[216:219], v[4:7]
	v_mfma_f32_16x16x32_bf16 v[56:59], v[168:171], v[188:191], v[56:59]
	v_mfma_f32_16x16x32_bf16 v[48:51], v[176:179], v[188:191], v[48:51]
	v_mfma_f32_16x16x32_bf16 v[40:43], v[168:171], v[196:199], v[40:43]
	v_mfma_f32_16x16x32_bf16 v[32:35], v[176:179], v[196:199], v[32:35]
	v_mfma_f32_16x16x32_bf16 v[24:27], v[168:171], v[204:207], v[24:27]
	v_mfma_f32_16x16x32_bf16 v[16:19], v[176:179], v[204:207], v[16:19]
	v_mfma_f32_16x16x32_bf16 v[8:11], v[168:171], v[212:215], v[8:11]
	v_mfma_f32_16x16x32_bf16 v[0:3], v[176:179], v[212:215], v[0:3]
	v_mfma_f32_16x16x32_bf16 v[56:59], v[172:175], v[192:195], v[56:59]
	v_mfma_f32_16x16x32_bf16 v[48:51], v[180:183], v[192:195], v[48:51]
	v_mfma_f32_16x16x32_bf16 v[40:43], v[172:175], v[200:203], v[40:43]
	v_mfma_f32_16x16x32_bf16 v[32:35], v[180:183], v[200:203], v[32:35]
	v_mfma_f32_16x16x32_bf16 v[24:27], v[172:175], v[208:211], v[24:27]
	v_mfma_f32_16x16x32_bf16 v[16:19], v[180:183], v[208:211], v[16:19]
	v_mfma_f32_16x16x32_bf16 v[8:11], v[172:175], v[216:219], v[8:11]
	v_mfma_f32_16x16x32_bf16 v[0:3], v[180:183], v[216:219], v[0:3]
	s_barrier
	s_add_i32 s58, 0, 0x18000
	v_add_u32_e32 v151, s58, v145
	s_add_i32 s59, 0, 0x1c000
	ds_read_b128 v[152:155], v151
	ds_read_b128 v[156:159], v151 offset:1024
	ds_read_b128 v[160:163], v151 offset:2048
	ds_read_b128 v[164:167], v151 offset:3072
	v_add_u32_e32 v151, s59, v145
	ds_read_b128 v[168:171], v151
	ds_read_b128 v[172:175], v151 offset:1024
	ds_read_b128 v[176:179], v151 offset:2048
	ds_read_b128 v[180:183], v151 offset:3072
	s_add_u32 s30, s30, 0x40000
	s_addc_u32 s31, s31, 0
	s_mov_b32 m0, s40
	v_lshl_add_u64 v[226:227], s[30:31], 0, v[134:135]
	ds_read_b128 v[188:191], v149 offset:32768
	ds_read_b128 v[192:195], v149 offset:33792
	ds_read_b128 v[196:199], v149 offset:34816
	ds_read_b128 v[200:203], v149 offset:35840
	ds_read_b128 v[204:207], v149 offset:36864
	ds_read_b128 v[208:211], v149 offset:37888
	ds_read_b128 v[212:215], v149 offset:38912
	ds_read_b128 v[216:219], v149 offset:39936
	global_load_lds_dwordx4 v[226:227], off
	v_lshl_add_u64 v[226:227], s[30:31], 0, v[130:131]
	s_mov_b32 m0, s41
	s_nop 0
	global_load_lds_dwordx4 v[226:227], off
	s_waitcnt vmcnt(8) lgkmcnt(0)
	s_barrier
	v_mfma_f32_16x16x32_bf16 v[116:119], v[152:155], v[188:191], v[116:119]
	v_mfma_f32_16x16x32_bf16 v[108:111], v[160:163], v[188:191], v[108:111]
	v_mfma_f32_16x16x32_bf16 v[104:107], v[152:155], v[196:199], v[104:107]
	v_mfma_f32_16x16x32_bf16 v[100:103], v[160:163], v[196:199], v[100:103]
	v_mfma_f32_16x16x32_bf16 v[92:95], v[152:155], v[204:207], v[92:95]
	v_mfma_f32_16x16x32_bf16 v[84:87], v[160:163], v[204:207], v[84:87]
	v_mfma_f32_16x16x32_bf16 v[76:79], v[152:155], v[212:215], v[76:79]
	v_mfma_f32_16x16x32_bf16 v[68:71], v[160:163], v[212:215], v[68:71]
	v_mfma_f32_16x16x32_bf16 v[116:119], v[156:159], v[192:195], v[116:119]
	v_mfma_f32_16x16x32_bf16 v[108:111], v[164:167], v[192:195], v[108:111]
	v_mfma_f32_16x16x32_bf16 v[104:107], v[156:159], v[200:203], v[104:107]
	v_mfma_f32_16x16x32_bf16 v[100:103], v[164:167], v[200:203], v[100:103]
	v_mfma_f32_16x16x32_bf16 v[92:95], v[156:159], v[208:211], v[92:95]
	v_mfma_f32_16x16x32_bf16 v[84:87], v[164:167], v[208:211], v[84:87]
	v_mfma_f32_16x16x32_bf16 v[76:79], v[156:159], v[216:219], v[76:79]
	v_mfma_f32_16x16x32_bf16 v[68:71], v[164:167], v[216:219], v[68:71]
	v_mfma_f32_16x16x32_bf16 v[124:127], v[168:171], v[188:191], v[124:127]
	v_mfma_f32_16x16x32_bf16 v[120:123], v[176:179], v[188:191], v[120:123]
	v_mfma_f32_16x16x32_bf16 v[112:115], v[168:171], v[196:199], v[112:115]
	v_mfma_f32_16x16x32_bf16 v[96:99], v[176:179], v[196:199], v[96:99]
	v_mfma_f32_16x16x32_bf16 v[88:91], v[168:171], v[204:207], v[88:91]
	v_mfma_f32_16x16x32_bf16 v[80:83], v[176:179], v[204:207], v[80:83]
	v_mfma_f32_16x16x32_bf16 v[72:75], v[168:171], v[212:215], v[72:75]
	v_mfma_f32_16x16x32_bf16 v[64:67], v[176:179], v[212:215], v[64:67]
	v_mfma_f32_16x16x32_bf16 v[124:127], v[172:175], v[192:195], v[124:127]
	v_mfma_f32_16x16x32_bf16 v[120:123], v[180:183], v[192:195], v[120:123]
	v_mfma_f32_16x16x32_bf16 v[112:115], v[172:175], v[200:203], v[112:115]
	v_mfma_f32_16x16x32_bf16 v[96:99], v[180:183], v[200:203], v[96:99]
	v_mfma_f32_16x16x32_bf16 v[88:91], v[172:175], v[208:211], v[88:91]
	v_mfma_f32_16x16x32_bf16 v[80:83], v[180:183], v[208:211], v[80:83]
	v_mfma_f32_16x16x32_bf16 v[72:75], v[172:175], v[216:219], v[72:75]
	v_mfma_f32_16x16x32_bf16 v[64:67], v[180:183], v[216:219], v[64:67]
	s_barrier
; #define PG8_STAGE(bufoff, gbase, voff) do { _Pragma("unroll") for (int _i = 0; _i < 2; ++_i) \
;         __builtin_amdgcn_global_load_lds((const unsigned*)((const char*)(gbase) + (voff)[_i]), (PG8_LAS unsigned*)(lds + (bufoff) + ldsw + _i * 8192), 16, 0, 0); } while (0)
; #define PG8_LDA(dst, b, h) do { _Pragma("unroll") for (int m = 0; m < 4; ++m) _Pragma("unroll") for (int k = 0; k < 2; ++k) dst[m][k] = *(const PG8_LAS bf16x8*)(lds + PG8_SA(b, h) + aoff + m * 2048 + k * 1024); } while (0)
; #define PG8_MMA(ai, bj, At, Bt) do { __builtin_amdgcn_s_setprio(1); _Pragma("unroll") for (int m = 0; m < 4; ++m) _Pragma("unroll") for (int n = 0; n < 2; ++n) _Pragma("unroll") for (int k = 0; k < 2; ++k) \
;         acc[ai][bj][m][n] = __builtin_amdgcn_mfma_f32_16x16x32_bf16(Bt[n][k], At[m][k], acc[ai][bj][m][n], 0, 0, 0); __builtin_amdgcn_s_setprio(0); } while (0)
; #define PG8_WAIT_V(n) asm volatile("s_waitcnt vmcnt(" #n ")" ::: "memory")
; #define PG8_WAIT_L(n) asm volatile("s_waitcnt lgkmcnt(" #n ")" ::: "memory")
; #define PG8_BAR __builtin_amdgcn_s_barrier()
; #define PG8_SCHED __builtin_amdgcn_sched_barrier(0)
; template <class Epi, class Sched, bool ALIGN_EPI = false, bool SP2 = false>
; __device__ __forceinline__ void gemm_phase(PG8_LAS unsigned char* lds, const Gemm g, const Sched& S, const Epi& E) {
;     ...
;             PG8_LDA(At, 1, 1); PG8_STAGE(PG8_SB(1, 0), b3, voffB); PG8_STAGE(PG8_SB(1, 1), b3 + hstepB, voffB); PG8_STAGE(PG8_SA(1, 0), a3, voffA);
;             PG8_WAIT_V(8); PG8_WAIT_L(0); PG8_BAR; PG8_MMA(1, 0, At, B0); PG8_MMA(1, 1, At, B1); PG8_BAR; PG8_SCHED;
;     ...
;         if constexpr (ALIGN_EPI) { if (wr == 0) PG8_BAR; }
	s_add_i32 s30, s58, s36
	v_lshl_add_u64 v[184:185], v[184:185], 0, s[8:9]
	s_mov_b32 m0, s30
	ds_read_b128 v[188:191], v149 offset:49152
	ds_read_b128 v[192:195], v149 offset:50176
	ds_read_b128 v[196:199], v149 offset:51200
	ds_read_b128 v[200:203], v149 offset:52224
	ds_read_b128 v[204:207], v149 offset:53248
	ds_read_b128 v[208:211], v149 offset:54272
	ds_read_b128 v[212:215], v149 offset:55296
	ds_read_b128 v[216:219], v149 offset:56320
	global_load_lds_dwordx4 v[184:185], off
	s_add_i32 m0, s30, 0x2000
	s_add_u32 s28, s28, 0x40080
	v_lshl_add_u64 v[184:185], v[220:221], 0, s[8:9]
	s_addc_u32 s29, s29, 0
	s_add_i32 s30, s59, s36
	global_load_lds_dwordx4 v[184:185], off
	v_lshl_add_u64 v[184:185], s[28:29], 0, v[132:133]
	s_mov_b32 m0, s30
	s_nop 0
	global_load_lds_dwordx4 v[184:185], off
	v_lshl_add_u64 v[184:185], s[28:29], 0, v[128:129]
	s_add_i32 m0, s30, 0x2000
	s_nop 0
	global_load_lds_dwordx4 v[184:185], off
	v_lshl_add_u64 v[184:185], v[222:223], 0, s[8:9]
	s_mov_b32 m0, s43
	s_nop 0
	global_load_lds_dwordx4 v[184:185], off
	v_lshl_add_u64 v[184:185], v[224:225], 0, s[8:9]
	s_mov_b32 m0, s44
	s_nop 0
	global_load_lds_dwordx4 v[184:185], off
	s_waitcnt vmcnt(8) lgkmcnt(0)
	s_barrier
	v_mfma_f32_16x16x32_bf16 v[60:63], v[152:155], v[188:191], v[60:63]
	v_mfma_f32_16x16x32_bf16 v[52:55], v[160:163], v[188:191], v[52:55]
	v_mfma_f32_16x16x32_bf16 v[44:47], v[152:155], v[196:199], v[44:47]
	v_mfma_f32_16x16x32_bf16 v[36:39], v[160:163], v[196:199], v[36:39]
	v_mfma_f32_16x16x32_bf16 v[28:31], v[152:155], v[204:207], v[28:31]
	v_mfma_f32_16x16x32_bf16 v[20:23], v[160:163], v[204:207], v[20:23]
	v_mfma_f32_16x16x32_bf16 v[12:15], v[152:155], v[212:215], v[12:15]
	v_mfma_f32_16x16x32_bf16 v[4:7], v[160:163], v[212:215], v[4:7]
	v_mfma_f32_16x16x32_bf16 v[60:63], v[156:159], v[192:195], v[60:63]
	v_mfma_f32_16x16x32_bf16 v[52:55], v[164:167], v[192:195], v[52:55]
	v_mfma_f32_16x16x32_bf16 v[44:47], v[156:159], v[200:203], v[44:47]
	v_mfma_f32_16x16x32_bf16 v[36:39], v[164:167], v[200:203], v[36:39]
	v_mfma_f32_16x16x32_bf16 v[28:31], v[156:159], v[208:211], v[28:31]
	v_mfma_f32_16x16x32_bf16 v[20:23], v[164:167], v[208:211], v[20:23]
	v_mfma_f32_16x16x32_bf16 v[12:15], v[156:159], v[216:219], v[12:15]
	v_mfma_f32_16x16x32_bf16 v[4:7], v[164:167], v[216:219], v[4:7]
	v_mfma_f32_16x16x32_bf16 v[56:59], v[168:171], v[188:191], v[56:59]
	v_mfma_f32_16x16x32_bf16 v[48:51], v[176:179], v[188:191], v[48:51]
	v_mfma_f32_16x16x32_bf16 v[40:43], v[168:171], v[196:199], v[40:43]
	v_mfma_f32_16x16x32_bf16 v[32:35], v[176:179], v[196:199], v[32:35]
	v_mfma_f32_16x16x32_bf16 v[24:27], v[168:171], v[204:207], v[24:27]
	v_mfma_f32_16x16x32_bf16 v[16:19], v[176:179], v[204:207], v[16:19]
	v_mfma_f32_16x16x32_bf16 v[8:11], v[168:171], v[212:215], v[8:11]
	v_mfma_f32_16x16x32_bf16 v[0:3], v[176:179], v[212:215], v[0:3]
	v_mfma_f32_16x16x32_bf16 v[56:59], v[172:175], v[192:195], v[56:59]
	v_mfma_f32_16x16x32_bf16 v[48:51], v[180:183], v[192:195], v[48:51]
	v_mfma_f32_16x16x32_bf16 v[40:43], v[172:175], v[200:203], v[40:43]
	v_mfma_f32_16x16x32_bf16 v[32:35], v[180:183], v[200:203], v[32:35]
	v_mfma_f32_16x16x32_bf16 v[24:27], v[172:175], v[208:211], v[24:27]
	v_mfma_f32_16x16x32_bf16 v[16:19], v[180:183], v[208:211], v[16:19]
	v_mfma_f32_16x16x32_bf16 v[8:11], v[172:175], v[216:219], v[8:11]
	v_mfma_f32_16x16x32_bf16 v[0:3], v[180:183], v[216:219], v[0:3]
	s_barrier
	s_add_i32 s68, s68, 2
	s_add_u32 s26, s26, 0x100
	s_addc_u32 s27, s27, 0
	s_add_u32 s66, s66, 0x100
	s_addc_u32 s67, s67, 0
	s_cmp_gt_u32 s68, 13
	s_cbranch_scc0 .LBB0_244
	s_and_b64 vcc, exec, s[10:11]
	s_cbranch_vccz .LBB0_247
	s_barrier

; #define PG8_STAGE(bufoff, gbase, voff) do { _Pragma("unroll") for (int _i = 0; _i < 2; ++_i) \
;         __builtin_amdgcn_global_load_lds((const unsigned*)((const char*)(gbase) + (voff)[_i]), (PG8_LAS unsigned*)(lds + (bufoff) + ldsw + _i * 8192), 16, 0, 0); } while (0)
; #define PG8_LDA(dst, b, h) do { _Pragma("unroll") for (int m = 0; m < 4; ++m) _Pragma("unroll") for (int k = 0; k < 2; ++k) dst[m][k] = *(const PG8_LAS bf16x8*)(lds + PG8_SA(b, h) + aoff + m * 2048 + k * 1024); } while (0)
; #define PG8_LDB(dst, b, h) do { _Pragma("unroll") for (int n = 0; n < 2; ++n) _Pragma("unroll") for (int k = 0; k < 2; ++k) dst[n][k] = *(const PG8_LAS bf16x8*)(lds + PG8_SB(b, h) + boff + n * 2048 + k * 1024); } while (0)
; #define PG8_MMA(ai, bj, At, Bt) do { __builtin_amdgcn_s_setprio(1); _Pragma("unroll") for (int m = 0; m < 4; ++m) _Pragma("unroll") for (int n = 0; n < 2; ++n) _Pragma("unroll") for (int k = 0; k < 2; ++k) \
;         acc[ai][bj][m][n] = __builtin_amdgcn_mfma_f32_16x16x32_bf16(Bt[n][k], At[m][k], acc[ai][bj][m][n], 0, 0, 0); __builtin_amdgcn_s_setprio(0); } while (0)
; #define PG8_WAIT_V(n) asm volatile("s_waitcnt vmcnt(" #n ")" ::: "memory")
; #define PG8_WAIT_L(n) asm volatile("s_waitcnt lgkmcnt(" #n ")" ::: "memory")
; #define PG8_BAR __builtin_amdgcn_s_barrier()
; #define PG8_SCHED __builtin_amdgcn_sched_barrier(0)
; template <class Epi, class Sched, bool ALIGN_EPI = false, bool SP2 = false>
; __device__ __forceinline__ void gemm_phase(PG8_LAS unsigned char* lds, const Gemm g, const Sched& S, const Epi& E) {
;     ...
;             if constexpr (SP2) {
;             PG8_LDB(B0, 0, 0); PG8_LDB(B1, 0, 1); PG8_SCHED; PG8_LDA(At, 0, 0); PG8_STAGE(PG8_SA(1, 1), a1 + hstepA, voffA);
;             PG8_WAIT_V(8); PG8_WAIT_L(0); PG8_BAR; PG8_MMA(0, 0, At, B0); PG8_MMA(0, 1, At, B1); PG8_BAR; PG8_SCHED;
;             PG8_LDA(At, 0, 1); PG8_STAGE(PG8_SB(0, 0), b2, voffB); PG8_STAGE(PG8_SB(0, 1), b2 + hstepB, voffB); PG8_STAGE(PG8_SA(0, 0), a2, voffA);
;             PG8_WAIT_V(8); PG8_WAIT_L(0); PG8_BAR; PG8_MMA(1, 0, At, B0); PG8_MMA(1, 1, At, B1); PG8_BAR; PG8_SCHED;
.LBB0_318:
	ds_read_b128 v[128:131], v191
	ds_read_b128 v[132:135], v191 offset:1024
	ds_read_b128 v[136:139], v191 offset:2048
	ds_read_b128 v[140:143], v191 offset:3072
	ds_read_b128 v[144:147], v192
	ds_read_b128 v[148:151], v192 offset:1024
	ds_read_b128 v[168:171], v192 offset:2048
	ds_read_b128 v[172:175], v192 offset:3072
	s_add_u32 s28, s26, 0x100
	s_addc_u32 s29, s27, 0
	s_cmp_eq_u32 s72, 40
	s_cselect_b32 s35, s11, s29
	s_cselect_b32 s34, s10, s28
	s_cselect_b32 s31, s23, s71
	s_cselect_b32 s30, s22, s70
	v_lshl_add_u64 v[184:185], s[26:27], 0, v[160:161]
	s_add_i32 m0, s39, 0xc000
	ds_read_b128 v[176:179], v193
	ds_read_b128 v[180:183], v193 offset:1024
	ds_read_b128 v[196:199], v193 offset:2048
	ds_read_b128 v[200:203], v193 offset:3072
	ds_read_b128 v[204:207], v193 offset:4096
	ds_read_b128 v[208:211], v193 offset:5120
	ds_read_b128 v[212:215], v193 offset:6144
	ds_read_b128 v[216:219], v193 offset:7168
	global_load_lds_dwordx4 v[184:185], off
	v_lshl_add_u64 v[184:185], s[26:27], 0, v[162:163]
	s_add_i32 m0, s39, 0xe000
	s_nop 0
	global_load_lds_dwordx4 v[184:185], off
	s_waitcnt vmcnt(8) lgkmcnt(0)
	s_barrier
	v_mfma_f32_16x16x32_bf16 v[124:127], v[128:131], v[176:179], v[124:127]
	v_mfma_f32_16x16x32_bf16 v[120:123], v[136:139], v[176:179], v[120:123]
	v_mfma_f32_16x16x32_bf16 v[108:111], v[128:131], v[196:199], v[108:111]
	v_mfma_f32_16x16x32_bf16 v[104:107], v[136:139], v[196:199], v[104:107]
	v_mfma_f32_16x16x32_bf16 v[92:95], v[128:131], v[204:207], v[92:95]
	v_mfma_f32_16x16x32_bf16 v[88:91], v[136:139], v[204:207], v[88:91]
	v_mfma_f32_16x16x32_bf16 v[76:79], v[128:131], v[212:215], v[76:79]
	v_mfma_f32_16x16x32_bf16 v[72:75], v[136:139], v[212:215], v[72:75]
	v_mfma_f32_16x16x32_bf16 v[124:127], v[132:135], v[180:183], v[124:127]
	v_mfma_f32_16x16x32_bf16 v[120:123], v[140:143], v[180:183], v[120:123]
	v_mfma_f32_16x16x32_bf16 v[108:111], v[132:135], v[200:203], v[108:111]
	v_mfma_f32_16x16x32_bf16 v[104:107], v[140:143], v[200:203], v[104:107]
	v_mfma_f32_16x16x32_bf16 v[92:95], v[132:135], v[208:211], v[92:95]
	v_mfma_f32_16x16x32_bf16 v[88:91], v[140:143], v[208:211], v[88:91]
	v_mfma_f32_16x16x32_bf16 v[76:79], v[132:135], v[216:219], v[76:79]
	v_mfma_f32_16x16x32_bf16 v[72:75], v[140:143], v[216:219], v[72:75]
	v_mfma_f32_16x16x32_bf16 v[116:119], v[144:147], v[176:179], v[116:119]
	v_mfma_f32_16x16x32_bf16 v[112:115], v[168:171], v[176:179], v[112:115]
	v_mfma_f32_16x16x32_bf16 v[100:103], v[144:147], v[196:199], v[100:103]
	v_mfma_f32_16x16x32_bf16 v[96:99], v[168:171], v[196:199], v[96:99]
	v_mfma_f32_16x16x32_bf16 v[84:87], v[144:147], v[204:207], v[84:87]
	v_mfma_f32_16x16x32_bf16 v[80:83], v[168:171], v[204:207], v[80:83]
	v_mfma_f32_16x16x32_bf16 v[68:71], v[144:147], v[212:215], v[68:71]
	v_mfma_f32_16x16x32_bf16 v[64:67], v[168:171], v[212:215], v[64:67]
	v_mfma_f32_16x16x32_bf16 v[116:119], v[148:151], v[180:183], v[116:119]
	v_mfma_f32_16x16x32_bf16 v[112:115], v[172:175], v[180:183], v[112:115]
	v_mfma_f32_16x16x32_bf16 v[100:103], v[148:151], v[200:203], v[100:103]
	v_mfma_f32_16x16x32_bf16 v[96:99], v[172:175], v[200:203], v[96:99]
	v_mfma_f32_16x16x32_bf16 v[84:87], v[148:151], v[208:211], v[84:87]
	v_mfma_f32_16x16x32_bf16 v[80:83], v[172:175], v[208:211], v[80:83]
	v_mfma_f32_16x16x32_bf16 v[68:71], v[148:151], v[216:219], v[68:71]
	v_mfma_f32_16x16x32_bf16 v[64:67], v[172:175], v[216:219], v[64:67]
	s_barrier
	s_add_i32 s26, s49, s38
	v_lshl_add_u64 v[184:185], s[30:31], 0, v[154:155]
	s_mov_b32 m0, s26
	ds_read_b128 v[176:179], v193 offset:16384
	ds_read_b128 v[180:183], v193 offset:17408
	ds_read_b128 v[196:199], v193 offset:18432
	ds_read_b128 v[200:203], v193 offset:19456
	ds_read_b128 v[204:207], v193 offset:20480
	ds_read_b128 v[208:211], v193 offset:21504
	ds_read_b128 v[212:215], v193 offset:22528
	ds_read_b128 v[216:219], v193 offset:23552
	global_load_lds_dwordx4 v[184:185], off
	s_add_i32 m0, s26, 0x2000
	s_add_u32 s26, s30, 0xb0000
	v_lshl_add_u64 v[220:221], s[30:31], 0, v[158:159]
	s_addc_u32 s27, s31, 0
	s_add_i32 s58, s62, s38
	global_load_lds_dwordx4 v[220:221], off
	v_lshl_add_u64 v[222:223], s[26:27], 0, v[154:155]
	s_mov_b32 m0, s58
	v_lshl_add_u64 v[224:225], s[34:35], 0, v[156:157]
	global_load_lds_dwordx4 v[222:223], off
	v_lshl_add_u64 v[222:223], s[26:27], 0, v[158:159]
	s_add_i32 m0, s58, 0x2000
	s_nop 0
	global_load_lds_dwordx4 v[222:223], off
	v_lshl_add_u64 v[222:223], s[34:35], 0, v[152:153]
	s_mov_b32 m0, s39
	s_nop 0
	global_load_lds_dwordx4 v[222:223], off
	s_mov_b32 m0, s40
	s_nop 0
	global_load_lds_dwordx4 v[224:225], off
	s_waitcnt vmcnt(8) lgkmcnt(0)
	s_barrier
; #define PG8_STAGE(bufoff, gbase, voff) do { _Pragma("unroll") for (int _i = 0; _i < 2; ++_i) \
;         __builtin_amdgcn_global_load_lds((const unsigned*)((const char*)(gbase) + (voff)[_i]), (PG8_LAS unsigned*)(lds + (bufoff) + ldsw + _i * 8192), 16, 0, 0); } while (0)
; #define PG8_LDA(dst, b, h) do { _Pragma("unroll") for (int m = 0; m < 4; ++m) _Pragma("unroll") for (int k = 0; k < 2; ++k) dst[m][k] = *(const PG8_LAS bf16x8*)(lds + PG8_SA(b, h) + aoff + m * 2048 + k * 1024); } while (0)
; #define PG8_LDB(dst, b, h) do { _Pragma("unroll") for (int n = 0; n < 2; ++n) _Pragma("unroll") for (int k = 0; k < 2; ++k) dst[n][k] = *(const PG8_LAS bf16x8*)(lds + PG8_SB(b, h) + boff + n * 2048 + k * 1024); } while (0)
; #define PG8_MMA(ai, bj, At, Bt) do { __builtin_amdgcn_s_setprio(1); _Pragma("unroll") for (int m = 0; m < 4; ++m) _Pragma("unroll") for (int n = 0; n < 2; ++n) _Pragma("unroll") for (int k = 0; k < 2; ++k) \
;         acc[ai][bj][m][n] = __builtin_amdgcn_mfma_f32_16x16x32_bf16(Bt[n][k], At[m][k], acc[ai][bj][m][n], 0, 0, 0); __builtin_amdgcn_s_setprio(0); } while (0)
; #define PG8_WAIT_V(n) asm volatile("s_waitcnt vmcnt(" #n ")" ::: "memory")
; #define PG8_WAIT_L(n) asm volatile("s_waitcnt lgkmcnt(" #n ")" ::: "memory")
; #define PG8_BAR __builtin_amdgcn_s_barrier()
; #define PG8_SCHED __builtin_amdgcn_sched_barrier(0)
; template <class Epi, class Sched, bool ALIGN_EPI = false, bool SP2 = false>
; __device__ __forceinline__ void gemm_phase(PG8_LAS unsigned char* lds, const Gemm g, const Sched& S, const Epi& E) {
;     ...
;             PG8_WAIT_V(8); PG8_WAIT_L(0); PG8_BAR; PG8_MMA(1, 0, At, B0); PG8_MMA(1, 1, At, B1); PG8_BAR; PG8_SCHED;
;             PG8_LDB(B0, 1, 0); PG8_LDB(B1, 1, 1); PG8_SCHED; PG8_LDA(At, 1, 0); PG8_STAGE(PG8_SA(0, 1), a2 + hstepA, voffA);
;             PG8_WAIT_V(8); PG8_WAIT_L(0); PG8_BAR; PG8_MMA(0, 0, At, B0); PG8_MMA(0, 1, At, B1); PG8_BAR; PG8_SCHED;
	v_mfma_f32_16x16x32_bf16 v[60:63], v[128:131], v[176:179], v[60:63]
	v_mfma_f32_16x16x32_bf16 v[56:59], v[136:139], v[176:179], v[56:59]
	v_mfma_f32_16x16x32_bf16 v[44:47], v[128:131], v[196:199], v[44:47]
	v_mfma_f32_16x16x32_bf16 v[40:43], v[136:139], v[196:199], v[40:43]
	v_mfma_f32_16x16x32_bf16 v[28:31], v[128:131], v[204:207], v[28:31]
	v_mfma_f32_16x16x32_bf16 v[24:27], v[136:139], v[204:207], v[24:27]
	v_mfma_f32_16x16x32_bf16 v[12:15], v[128:131], v[212:215], v[12:15]
	v_mfma_f32_16x16x32_bf16 v[8:11], v[136:139], v[212:215], v[8:11]
	v_mfma_f32_16x16x32_bf16 v[60:63], v[132:135], v[180:183], v[60:63]
	v_mfma_f32_16x16x32_bf16 v[56:59], v[140:143], v[180:183], v[56:59]
	v_mfma_f32_16x16x32_bf16 v[44:47], v[132:135], v[200:203], v[44:47]
	v_mfma_f32_16x16x32_bf16 v[40:43], v[140:143], v[200:203], v[40:43]
	v_mfma_f32_16x16x32_bf16 v[28:31], v[132:135], v[208:211], v[28:31]
	v_mfma_f32_16x16x32_bf16 v[24:27], v[140:143], v[208:211], v[24:27]
	v_mfma_f32_16x16x32_bf16 v[12:15], v[132:135], v[216:219], v[12:15]
	v_mfma_f32_16x16x32_bf16 v[8:11], v[140:143], v[216:219], v[8:11]
	v_mfma_f32_16x16x32_bf16 v[52:55], v[144:147], v[176:179], v[52:55]
	v_mfma_f32_16x16x32_bf16 v[48:51], v[168:171], v[176:179], v[48:51]
	v_mfma_f32_16x16x32_bf16 v[36:39], v[144:147], v[196:199], v[36:39]
	v_mfma_f32_16x16x32_bf16 v[32:35], v[168:171], v[196:199], v[32:35]
	v_mfma_f32_16x16x32_bf16 v[20:23], v[144:147], v[204:207], v[20:23]
	v_mfma_f32_16x16x32_bf16 v[16:19], v[168:171], v[204:207], v[16:19]
	v_mfma_f32_16x16x32_bf16 v[4:7], v[144:147], v[212:215], v[4:7]
	v_mfma_f32_16x16x32_bf16 v[0:3], v[168:171], v[212:215], v[0:3]
	v_mfma_f32_16x16x32_bf16 v[52:55], v[148:151], v[180:183], v[52:55]
	v_mfma_f32_16x16x32_bf16 v[48:51], v[172:175], v[180:183], v[48:51]
	v_mfma_f32_16x16x32_bf16 v[36:39], v[148:151], v[200:203], v[36:39]
	v_mfma_f32_16x16x32_bf16 v[32:35], v[172:175], v[200:203], v[32:35]
	v_mfma_f32_16x16x32_bf16 v[20:23], v[148:151], v[208:211], v[20:23]
	v_mfma_f32_16x16x32_bf16 v[16:19], v[172:175], v[208:211], v[16:19]
	v_mfma_f32_16x16x32_bf16 v[4:7], v[148:151], v[216:219], v[4:7]
	v_mfma_f32_16x16x32_bf16 v[0:3], v[172:175], v[216:219], v[0:3]
	s_barrier
	s_add_i32 s58, 0, 0x18000
	s_add_i32 s59, 0, 0x1c000
	v_add_u32_e32 v140, s58, v189
	v_add_u32_e32 v172, s59, v189
	ds_read_b128 v[128:131], v140
	ds_read_b128 v[132:135], v140 offset:1024
	ds_read_b128 v[136:139], v140 offset:2048
	ds_read_b128 v[140:143], v140 offset:3072
	ds_read_b128 v[144:147], v172
	ds_read_b128 v[148:151], v172 offset:1024
	ds_read_b128 v[168:171], v172 offset:2048
	ds_read_b128 v[172:175], v172 offset:3072
	s_add_u32 s26, s34, 0xb0000
	s_addc_u32 s27, s35, 0
	s_mov_b32 m0, s41
	v_lshl_add_u64 v[226:227], s[26:27], 0, v[152:153]
	ds_read_b128 v[176:179], v193 offset:32768
	ds_read_b128 v[180:183], v193 offset:33792
	ds_read_b128 v[196:199], v193 offset:34816
	ds_read_b128 v[200:203], v193 offset:35840
	ds_read_b128 v[204:207], v193 offset:36864
	ds_read_b128 v[208:211], v193 offset:37888
	ds_read_b128 v[212:215], v193 offset:38912
	ds_read_b128 v[216:219], v193 offset:39936
	global_load_lds_dwordx4 v[226:227], off
	v_lshl_add_u64 v[226:227], s[26:27], 0, v[156:157]
	s_mov_b32 m0, s42
	s_nop 0
	global_load_lds_dwordx4 v[226:227], off
	s_waitcnt vmcnt(8) lgkmcnt(0)
	s_barrier
	v_mfma_f32_16x16x32_bf16 v[124:127], v[128:131], v[176:179], v[124:127]
	v_mfma_f32_16x16x32_bf16 v[120:123], v[136:139], v[176:179], v[120:123]
	v_mfma_f32_16x16x32_bf16 v[108:111], v[128:131], v[196:199], v[108:111]
	v_mfma_f32_16x16x32_bf16 v[104:107], v[136:139], v[196:199], v[104:107]
	v_mfma_f32_16x16x32_bf16 v[92:95], v[128:131], v[204:207], v[92:95]
	v_mfma_f32_16x16x32_bf16 v[88:91], v[136:139], v[204:207], v[88:91]
	v_mfma_f32_16x16x32_bf16 v[76:79], v[128:131], v[212:215], v[76:79]
	v_mfma_f32_16x16x32_bf16 v[72:75], v[136:139], v[212:215], v[72:75]
	v_mfma_f32_16x16x32_bf16 v[124:127], v[132:135], v[180:183], v[124:127]
	v_mfma_f32_16x16x32_bf16 v[120:123], v[140:143], v[180:183], v[120:123]
	v_mfma_f32_16x16x32_bf16 v[108:111], v[132:135], v[200:203], v[108:111]
	v_mfma_f32_16x16x32_bf16 v[104:107], v[140:143], v[200:203], v[104:107]
	v_mfma_f32_16x16x32_bf16 v[92:95], v[132:135], v[208:211], v[92:95]
	v_mfma_f32_16x16x32_bf16 v[88:91], v[140:143], v[208:211], v[88:91]
	v_mfma_f32_16x16x32_bf16 v[76:79], v[132:135], v[216:219], v[76:79]
	v_mfma_f32_16x16x32_bf16 v[72:75], v[140:143], v[216:219], v[72:75]
	v_mfma_f32_16x16x32_bf16 v[116:119], v[144:147], v[176:179], v[116:119]
	v_mfma_f32_16x16x32_bf16 v[112:115], v[168:171], v[176:179], v[112:115]
	v_mfma_f32_16x16x32_bf16 v[100:103], v[144:147], v[196:199], v[100:103]
	v_mfma_f32_16x16x32_bf16 v[96:99], v[168:171], v[196:199], v[96:99]
	v_mfma_f32_16x16x32_bf16 v[84:87], v[144:147], v[204:207], v[84:87]
	v_mfma_f32_16x16x32_bf16 v[80:83], v[168:171], v[204:207], v[80:83]
	v_mfma_f32_16x16x32_bf16 v[68:71], v[144:147], v[212:215], v[68:71]
	v_mfma_f32_16x16x32_bf16 v[64:67], v[168:171], v[212:215], v[64:67]
	v_mfma_f32_16x16x32_bf16 v[116:119], v[148:151], v[180:183], v[116:119]
	v_mfma_f32_16x16x32_bf16 v[112:115], v[172:175], v[180:183], v[112:115]
	v_mfma_f32_16x16x32_bf16 v[100:103], v[148:151], v[200:203], v[100:103]
	v_mfma_f32_16x16x32_bf16 v[96:99], v[172:175], v[200:203], v[96:99]
	v_mfma_f32_16x16x32_bf16 v[84:87], v[148:151], v[208:211], v[84:87]
	v_mfma_f32_16x16x32_bf16 v[80:83], v[172:175], v[208:211], v[80:83]
	v_mfma_f32_16x16x32_bf16 v[68:71], v[148:151], v[216:219], v[68:71]
	v_mfma_f32_16x16x32_bf16 v[64:67], v[172:175], v[216:219], v[64:67]
	s_barrier
; #define PG8_STAGE(bufoff, gbase, voff) do { _Pragma("unroll") for (int _i = 0; _i < 2; ++_i) \
;         __builtin_amdgcn_global_load_lds((const unsigned*)((const char*)(gbase) + (voff)[_i]), (PG8_LAS unsigned*)(lds + (bufoff) + ldsw + _i * 8192), 16, 0, 0); } while (0)
; #define PG8_LDA(dst, b, h) do { _Pragma("unroll") for (int m = 0; m < 4; ++m) _Pragma("unroll") for (int k = 0; k < 2; ++k) dst[m][k] = *(const PG8_LAS bf16x8*)(lds + PG8_SA(b, h) + aoff + m * 2048 + k * 1024); } while (0)
; #define PG8_MMA(ai, bj, At, Bt) do { __builtin_amdgcn_s_setprio(1); _Pragma("unroll") for (int m = 0; m < 4; ++m) _Pragma("unroll") for (int n = 0; n < 2; ++n) _Pragma("unroll") for (int k = 0; k < 2; ++k) \
;         acc[ai][bj][m][n] = __builtin_amdgcn_mfma_f32_16x16x32_bf16(Bt[n][k], At[m][k], acc[ai][bj][m][n], 0, 0, 0); __builtin_amdgcn_s_setprio(0); } while (0)
; #define PG8_WAIT_V(n) asm volatile("s_waitcnt vmcnt(" #n ")" ::: "memory")
; #define PG8_WAIT_L(n) asm volatile("s_waitcnt lgkmcnt(" #n ")" ::: "memory")
; #define PG8_BAR __builtin_amdgcn_s_barrier()
; #define PG8_SCHED __builtin_amdgcn_sched_barrier(0)
; template <class Epi, class Sched, bool ALIGN_EPI = false, bool SP2 = false>
; __device__ __forceinline__ void gemm_phase(PG8_LAS unsigned char* lds, const Gemm g, const Sched& S, const Epi& E) {
;     ...
;             PG8_LDA(At, 1, 1); PG8_STAGE(PG8_SB(1, 0), b3, voffB); PG8_STAGE(PG8_SB(1, 1), b3 + hstepB, voffB); PG8_STAGE(PG8_SA(1, 0), a3, voffA);
;             PG8_WAIT_V(8); PG8_WAIT_L(0); PG8_BAR; PG8_MMA(1, 0, At, B0); PG8_MMA(1, 1, At, B1); PG8_BAR; PG8_SCHED;
;     ...
;         if constexpr (ALIGN_EPI) { if (wr == 0) PG8_BAR; }
	s_add_i32 s26, s58, s38
	v_lshl_add_u64 v[184:185], v[184:185], 0, s[14:15]
	s_mov_b32 m0, s26
	ds_read_b128 v[176:179], v193 offset:49152
	ds_read_b128 v[180:183], v193 offset:50176
	ds_read_b128 v[196:199], v193 offset:51200
	ds_read_b128 v[200:203], v193 offset:52224
	ds_read_b128 v[204:207], v193 offset:53248
	ds_read_b128 v[208:211], v193 offset:54272
	ds_read_b128 v[212:215], v193 offset:55296
	ds_read_b128 v[216:219], v193 offset:56320
	global_load_lds_dwordx4 v[184:185], off
	s_add_i32 m0, s26, 0x2000
	s_add_u32 s26, s30, 0xb0080
	v_lshl_add_u64 v[184:185], v[220:221], 0, s[14:15]
	s_addc_u32 s27, s31, 0
	s_add_i32 s30, s59, s38
	global_load_lds_dwordx4 v[184:185], off
	v_lshl_add_u64 v[184:185], s[26:27], 0, v[154:155]
	s_mov_b32 m0, s30
	s_nop 0
	global_load_lds_dwordx4 v[184:185], off
	v_lshl_add_u64 v[184:185], s[26:27], 0, v[158:159]
	s_add_i32 m0, s30, 0x2000
	s_nop 0
	global_load_lds_dwordx4 v[184:185], off
	v_lshl_add_u64 v[184:185], v[222:223], 0, s[14:15]
	s_mov_b32 m0, s44
	s_nop 0
	global_load_lds_dwordx4 v[184:185], off
	v_lshl_add_u64 v[184:185], v[224:225], 0, s[14:15]
	s_mov_b32 m0, s45
	s_nop 0
	global_load_lds_dwordx4 v[184:185], off
	s_waitcnt vmcnt(8) lgkmcnt(0)
	s_barrier
	v_mfma_f32_16x16x32_bf16 v[60:63], v[128:131], v[176:179], v[60:63]
	v_mfma_f32_16x16x32_bf16 v[56:59], v[136:139], v[176:179], v[56:59]
	v_mfma_f32_16x16x32_bf16 v[44:47], v[128:131], v[196:199], v[44:47]
	v_mfma_f32_16x16x32_bf16 v[40:43], v[136:139], v[196:199], v[40:43]
	v_mfma_f32_16x16x32_bf16 v[28:31], v[128:131], v[204:207], v[28:31]
	v_mfma_f32_16x16x32_bf16 v[24:27], v[136:139], v[204:207], v[24:27]
	v_mfma_f32_16x16x32_bf16 v[12:15], v[128:131], v[212:215], v[12:15]
	v_mfma_f32_16x16x32_bf16 v[8:11], v[136:139], v[212:215], v[8:11]
	v_mfma_f32_16x16x32_bf16 v[60:63], v[132:135], v[180:183], v[60:63]
	v_mfma_f32_16x16x32_bf16 v[56:59], v[140:143], v[180:183], v[56:59]
	v_mfma_f32_16x16x32_bf16 v[44:47], v[132:135], v[200:203], v[44:47]
	v_mfma_f32_16x16x32_bf16 v[40:43], v[140:143], v[200:203], v[40:43]
	v_mfma_f32_16x16x32_bf16 v[28:31], v[132:135], v[208:211], v[28:31]
	v_mfma_f32_16x16x32_bf16 v[24:27], v[140:143], v[208:211], v[24:27]
	v_mfma_f32_16x16x32_bf16 v[12:15], v[132:135], v[216:219], v[12:15]
	v_mfma_f32_16x16x32_bf16 v[8:11], v[140:143], v[216:219], v[8:11]
	v_mfma_f32_16x16x32_bf16 v[52:55], v[144:147], v[176:179], v[52:55]
	v_mfma_f32_16x16x32_bf16 v[48:51], v[168:171], v[176:179], v[48:51]
	v_mfma_f32_16x16x32_bf16 v[36:39], v[144:147], v[196:199], v[36:39]
	v_mfma_f32_16x16x32_bf16 v[32:35], v[168:171], v[196:199], v[32:35]
	v_mfma_f32_16x16x32_bf16 v[20:23], v[144:147], v[204:207], v[20:23]
	v_mfma_f32_16x16x32_bf16 v[16:19], v[168:171], v[204:207], v[16:19]
	v_mfma_f32_16x16x32_bf16 v[4:7], v[144:147], v[212:215], v[4:7]
	v_mfma_f32_16x16x32_bf16 v[0:3], v[168:171], v[212:215], v[0:3]
	v_mfma_f32_16x16x32_bf16 v[52:55], v[148:151], v[180:183], v[52:55]
	v_mfma_f32_16x16x32_bf16 v[48:51], v[172:175], v[180:183], v[48:51]
	v_mfma_f32_16x16x32_bf16 v[36:39], v[148:151], v[200:203], v[36:39]
	v_mfma_f32_16x16x32_bf16 v[32:35], v[172:175], v[200:203], v[32:35]
	v_mfma_f32_16x16x32_bf16 v[20:23], v[148:151], v[208:211], v[20:23]
	v_mfma_f32_16x16x32_bf16 v[16:19], v[172:175], v[208:211], v[16:19]
	v_mfma_f32_16x16x32_bf16 v[4:7], v[148:151], v[216:219], v[4:7]
	v_mfma_f32_16x16x32_bf16 v[0:3], v[172:175], v[216:219], v[0:3]
	s_barrier
	s_add_i32 s72, s72, 2
	s_add_u32 s70, s70, 0x100
	s_addc_u32 s71, s71, 0
	s_cmp_gt_u32 s72, 41
	s_mov_b64 s[26:27], s[28:29]
	s_cbranch_scc0 .LBB0_318
	s_and_b64 vcc, exec, s[20:21]
	s_cbranch_vccz .LBB0_321
	s_barrier

; #define PG8_STAGE(bufoff, gbase, voff) do { _Pragma("unroll") for (int _i = 0; _i < 2; ++_i) \
;         __builtin_amdgcn_global_load_lds((const unsigned*)((const char*)(gbase) + (voff)[_i]), (PG8_LAS unsigned*)(lds + (bufoff) + ldsw + _i * 8192), 16, 0, 0); } while (0)
; #define PG8_LDA(dst, b, h) do { _Pragma("unroll") for (int m = 0; m < 4; ++m) _Pragma("unroll") for (int k = 0; k < 2; ++k) dst[m][k] = *(const PG8_LAS bf16x8*)(lds + PG8_SA(b, h) + aoff + m * 2048 + k * 1024); } while (0)
; #define PG8_LDB(dst, b, h) do { _Pragma("unroll") for (int n = 0; n < 2; ++n) _Pragma("unroll") for (int k = 0; k < 2; ++k) dst[n][k] = *(const PG8_LAS bf16x8*)(lds + PG8_SB(b, h) + boff + n * 2048 + k * 1024); } while (0)
; #define PG8_MMA(ai, bj, At, Bt) do { __builtin_amdgcn_s_setprio(1); _Pragma("unroll") for (int m = 0; m < 4; ++m) _Pragma("unroll") for (int n = 0; n < 2; ++n) _Pragma("unroll") for (int k = 0; k < 2; ++k) \
;         acc[ai][bj][m][n] = __builtin_amdgcn_mfma_f32_16x16x32_bf16(Bt[n][k], At[m][k], acc[ai][bj][m][n], 0, 0, 0); __builtin_amdgcn_s_setprio(0); } while (0)
; #define PG8_WAIT_V(n) asm volatile("s_waitcnt vmcnt(" #n ")" ::: "memory")
; #define PG8_WAIT_L(n) asm volatile("s_waitcnt lgkmcnt(" #n ")" ::: "memory")
; #define PG8_BAR __builtin_amdgcn_s_barrier()
; #define PG8_SCHED __builtin_amdgcn_sched_barrier(0)
; template <class Epi, class Sched, bool ALIGN_EPI = false, bool SP2 = false>
; __device__ __forceinline__ void gemm_phase(PG8_LAS unsigned char* lds, const Gemm g, const Sched& S, const Epi& E) {
;     ...
;             if constexpr (SP2) {
;             PG8_LDB(B0, 0, 0); PG8_LDB(B1, 0, 1); PG8_SCHED; PG8_LDA(At, 0, 0); PG8_STAGE(PG8_SA(1, 1), a1 + hstepA, voffA);
;             PG8_WAIT_V(8); PG8_WAIT_L(0); PG8_BAR; PG8_MMA(0, 0, At, B0); PG8_MMA(0, 1, At, B1); PG8_BAR; PG8_SCHED;
;             PG8_LDA(At, 0, 1); PG8_STAGE(PG8_SB(0, 0), b2, voffB); PG8_STAGE(PG8_SB(0, 1), b2 + hstepB, voffB); PG8_STAGE(PG8_SA(0, 0), a2, voffA);
;             PG8_WAIT_V(8); PG8_WAIT_L(0); PG8_BAR; PG8_MMA(1, 0, At, B0); PG8_MMA(1, 1, At, B1); PG8_BAR; PG8_SCHED;
.LBB0_404:
	ds_read_b128 v[152:155], v165
	ds_read_b128 v[156:159], v165 offset:1024
	ds_read_b128 v[178:181], v165 offset:2048
	ds_read_b128 v[182:185], v165 offset:3072
	ds_read_b128 v[188:191], v166
	ds_read_b128 v[192:195], v166 offset:1024
	ds_read_b128 v[196:199], v166 offset:2048
	ds_read_b128 v[200:203], v166 offset:3072
	s_add_u32 s46, s14, 0xfffc0080
	s_addc_u32 s47, s15, -1
	s_cmp_eq_u32 s91, 12
	s_cselect_b32 s49, s11, s47
	s_cselect_b32 s48, s13, s46
	s_cselect_b32 s47, s39, s67
	s_cselect_b32 s46, s41, s66
	v_lshl_add_u64 v[160:161], s[14:15], 0, v[144:145]
	s_add_i32 m0, s71, 0xc000
	ds_read_b128 v[204:207], v167
	ds_read_b128 v[208:211], v167 offset:1024
	ds_read_b128 v[212:215], v167 offset:2048
	ds_read_b128 v[216:219], v167 offset:3072
	ds_read_b128 v[220:223], v167 offset:4096
	ds_read_b128 v[224:227], v167 offset:5120
	ds_read_b128 v[228:231], v167 offset:6144
	ds_read_b128 v[232:235], v167 offset:7168
	global_load_lds_dwordx4 v[160:161], off
	v_lshl_add_u64 v[160:161], s[14:15], 0, v[146:147]
	s_add_i32 m0, s71, 0xe000
	s_nop 0
	global_load_lds_dwordx4 v[160:161], off
	s_waitcnt vmcnt(8) lgkmcnt(0)
	s_barrier
	v_mfma_f32_16x16x32_bf16 v[124:127], v[152:155], v[204:207], v[124:127]
	v_mfma_f32_16x16x32_bf16 v[120:123], v[178:181], v[204:207], v[120:123]
	v_mfma_f32_16x16x32_bf16 v[108:111], v[152:155], v[212:215], v[108:111]
	v_mfma_f32_16x16x32_bf16 v[104:107], v[178:181], v[212:215], v[104:107]
	v_mfma_f32_16x16x32_bf16 v[92:95], v[152:155], v[220:223], v[92:95]
	v_mfma_f32_16x16x32_bf16 v[88:91], v[178:181], v[220:223], v[88:91]
	v_mfma_f32_16x16x32_bf16 v[76:79], v[152:155], v[228:231], v[76:79]
	v_mfma_f32_16x16x32_bf16 v[72:75], v[178:181], v[228:231], v[72:75]
	v_mfma_f32_16x16x32_bf16 v[124:127], v[156:159], v[208:211], v[124:127]
	v_mfma_f32_16x16x32_bf16 v[120:123], v[182:185], v[208:211], v[120:123]
	v_mfma_f32_16x16x32_bf16 v[108:111], v[156:159], v[216:219], v[108:111]
	v_mfma_f32_16x16x32_bf16 v[104:107], v[182:185], v[216:219], v[104:107]
	v_mfma_f32_16x16x32_bf16 v[92:95], v[156:159], v[224:227], v[92:95]
	v_mfma_f32_16x16x32_bf16 v[88:91], v[182:185], v[224:227], v[88:91]
	v_mfma_f32_16x16x32_bf16 v[76:79], v[156:159], v[232:235], v[76:79]
	v_mfma_f32_16x16x32_bf16 v[72:75], v[182:185], v[232:235], v[72:75]
	v_mfma_f32_16x16x32_bf16 v[116:119], v[188:191], v[204:207], v[116:119]
	v_mfma_f32_16x16x32_bf16 v[112:115], v[196:199], v[204:207], v[112:115]
	v_mfma_f32_16x16x32_bf16 v[100:103], v[188:191], v[212:215], v[100:103]
	v_mfma_f32_16x16x32_bf16 v[96:99], v[196:199], v[212:215], v[96:99]
	v_mfma_f32_16x16x32_bf16 v[84:87], v[188:191], v[220:223], v[84:87]
	v_mfma_f32_16x16x32_bf16 v[80:83], v[196:199], v[220:223], v[80:83]
	v_mfma_f32_16x16x32_bf16 v[68:71], v[188:191], v[228:231], v[68:71]
	v_mfma_f32_16x16x32_bf16 v[64:67], v[196:199], v[228:231], v[64:67]
	v_mfma_f32_16x16x32_bf16 v[116:119], v[192:195], v[208:211], v[116:119]
	v_mfma_f32_16x16x32_bf16 v[112:115], v[200:203], v[208:211], v[112:115]
	v_mfma_f32_16x16x32_bf16 v[100:103], v[192:195], v[216:219], v[100:103]
	v_mfma_f32_16x16x32_bf16 v[96:99], v[200:203], v[216:219], v[96:99]
	v_mfma_f32_16x16x32_bf16 v[84:87], v[192:195], v[224:227], v[84:87]
	v_mfma_f32_16x16x32_bf16 v[80:83], v[200:203], v[224:227], v[80:83]
	v_mfma_f32_16x16x32_bf16 v[68:71], v[192:195], v[232:235], v[68:71]
	v_mfma_f32_16x16x32_bf16 v[64:67], v[200:203], v[232:235], v[64:67]
	s_barrier
	s_add_i32 s58, s83, s70
	v_lshl_add_u64 v[160:161], s[46:47], 0, v[130:131]
	s_mov_b32 m0, s58
	ds_read_b128 v[204:207], v167 offset:16384
	ds_read_b128 v[208:211], v167 offset:17408
	ds_read_b128 v[212:215], v167 offset:18432
	ds_read_b128 v[216:219], v167 offset:19456
	ds_read_b128 v[220:223], v167 offset:20480
	ds_read_b128 v[224:227], v167 offset:21504
	ds_read_b128 v[228:231], v167 offset:22528
	ds_read_b128 v[232:235], v167 offset:23552
	global_load_lds_dwordx4 v[160:161], off
	s_add_i32 m0, s58, 0x2000
	s_add_u32 s58, s46, 0x40000
	v_lshl_add_u64 v[236:237], s[46:47], 0, v[134:135]
	s_addc_u32 s59, s47, 0
	s_add_i32 s92, s84, s70
	global_load_lds_dwordx4 v[236:237], off
	v_lshl_add_u64 v[238:239], s[58:59], 0, v[130:131]
	s_mov_b32 m0, s92
	v_lshl_add_u64 v[240:241], s[48:49], 0, v[132:133]
	global_load_lds_dwordx4 v[238:239], off
	v_lshl_add_u64 v[238:239], s[58:59], 0, v[134:135]
	s_add_i32 m0, s92, 0x2000
	s_nop 0
	global_load_lds_dwordx4 v[238:239], off
	v_lshl_add_u64 v[238:239], s[48:49], 0, v[128:129]
	s_mov_b32 m0, s71
	s_nop 0
	global_load_lds_dwordx4 v[238:239], off
	s_mov_b32 m0, s72
	s_nop 0
	global_load_lds_dwordx4 v[240:241], off
	s_waitcnt vmcnt(8) lgkmcnt(0)
	s_barrier
; #define PG8_STAGE(bufoff, gbase, voff) do { _Pragma("unroll") for (int _i = 0; _i < 2; ++_i) \
;         __builtin_amdgcn_global_load_lds((const unsigned*)((const char*)(gbase) + (voff)[_i]), (PG8_LAS unsigned*)(lds + (bufoff) + ldsw + _i * 8192), 16, 0, 0); } while (0)
; #define PG8_LDA(dst, b, h) do { _Pragma("unroll") for (int m = 0; m < 4; ++m) _Pragma("unroll") for (int k = 0; k < 2; ++k) dst[m][k] = *(const PG8_LAS bf16x8*)(lds + PG8_SA(b, h) + aoff + m * 2048 + k * 1024); } while (0)
; #define PG8_LDB(dst, b, h) do { _Pragma("unroll") for (int n = 0; n < 2; ++n) _Pragma("unroll") for (int k = 0; k < 2; ++k) dst[n][k] = *(const PG8_LAS bf16x8*)(lds + PG8_SB(b, h) + boff + n * 2048 + k * 1024); } while (0)
; #define PG8_MMA(ai, bj, At, Bt) do { __builtin_amdgcn_s_setprio(1); _Pragma("unroll") for (int m = 0; m < 4; ++m) _Pragma("unroll") for (int n = 0; n < 2; ++n) _Pragma("unroll") for (int k = 0; k < 2; ++k) \
;         acc[ai][bj][m][n] = __builtin_amdgcn_mfma_f32_16x16x32_bf16(Bt[n][k], At[m][k], acc[ai][bj][m][n], 0, 0, 0); __builtin_amdgcn_s_setprio(0); } while (0)
; #define PG8_WAIT_V(n) asm volatile("s_waitcnt vmcnt(" #n ")" ::: "memory")
; #define PG8_WAIT_L(n) asm volatile("s_waitcnt lgkmcnt(" #n ")" ::: "memory")
; #define PG8_BAR __builtin_amdgcn_s_barrier()
; #define PG8_SCHED __builtin_amdgcn_sched_barrier(0)
; template <class Epi, class Sched, bool ALIGN_EPI = false, bool SP2 = false>
; __device__ __forceinline__ void gemm_phase(PG8_LAS unsigned char* lds, const Gemm g, const Sched& S, const Epi& E) {
;     ...
;             PG8_WAIT_V(8); PG8_WAIT_L(0); PG8_BAR; PG8_MMA(1, 0, At, B0); PG8_MMA(1, 1, At, B1); PG8_BAR; PG8_SCHED;
;             PG8_LDB(B0, 1, 0); PG8_LDB(B1, 1, 1); PG8_SCHED; PG8_LDA(At, 1, 0); PG8_STAGE(PG8_SA(0, 1), a2 + hstepA, voffA);
;             PG8_WAIT_V(8); PG8_WAIT_L(0); PG8_BAR; PG8_MMA(0, 0, At, B0); PG8_MMA(0, 1, At, B1); PG8_BAR; PG8_SCHED;
	v_mfma_f32_16x16x32_bf16 v[60:63], v[152:155], v[204:207], v[60:63]
	v_mfma_f32_16x16x32_bf16 v[56:59], v[178:181], v[204:207], v[56:59]
	v_mfma_f32_16x16x32_bf16 v[44:47], v[152:155], v[212:215], v[44:47]
	v_mfma_f32_16x16x32_bf16 v[40:43], v[178:181], v[212:215], v[40:43]
	v_mfma_f32_16x16x32_bf16 v[28:31], v[152:155], v[220:223], v[28:31]
	v_mfma_f32_16x16x32_bf16 v[24:27], v[178:181], v[220:223], v[24:27]
	v_mfma_f32_16x16x32_bf16 v[12:15], v[152:155], v[228:231], v[12:15]
	v_mfma_f32_16x16x32_bf16 v[8:11], v[178:181], v[228:231], v[8:11]
	v_mfma_f32_16x16x32_bf16 v[60:63], v[156:159], v[208:211], v[60:63]
	v_mfma_f32_16x16x32_bf16 v[56:59], v[182:185], v[208:211], v[56:59]
	v_mfma_f32_16x16x32_bf16 v[44:47], v[156:159], v[216:219], v[44:47]
	v_mfma_f32_16x16x32_bf16 v[40:43], v[182:185], v[216:219], v[40:43]
	v_mfma_f32_16x16x32_bf16 v[28:31], v[156:159], v[224:227], v[28:31]
	v_mfma_f32_16x16x32_bf16 v[24:27], v[182:185], v[224:227], v[24:27]
	v_mfma_f32_16x16x32_bf16 v[12:15], v[156:159], v[232:235], v[12:15]
	v_mfma_f32_16x16x32_bf16 v[8:11], v[182:185], v[232:235], v[8:11]
	v_mfma_f32_16x16x32_bf16 v[52:55], v[188:191], v[204:207], v[52:55]
	v_mfma_f32_16x16x32_bf16 v[48:51], v[196:199], v[204:207], v[48:51]
	v_mfma_f32_16x16x32_bf16 v[36:39], v[188:191], v[212:215], v[36:39]
	v_mfma_f32_16x16x32_bf16 v[32:35], v[196:199], v[212:215], v[32:35]
	v_mfma_f32_16x16x32_bf16 v[20:23], v[188:191], v[220:223], v[20:23]
	v_mfma_f32_16x16x32_bf16 v[16:19], v[196:199], v[220:223], v[16:19]
	v_mfma_f32_16x16x32_bf16 v[4:7], v[188:191], v[228:231], v[4:7]
	v_mfma_f32_16x16x32_bf16 v[0:3], v[196:199], v[228:231], v[0:3]
	v_mfma_f32_16x16x32_bf16 v[52:55], v[192:195], v[208:211], v[52:55]
	v_mfma_f32_16x16x32_bf16 v[48:51], v[200:203], v[208:211], v[48:51]
	v_mfma_f32_16x16x32_bf16 v[36:39], v[192:195], v[216:219], v[36:39]
	v_mfma_f32_16x16x32_bf16 v[32:35], v[200:203], v[216:219], v[32:35]
	v_mfma_f32_16x16x32_bf16 v[20:23], v[192:195], v[224:227], v[20:23]
	v_mfma_f32_16x16x32_bf16 v[16:19], v[200:203], v[224:227], v[16:19]
	v_mfma_f32_16x16x32_bf16 v[4:7], v[192:195], v[232:235], v[4:7]
	v_mfma_f32_16x16x32_bf16 v[0:3], v[200:203], v[232:235], v[0:3]
	s_barrier
	s_add_i32 s58, 0, 0x18000
	v_add_u32_e32 v136, s58, v163
	s_add_i32 s59, 0, 0x1c000
	ds_read_b128 v[152:155], v136
	ds_read_b128 v[156:159], v136 offset:1024
	ds_read_b128 v[178:181], v136 offset:2048
	ds_read_b128 v[182:185], v136 offset:3072
	v_add_u32_e32 v136, s59, v163
	ds_read_b128 v[188:191], v136
	ds_read_b128 v[192:195], v136 offset:1024
	ds_read_b128 v[196:199], v136 offset:2048
	ds_read_b128 v[200:203], v136 offset:3072
	s_add_u32 s48, s48, 0x40000
	s_addc_u32 s49, s49, 0
	s_mov_b32 m0, s73
	v_lshl_add_u64 v[242:243], s[48:49], 0, v[128:129]
	ds_read_b128 v[204:207], v167 offset:32768
	ds_read_b128 v[208:211], v167 offset:33792
	ds_read_b128 v[212:215], v167 offset:34816
	ds_read_b128 v[216:219], v167 offset:35840
	ds_read_b128 v[220:223], v167 offset:36864
	ds_read_b128 v[224:227], v167 offset:37888
	ds_read_b128 v[228:231], v167 offset:38912
	ds_read_b128 v[232:235], v167 offset:39936
	global_load_lds_dwordx4 v[242:243], off
	v_lshl_add_u64 v[242:243], s[48:49], 0, v[132:133]
	s_mov_b32 m0, s74
	s_nop 0
	global_load_lds_dwordx4 v[242:243], off
	s_waitcnt vmcnt(8) lgkmcnt(0)
	s_barrier
	v_mfma_f32_16x16x32_bf16 v[124:127], v[152:155], v[204:207], v[124:127]
	v_mfma_f32_16x16x32_bf16 v[120:123], v[178:181], v[204:207], v[120:123]
	v_mfma_f32_16x16x32_bf16 v[108:111], v[152:155], v[212:215], v[108:111]
	v_mfma_f32_16x16x32_bf16 v[104:107], v[178:181], v[212:215], v[104:107]
	v_mfma_f32_16x16x32_bf16 v[92:95], v[152:155], v[220:223], v[92:95]
	v_mfma_f32_16x16x32_bf16 v[88:91], v[178:181], v[220:223], v[88:91]
	v_mfma_f32_16x16x32_bf16 v[76:79], v[152:155], v[228:231], v[76:79]
	v_mfma_f32_16x16x32_bf16 v[72:75], v[178:181], v[228:231], v[72:75]
	v_mfma_f32_16x16x32_bf16 v[124:127], v[156:159], v[208:211], v[124:127]
	v_mfma_f32_16x16x32_bf16 v[120:123], v[182:185], v[208:211], v[120:123]
	v_mfma_f32_16x16x32_bf16 v[108:111], v[156:159], v[216:219], v[108:111]
	v_mfma_f32_16x16x32_bf16 v[104:107], v[182:185], v[216:219], v[104:107]
	v_mfma_f32_16x16x32_bf16 v[92:95], v[156:159], v[224:227], v[92:95]
	v_mfma_f32_16x16x32_bf16 v[88:91], v[182:185], v[224:227], v[88:91]
	v_mfma_f32_16x16x32_bf16 v[76:79], v[156:159], v[232:235], v[76:79]
	v_mfma_f32_16x16x32_bf16 v[72:75], v[182:185], v[232:235], v[72:75]
	v_mfma_f32_16x16x32_bf16 v[116:119], v[188:191], v[204:207], v[116:119]
	v_mfma_f32_16x16x32_bf16 v[112:115], v[196:199], v[204:207], v[112:115]
	v_mfma_f32_16x16x32_bf16 v[100:103], v[188:191], v[212:215], v[100:103]
	v_mfma_f32_16x16x32_bf16 v[96:99], v[196:199], v[212:215], v[96:99]
	v_mfma_f32_16x16x32_bf16 v[84:87], v[188:191], v[220:223], v[84:87]
	v_mfma_f32_16x16x32_bf16 v[80:83], v[196:199], v[220:223], v[80:83]
	v_mfma_f32_16x16x32_bf16 v[68:71], v[188:191], v[228:231], v[68:71]
	v_mfma_f32_16x16x32_bf16 v[64:67], v[196:199], v[228:231], v[64:67]
	v_mfma_f32_16x16x32_bf16 v[116:119], v[192:195], v[208:211], v[116:119]
	v_mfma_f32_16x16x32_bf16 v[112:115], v[200:203], v[208:211], v[112:115]
	v_mfma_f32_16x16x32_bf16 v[100:103], v[192:195], v[216:219], v[100:103]
	v_mfma_f32_16x16x32_bf16 v[96:99], v[200:203], v[216:219], v[96:99]
	v_mfma_f32_16x16x32_bf16 v[84:87], v[192:195], v[224:227], v[84:87]
	v_mfma_f32_16x16x32_bf16 v[80:83], v[200:203], v[224:227], v[80:83]
	v_mfma_f32_16x16x32_bf16 v[68:71], v[192:195], v[232:235], v[68:71]
	v_mfma_f32_16x16x32_bf16 v[64:67], v[200:203], v[232:235], v[64:67]
	s_barrier
; #define PG8_STAGE(bufoff, gbase, voff) do { _Pragma("unroll") for (int _i = 0; _i < 2; ++_i) \
;         __builtin_amdgcn_global_load_lds((const unsigned*)((const char*)(gbase) + (voff)[_i]), (PG8_LAS unsigned*)(lds + (bufoff) + ldsw + _i * 8192), 16, 0, 0); } while (0)
; #define PG8_LDA(dst, b, h) do { _Pragma("unroll") for (int m = 0; m < 4; ++m) _Pragma("unroll") for (int k = 0; k < 2; ++k) dst[m][k] = *(const PG8_LAS bf16x8*)(lds + PG8_SA(b, h) + aoff + m * 2048 + k * 1024); } while (0)
; #define PG8_MMA(ai, bj, At, Bt) do { __builtin_amdgcn_s_setprio(1); _Pragma("unroll") for (int m = 0; m < 4; ++m) _Pragma("unroll") for (int n = 0; n < 2; ++n) _Pragma("unroll") for (int k = 0; k < 2; ++k) \
;         acc[ai][bj][m][n] = __builtin_amdgcn_mfma_f32_16x16x32_bf16(Bt[n][k], At[m][k], acc[ai][bj][m][n], 0, 0, 0); __builtin_amdgcn_s_setprio(0); } while (0)
; #define PG8_WAIT_V(n) asm volatile("s_waitcnt vmcnt(" #n ")" ::: "memory")
; #define PG8_WAIT_L(n) asm volatile("s_waitcnt lgkmcnt(" #n ")" ::: "memory")
; #define PG8_BAR __builtin_amdgcn_s_barrier()
; #define PG8_SCHED __builtin_amdgcn_sched_barrier(0)
; template <class Epi, class Sched, bool ALIGN_EPI = false, bool SP2 = false>
; __device__ __forceinline__ void gemm_phase(PG8_LAS unsigned char* lds, const Gemm g, const Sched& S, const Epi& E) {
;     ...
;             PG8_LDA(At, 1, 1); PG8_STAGE(PG8_SB(1, 0), b3, voffB); PG8_STAGE(PG8_SB(1, 1), b3 + hstepB, voffB); PG8_STAGE(PG8_SA(1, 0), a3, voffA);
;             PG8_WAIT_V(8); PG8_WAIT_L(0); PG8_BAR; PG8_MMA(1, 0, At, B0); PG8_MMA(1, 1, At, B1); PG8_BAR; PG8_SCHED;
;     ...
;         if constexpr (ALIGN_EPI) { if (wr == 0) PG8_BAR; }
	s_add_i32 s48, s58, s70
	v_lshl_add_u64 v[160:161], v[160:161], 0, s[30:31]
	s_mov_b32 m0, s48
	ds_read_b128 v[204:207], v167 offset:49152
	ds_read_b128 v[208:211], v167 offset:50176
	ds_read_b128 v[212:215], v167 offset:51200
	ds_read_b128 v[216:219], v167 offset:52224
	ds_read_b128 v[220:223], v167 offset:53248
	ds_read_b128 v[224:227], v167 offset:54272
	ds_read_b128 v[228:231], v167 offset:55296
	ds_read_b128 v[232:235], v167 offset:56320
	global_load_lds_dwordx4 v[160:161], off
	s_add_i32 m0, s48, 0x2000
	s_add_u32 s46, s46, 0x40080
	v_lshl_add_u64 v[160:161], v[236:237], 0, s[30:31]
	s_addc_u32 s47, s47, 0
	s_add_i32 s48, s59, s70
	global_load_lds_dwordx4 v[160:161], off
	v_lshl_add_u64 v[160:161], s[46:47], 0, v[130:131]
	s_mov_b32 m0, s48
	s_nop 0
	global_load_lds_dwordx4 v[160:161], off
	v_lshl_add_u64 v[160:161], s[46:47], 0, v[134:135]
	s_add_i32 m0, s48, 0x2000
	s_nop 0
	global_load_lds_dwordx4 v[160:161], off
	v_lshl_add_u64 v[160:161], v[238:239], 0, s[30:31]
	s_mov_b32 m0, s76
	s_nop 0
	global_load_lds_dwordx4 v[160:161], off
	v_lshl_add_u64 v[160:161], v[240:241], 0, s[30:31]
	s_mov_b32 m0, s77
	s_nop 0
	global_load_lds_dwordx4 v[160:161], off
	s_waitcnt vmcnt(8) lgkmcnt(0)
	s_barrier
	v_mfma_f32_16x16x32_bf16 v[60:63], v[152:155], v[204:207], v[60:63]
	v_mfma_f32_16x16x32_bf16 v[56:59], v[178:181], v[204:207], v[56:59]
	v_mfma_f32_16x16x32_bf16 v[44:47], v[152:155], v[212:215], v[44:47]
	v_mfma_f32_16x16x32_bf16 v[40:43], v[178:181], v[212:215], v[40:43]
	v_mfma_f32_16x16x32_bf16 v[28:31], v[152:155], v[220:223], v[28:31]
	v_mfma_f32_16x16x32_bf16 v[24:27], v[178:181], v[220:223], v[24:27]
	v_mfma_f32_16x16x32_bf16 v[12:15], v[152:155], v[228:231], v[12:15]
	v_mfma_f32_16x16x32_bf16 v[8:11], v[178:181], v[228:231], v[8:11]
	v_mfma_f32_16x16x32_bf16 v[60:63], v[156:159], v[208:211], v[60:63]
	v_mfma_f32_16x16x32_bf16 v[56:59], v[182:185], v[208:211], v[56:59]
	v_mfma_f32_16x16x32_bf16 v[44:47], v[156:159], v[216:219], v[44:47]
	v_mfma_f32_16x16x32_bf16 v[40:43], v[182:185], v[216:219], v[40:43]
	v_mfma_f32_16x16x32_bf16 v[28:31], v[156:159], v[224:227], v[28:31]
	v_mfma_f32_16x16x32_bf16 v[24:27], v[182:185], v[224:227], v[24:27]
	v_mfma_f32_16x16x32_bf16 v[12:15], v[156:159], v[232:235], v[12:15]
	v_mfma_f32_16x16x32_bf16 v[8:11], v[182:185], v[232:235], v[8:11]
	v_mfma_f32_16x16x32_bf16 v[52:55], v[188:191], v[204:207], v[52:55]
	v_mfma_f32_16x16x32_bf16 v[48:51], v[196:199], v[204:207], v[48:51]
	v_mfma_f32_16x16x32_bf16 v[36:39], v[188:191], v[212:215], v[36:39]
	v_mfma_f32_16x16x32_bf16 v[32:35], v[196:199], v[212:215], v[32:35]
	v_mfma_f32_16x16x32_bf16 v[20:23], v[188:191], v[220:223], v[20:23]
	v_mfma_f32_16x16x32_bf16 v[16:19], v[196:199], v[220:223], v[16:19]
	v_mfma_f32_16x16x32_bf16 v[4:7], v[188:191], v[228:231], v[4:7]
	v_mfma_f32_16x16x32_bf16 v[0:3], v[196:199], v[228:231], v[0:3]
	v_mfma_f32_16x16x32_bf16 v[52:55], v[192:195], v[208:211], v[52:55]
	v_mfma_f32_16x16x32_bf16 v[48:51], v[200:203], v[208:211], v[48:51]
	v_mfma_f32_16x16x32_bf16 v[36:39], v[192:195], v[216:219], v[36:39]
	v_mfma_f32_16x16x32_bf16 v[32:35], v[200:203], v[216:219], v[32:35]
	v_mfma_f32_16x16x32_bf16 v[20:23], v[192:195], v[224:227], v[20:23]
	v_mfma_f32_16x16x32_bf16 v[16:19], v[200:203], v[224:227], v[16:19]
	v_mfma_f32_16x16x32_bf16 v[4:7], v[192:195], v[232:235], v[4:7]
	v_mfma_f32_16x16x32_bf16 v[0:3], v[200:203], v[232:235], v[0:3]
	s_barrier
	s_add_i32 s91, s91, 2
	s_add_u32 s14, s14, 0x100
	s_addc_u32 s15, s15, 0
	s_add_u32 s66, s66, 0x100
	s_addc_u32 s67, s67, 0
	s_cmp_gt_u32 s91, 13
	s_cbranch_scc0 .LBB0_404
	s_and_b64 vcc, exec, s[34:35]
	s_cbranch_vccz .LBB0_407
	s_barrier

; #define PG8_STAGE(bufoff, gbase, voff) do { _Pragma("unroll") for (int _i = 0; _i < 2; ++_i) \
;         __builtin_amdgcn_global_load_lds((const unsigned*)((const char*)(gbase) + (voff)[_i]), (PG8_LAS unsigned*)(lds + (bufoff) + ldsw + _i * 8192), 16, 0, 0); } while (0)
; #define PG8_LDA(dst, b, h) do { _Pragma("unroll") for (int m = 0; m < 4; ++m) _Pragma("unroll") for (int k = 0; k < 2; ++k) dst[m][k] = *(const PG8_LAS bf16x8*)(lds + PG8_SA(b, h) + aoff + m * 2048 + k * 1024); } while (0)
; #define PG8_LDB(dst, b, h) do { _Pragma("unroll") for (int n = 0; n < 2; ++n) _Pragma("unroll") for (int k = 0; k < 2; ++k) dst[n][k] = *(const PG8_LAS bf16x8*)(lds + PG8_SB(b, h) + boff + n * 2048 + k * 1024); } while (0)
; #define PG8_MMA(ai, bj, At, Bt) do { __builtin_amdgcn_s_setprio(1); _Pragma("unroll") for (int m = 0; m < 4; ++m) _Pragma("unroll") for (int n = 0; n < 2; ++n) _Pragma("unroll") for (int k = 0; k < 2; ++k) \
;         acc[ai][bj][m][n] = __builtin_amdgcn_mfma_f32_16x16x32_bf16(Bt[n][k], At[m][k], acc[ai][bj][m][n], 0, 0, 0); __builtin_amdgcn_s_setprio(0); } while (0)
; #define PG8_WAIT_V(n) asm volatile("s_waitcnt vmcnt(" #n ")" ::: "memory")
; #define PG8_WAIT_L(n) asm volatile("s_waitcnt lgkmcnt(" #n ")" ::: "memory")
; #define PG8_BAR __builtin_amdgcn_s_barrier()
; #define PG8_SCHED __builtin_amdgcn_sched_barrier(0)
; template <class Epi, class Sched, bool ALIGN_EPI = false, bool SP2 = false>
; __device__ __forceinline__ void gemm_phase(PG8_LAS unsigned char* lds, const Gemm g, const Sched& S, const Epi& E) {
;     ...
;             if constexpr (SP2) {
;             PG8_LDB(B0, 0, 0); PG8_LDB(B1, 0, 1); PG8_SCHED; PG8_LDA(At, 0, 0); PG8_STAGE(PG8_SA(1, 1), a1 + hstepA, voffA);
;             PG8_WAIT_V(8); PG8_WAIT_L(0); PG8_BAR; PG8_MMA(0, 0, At, B0); PG8_MMA(0, 1, At, B1); PG8_BAR; PG8_SCHED;
;             PG8_LDA(At, 0, 1); PG8_STAGE(PG8_SB(0, 0), b2, voffB); PG8_STAGE(PG8_SB(0, 1), b2 + hstepB, voffB); PG8_STAGE(PG8_SA(0, 0), a2, voffA);
;             PG8_WAIT_V(8); PG8_WAIT_L(0); PG8_BAR; PG8_MMA(1, 0, At, B0); PG8_MMA(1, 1, At, B1); PG8_BAR; PG8_SCHED;
.LBB0_524:
	ds_read_b128 v[144:147], v153
	ds_read_b128 v[158:161], v153 offset:1024
	ds_read_b128 v[162:165], v153 offset:2048
	ds_read_b128 v[166:169], v153 offset:3072
	ds_read_b128 v[170:173], v154
	ds_read_b128 v[174:177], v154 offset:1024
	ds_read_b128 v[178:181], v154 offset:2048
	ds_read_b128 v[182:185], v154 offset:3072
	s_add_u32 s30, s28, 0x100
	s_addc_u32 s31, s29, 0
	s_cmp_eq_u32 s76, 2
	s_cselect_b32 s37, s9, s31
	s_cselect_b32 s36, s8, s30
	s_cselect_b32 s35, s25, s75
	s_cselect_b32 s34, s24, s74
	v_lshl_add_u64 v[148:149], s[28:29], 0, v[136:137]
	s_add_i32 m0, s42, 0xc000
	ds_read_b128 v[188:191], v155
	ds_read_b128 v[192:195], v155 offset:1024
	ds_read_b128 v[196:199], v155 offset:2048
	ds_read_b128 v[200:203], v155 offset:3072
	ds_read_b128 v[204:207], v155 offset:4096
	ds_read_b128 v[208:211], v155 offset:5120
	ds_read_b128 v[212:215], v155 offset:6144
	ds_read_b128 v[216:219], v155 offset:7168
	global_load_lds_dwordx4 v[148:149], off
	v_lshl_add_u64 v[148:149], s[28:29], 0, v[138:139]
	s_add_i32 m0, s42, 0xe000
	s_nop 0
	global_load_lds_dwordx4 v[148:149], off
	s_waitcnt vmcnt(8) lgkmcnt(0)
	s_barrier
	v_mfma_f32_16x16x32_bf16 v[124:127], v[144:147], v[188:191], v[124:127]
	v_mfma_f32_16x16x32_bf16 v[120:123], v[162:165], v[188:191], v[120:123]
	v_mfma_f32_16x16x32_bf16 v[108:111], v[144:147], v[196:199], v[108:111]
	v_mfma_f32_16x16x32_bf16 v[104:107], v[162:165], v[196:199], v[104:107]
	v_mfma_f32_16x16x32_bf16 v[92:95], v[144:147], v[204:207], v[92:95]
	v_mfma_f32_16x16x32_bf16 v[88:91], v[162:165], v[204:207], v[88:91]
	v_mfma_f32_16x16x32_bf16 v[76:79], v[144:147], v[212:215], v[76:79]
	v_mfma_f32_16x16x32_bf16 v[72:75], v[162:165], v[212:215], v[72:75]
	v_mfma_f32_16x16x32_bf16 v[124:127], v[158:161], v[192:195], v[124:127]
	v_mfma_f32_16x16x32_bf16 v[120:123], v[166:169], v[192:195], v[120:123]
	v_mfma_f32_16x16x32_bf16 v[108:111], v[158:161], v[200:203], v[108:111]
	v_mfma_f32_16x16x32_bf16 v[104:107], v[166:169], v[200:203], v[104:107]
	v_mfma_f32_16x16x32_bf16 v[92:95], v[158:161], v[208:211], v[92:95]
	v_mfma_f32_16x16x32_bf16 v[88:91], v[166:169], v[208:211], v[88:91]
	v_mfma_f32_16x16x32_bf16 v[76:79], v[158:161], v[216:219], v[76:79]
	v_mfma_f32_16x16x32_bf16 v[72:75], v[166:169], v[216:219], v[72:75]
	v_mfma_f32_16x16x32_bf16 v[116:119], v[170:173], v[188:191], v[116:119]
	v_mfma_f32_16x16x32_bf16 v[112:115], v[178:181], v[188:191], v[112:115]
	v_mfma_f32_16x16x32_bf16 v[100:103], v[170:173], v[196:199], v[100:103]
	v_mfma_f32_16x16x32_bf16 v[96:99], v[178:181], v[196:199], v[96:99]
	v_mfma_f32_16x16x32_bf16 v[84:87], v[170:173], v[204:207], v[84:87]
	v_mfma_f32_16x16x32_bf16 v[80:83], v[178:181], v[204:207], v[80:83]
	v_mfma_f32_16x16x32_bf16 v[68:71], v[170:173], v[212:215], v[68:71]
	v_mfma_f32_16x16x32_bf16 v[64:67], v[178:181], v[212:215], v[64:67]
	v_mfma_f32_16x16x32_bf16 v[116:119], v[174:177], v[192:195], v[116:119]
	v_mfma_f32_16x16x32_bf16 v[112:115], v[182:185], v[192:195], v[112:115]
	v_mfma_f32_16x16x32_bf16 v[100:103], v[174:177], v[200:203], v[100:103]
	v_mfma_f32_16x16x32_bf16 v[96:99], v[182:185], v[200:203], v[96:99]
	v_mfma_f32_16x16x32_bf16 v[84:87], v[174:177], v[208:211], v[84:87]
	v_mfma_f32_16x16x32_bf16 v[80:83], v[182:185], v[208:211], v[80:83]
	v_mfma_f32_16x16x32_bf16 v[68:71], v[174:177], v[216:219], v[68:71]
	v_mfma_f32_16x16x32_bf16 v[64:67], v[182:185], v[216:219], v[64:67]
	s_barrier
	s_add_i32 s28, s66, s40
	v_lshl_add_u64 v[148:149], s[34:35], 0, v[132:133]
	s_mov_b32 m0, s28
	ds_read_b128 v[188:191], v155 offset:16384
	ds_read_b128 v[192:195], v155 offset:17408
	ds_read_b128 v[196:199], v155 offset:18432
	ds_read_b128 v[200:203], v155 offset:19456
	ds_read_b128 v[204:207], v155 offset:20480
	ds_read_b128 v[208:211], v155 offset:21504
	ds_read_b128 v[212:215], v155 offset:22528
	ds_read_b128 v[216:219], v155 offset:23552
	global_load_lds_dwordx4 v[148:149], off
	s_add_i32 m0, s28, 0x2000
	s_add_u32 s28, s34, 0x18000
	v_lshl_add_u64 v[220:221], s[34:35], 0, v[128:129]
	s_addc_u32 s29, s35, 0
	s_add_i32 s58, s67, s40
	global_load_lds_dwordx4 v[220:221], off
	v_lshl_add_u64 v[222:223], s[28:29], 0, v[132:133]
	s_mov_b32 m0, s58
	v_lshl_add_u64 v[224:225], s[36:37], 0, v[130:131]
	global_load_lds_dwordx4 v[222:223], off
	v_lshl_add_u64 v[222:223], s[28:29], 0, v[128:129]
	s_add_i32 m0, s58, 0x2000
	s_nop 0
	global_load_lds_dwordx4 v[222:223], off
	v_lshl_add_u64 v[222:223], s[36:37], 0, v[134:135]
	s_mov_b32 m0, s42
	s_nop 0
	global_load_lds_dwordx4 v[222:223], off
	s_mov_b32 m0, s43
	s_nop 0
	global_load_lds_dwordx4 v[224:225], off
	s_waitcnt vmcnt(8) lgkmcnt(0)
	s_barrier
; #define PG8_STAGE(bufoff, gbase, voff) do { _Pragma("unroll") for (int _i = 0; _i < 2; ++_i) \
;         __builtin_amdgcn_global_load_lds((const unsigned*)((const char*)(gbase) + (voff)[_i]), (PG8_LAS unsigned*)(lds + (bufoff) + ldsw + _i * 8192), 16, 0, 0); } while (0)
; #define PG8_LDA(dst, b, h) do { _Pragma("unroll") for (int m = 0; m < 4; ++m) _Pragma("unroll") for (int k = 0; k < 2; ++k) dst[m][k] = *(const PG8_LAS bf16x8*)(lds + PG8_SA(b, h) + aoff + m * 2048 + k * 1024); } while (0)
; #define PG8_LDB(dst, b, h) do { _Pragma("unroll") for (int n = 0; n < 2; ++n) _Pragma("unroll") for (int k = 0; k < 2; ++k) dst[n][k] = *(const PG8_LAS bf16x8*)(lds + PG8_SB(b, h) + boff + n * 2048 + k * 1024); } while (0)
; #define PG8_MMA(ai, bj, At, Bt) do { __builtin_amdgcn_s_setprio(1); _Pragma("unroll") for (int m = 0; m < 4; ++m) _Pragma("unroll") for (int n = 0; n < 2; ++n) _Pragma("unroll") for (int k = 0; k < 2; ++k) \
;         acc[ai][bj][m][n] = __builtin_amdgcn_mfma_f32_16x16x32_bf16(Bt[n][k], At[m][k], acc[ai][bj][m][n], 0, 0, 0); __builtin_amdgcn_s_setprio(0); } while (0)
; #define PG8_WAIT_V(n) asm volatile("s_waitcnt vmcnt(" #n ")" ::: "memory")
; #define PG8_WAIT_L(n) asm volatile("s_waitcnt lgkmcnt(" #n ")" ::: "memory")
; #define PG8_BAR __builtin_amdgcn_s_barrier()
; #define PG8_SCHED __builtin_amdgcn_sched_barrier(0)
; template <class Epi, class Sched, bool ALIGN_EPI = false, bool SP2 = false>
; __device__ __forceinline__ void gemm_phase(PG8_LAS unsigned char* lds, const Gemm g, const Sched& S, const Epi& E) {
;     ...
;             PG8_WAIT_V(8); PG8_WAIT_L(0); PG8_BAR; PG8_MMA(1, 0, At, B0); PG8_MMA(1, 1, At, B1); PG8_BAR; PG8_SCHED;
;             PG8_LDB(B0, 1, 0); PG8_LDB(B1, 1, 1); PG8_SCHED; PG8_LDA(At, 1, 0); PG8_STAGE(PG8_SA(0, 1), a2 + hstepA, voffA);
;             PG8_WAIT_V(8); PG8_WAIT_L(0); PG8_BAR; PG8_MMA(0, 0, At, B0); PG8_MMA(0, 1, At, B1); PG8_BAR; PG8_SCHED;
	v_mfma_f32_16x16x32_bf16 v[60:63], v[144:147], v[188:191], v[60:63]
	v_mfma_f32_16x16x32_bf16 v[56:59], v[162:165], v[188:191], v[56:59]
	v_mfma_f32_16x16x32_bf16 v[44:47], v[144:147], v[196:199], v[44:47]
	v_mfma_f32_16x16x32_bf16 v[40:43], v[162:165], v[196:199], v[40:43]
	v_mfma_f32_16x16x32_bf16 v[28:31], v[144:147], v[204:207], v[28:31]
	v_mfma_f32_16x16x32_bf16 v[24:27], v[162:165], v[204:207], v[24:27]
	v_mfma_f32_16x16x32_bf16 v[12:15], v[144:147], v[212:215], v[12:15]
	v_mfma_f32_16x16x32_bf16 v[8:11], v[162:165], v[212:215], v[8:11]
	v_mfma_f32_16x16x32_bf16 v[60:63], v[158:161], v[192:195], v[60:63]
	v_mfma_f32_16x16x32_bf16 v[56:59], v[166:169], v[192:195], v[56:59]
	v_mfma_f32_16x16x32_bf16 v[44:47], v[158:161], v[200:203], v[44:47]
	v_mfma_f32_16x16x32_bf16 v[40:43], v[166:169], v[200:203], v[40:43]
	v_mfma_f32_16x16x32_bf16 v[28:31], v[158:161], v[208:211], v[28:31]
	v_mfma_f32_16x16x32_bf16 v[24:27], v[166:169], v[208:211], v[24:27]
	v_mfma_f32_16x16x32_bf16 v[12:15], v[158:161], v[216:219], v[12:15]
	v_mfma_f32_16x16x32_bf16 v[8:11], v[166:169], v[216:219], v[8:11]
	v_mfma_f32_16x16x32_bf16 v[52:55], v[170:173], v[188:191], v[52:55]
	v_mfma_f32_16x16x32_bf16 v[48:51], v[178:181], v[188:191], v[48:51]
	v_mfma_f32_16x16x32_bf16 v[36:39], v[170:173], v[196:199], v[36:39]
	v_mfma_f32_16x16x32_bf16 v[32:35], v[178:181], v[196:199], v[32:35]
	v_mfma_f32_16x16x32_bf16 v[20:23], v[170:173], v[204:207], v[20:23]
	v_mfma_f32_16x16x32_bf16 v[16:19], v[178:181], v[204:207], v[16:19]
	v_mfma_f32_16x16x32_bf16 v[4:7], v[170:173], v[212:215], v[4:7]
	v_mfma_f32_16x16x32_bf16 v[0:3], v[178:181], v[212:215], v[0:3]
	v_mfma_f32_16x16x32_bf16 v[52:55], v[174:177], v[192:195], v[52:55]
	v_mfma_f32_16x16x32_bf16 v[48:51], v[182:185], v[192:195], v[48:51]
	v_mfma_f32_16x16x32_bf16 v[36:39], v[174:177], v[200:203], v[36:39]
	v_mfma_f32_16x16x32_bf16 v[32:35], v[182:185], v[200:203], v[32:35]
	v_mfma_f32_16x16x32_bf16 v[20:23], v[174:177], v[208:211], v[20:23]
	v_mfma_f32_16x16x32_bf16 v[16:19], v[182:185], v[208:211], v[16:19]
	v_mfma_f32_16x16x32_bf16 v[4:7], v[174:177], v[216:219], v[4:7]
	v_mfma_f32_16x16x32_bf16 v[0:3], v[182:185], v[216:219], v[0:3]
	s_barrier
	s_add_i32 s58, 0, 0x18000
	v_add_u32_e32 v157, s58, v151
	s_add_i32 s59, 0, 0x1c000
	ds_read_b128 v[144:147], v157
	ds_read_b128 v[158:161], v157 offset:1024
	ds_read_b128 v[162:165], v157 offset:2048
	ds_read_b128 v[166:169], v157 offset:3072
	v_add_u32_e32 v157, s59, v151
	ds_read_b128 v[170:173], v157
	ds_read_b128 v[174:177], v157 offset:1024
	ds_read_b128 v[178:181], v157 offset:2048
	ds_read_b128 v[182:185], v157 offset:3072
	s_add_u32 s28, s36, 0x30000
	s_addc_u32 s29, s37, 0
	s_mov_b32 m0, s44
	v_lshl_add_u64 v[226:227], s[28:29], 0, v[134:135]
	ds_read_b128 v[188:191], v155 offset:32768
	ds_read_b128 v[192:195], v155 offset:33792
	ds_read_b128 v[196:199], v155 offset:34816
	ds_read_b128 v[200:203], v155 offset:35840
	ds_read_b128 v[204:207], v155 offset:36864
	ds_read_b128 v[208:211], v155 offset:37888
	ds_read_b128 v[212:215], v155 offset:38912
	ds_read_b128 v[216:219], v155 offset:39936
	global_load_lds_dwordx4 v[226:227], off
	v_lshl_add_u64 v[226:227], s[28:29], 0, v[130:131]
	s_mov_b32 m0, s45
	s_nop 0
	global_load_lds_dwordx4 v[226:227], off
	s_waitcnt vmcnt(8) lgkmcnt(0)
	s_barrier
	v_mfma_f32_16x16x32_bf16 v[124:127], v[144:147], v[188:191], v[124:127]
	v_mfma_f32_16x16x32_bf16 v[120:123], v[162:165], v[188:191], v[120:123]
	v_mfma_f32_16x16x32_bf16 v[108:111], v[144:147], v[196:199], v[108:111]
	v_mfma_f32_16x16x32_bf16 v[104:107], v[162:165], v[196:199], v[104:107]
	v_mfma_f32_16x16x32_bf16 v[92:95], v[144:147], v[204:207], v[92:95]
	v_mfma_f32_16x16x32_bf16 v[88:91], v[162:165], v[204:207], v[88:91]
	v_mfma_f32_16x16x32_bf16 v[76:79], v[144:147], v[212:215], v[76:79]
	v_mfma_f32_16x16x32_bf16 v[72:75], v[162:165], v[212:215], v[72:75]
	v_mfma_f32_16x16x32_bf16 v[124:127], v[158:161], v[192:195], v[124:127]
	v_mfma_f32_16x16x32_bf16 v[120:123], v[166:169], v[192:195], v[120:123]
	v_mfma_f32_16x16x32_bf16 v[108:111], v[158:161], v[200:203], v[108:111]
	v_mfma_f32_16x16x32_bf16 v[104:107], v[166:169], v[200:203], v[104:107]
	v_mfma_f32_16x16x32_bf16 v[92:95], v[158:161], v[208:211], v[92:95]
	v_mfma_f32_16x16x32_bf16 v[88:91], v[166:169], v[208:211], v[88:91]
	v_mfma_f32_16x16x32_bf16 v[76:79], v[158:161], v[216:219], v[76:79]
	v_mfma_f32_16x16x32_bf16 v[72:75], v[166:169], v[216:219], v[72:75]
	v_mfma_f32_16x16x32_bf16 v[116:119], v[170:173], v[188:191], v[116:119]
	v_mfma_f32_16x16x32_bf16 v[112:115], v[178:181], v[188:191], v[112:115]
	v_mfma_f32_16x16x32_bf16 v[100:103], v[170:173], v[196:199], v[100:103]
	v_mfma_f32_16x16x32_bf16 v[96:99], v[178:181], v[196:199], v[96:99]
	v_mfma_f32_16x16x32_bf16 v[84:87], v[170:173], v[204:207], v[84:87]
	v_mfma_f32_16x16x32_bf16 v[80:83], v[178:181], v[204:207], v[80:83]
	v_mfma_f32_16x16x32_bf16 v[68:71], v[170:173], v[212:215], v[68:71]
	v_mfma_f32_16x16x32_bf16 v[64:67], v[178:181], v[212:215], v[64:67]
	v_mfma_f32_16x16x32_bf16 v[116:119], v[174:177], v[192:195], v[116:119]
	v_mfma_f32_16x16x32_bf16 v[112:115], v[182:185], v[192:195], v[112:115]
	v_mfma_f32_16x16x32_bf16 v[100:103], v[174:177], v[200:203], v[100:103]
	v_mfma_f32_16x16x32_bf16 v[96:99], v[182:185], v[200:203], v[96:99]
	v_mfma_f32_16x16x32_bf16 v[84:87], v[174:177], v[208:211], v[84:87]
	v_mfma_f32_16x16x32_bf16 v[80:83], v[182:185], v[208:211], v[80:83]
	v_mfma_f32_16x16x32_bf16 v[68:71], v[174:177], v[216:219], v[68:71]
	v_mfma_f32_16x16x32_bf16 v[64:67], v[182:185], v[216:219], v[64:67]
	s_barrier
; #define PG8_STAGE(bufoff, gbase, voff) do { _Pragma("unroll") for (int _i = 0; _i < 2; ++_i) \
;         __builtin_amdgcn_global_load_lds((const unsigned*)((const char*)(gbase) + (voff)[_i]), (PG8_LAS unsigned*)(lds + (bufoff) + ldsw + _i * 8192), 16, 0, 0); } while (0)
; #define PG8_LDA(dst, b, h) do { _Pragma("unroll") for (int m = 0; m < 4; ++m) _Pragma("unroll") for (int k = 0; k < 2; ++k) dst[m][k] = *(const PG8_LAS bf16x8*)(lds + PG8_SA(b, h) + aoff + m * 2048 + k * 1024); } while (0)
; #define PG8_MMA(ai, bj, At, Bt) do { __builtin_amdgcn_s_setprio(1); _Pragma("unroll") for (int m = 0; m < 4; ++m) _Pragma("unroll") for (int n = 0; n < 2; ++n) _Pragma("unroll") for (int k = 0; k < 2; ++k) \
;         acc[ai][bj][m][n] = __builtin_amdgcn_mfma_f32_16x16x32_bf16(Bt[n][k], At[m][k], acc[ai][bj][m][n], 0, 0, 0); __builtin_amdgcn_s_setprio(0); } while (0)
; #define PG8_WAIT_V(n) asm volatile("s_waitcnt vmcnt(" #n ")" ::: "memory")
; #define PG8_WAIT_L(n) asm volatile("s_waitcnt lgkmcnt(" #n ")" ::: "memory")
; #define PG8_BAR __builtin_amdgcn_s_barrier()
; #define PG8_SCHED __builtin_amdgcn_sched_barrier(0)
; template <class Epi, class Sched, bool ALIGN_EPI = false, bool SP2 = false>
; __device__ __forceinline__ void gemm_phase(PG8_LAS unsigned char* lds, const Gemm g, const Sched& S, const Epi& E) {
;     ...
;             PG8_LDA(At, 1, 1); PG8_STAGE(PG8_SB(1, 0), b3, voffB); PG8_STAGE(PG8_SB(1, 1), b3 + hstepB, voffB); PG8_STAGE(PG8_SA(1, 0), a3, voffA);
;             PG8_WAIT_V(8); PG8_WAIT_L(0); PG8_BAR; PG8_MMA(1, 0, At, B0); PG8_MMA(1, 1, At, B1); PG8_BAR; PG8_SCHED;
;     ...
;         if constexpr (ALIGN_EPI) { if (wr == 0) PG8_BAR; }
	s_add_i32 s28, s58, s40
	v_lshl_add_u64 v[148:149], v[148:149], 0, s[12:13]
	s_mov_b32 m0, s28
	ds_read_b128 v[188:191], v155 offset:49152
	ds_read_b128 v[192:195], v155 offset:50176
	ds_read_b128 v[196:199], v155 offset:51200
	ds_read_b128 v[200:203], v155 offset:52224
	ds_read_b128 v[204:207], v155 offset:53248
	ds_read_b128 v[208:211], v155 offset:54272
	ds_read_b128 v[212:215], v155 offset:55296
	ds_read_b128 v[216:219], v155 offset:56320
	global_load_lds_dwordx4 v[148:149], off
	s_add_i32 m0, s28, 0x2000
	s_add_u32 s28, s34, 0x18080
	v_lshl_add_u64 v[148:149], v[220:221], 0, s[12:13]
	s_addc_u32 s29, s35, 0
	s_add_i32 s34, s59, s40
	global_load_lds_dwordx4 v[148:149], off
	v_lshl_add_u64 v[148:149], s[28:29], 0, v[132:133]
	s_mov_b32 m0, s34
	s_nop 0
	global_load_lds_dwordx4 v[148:149], off
	v_lshl_add_u64 v[148:149], s[28:29], 0, v[128:129]
	s_add_i32 m0, s34, 0x2000
	s_nop 0
	global_load_lds_dwordx4 v[148:149], off
	v_lshl_add_u64 v[148:149], v[222:223], 0, s[12:13]
	s_mov_b32 m0, s47
	s_nop 0
	global_load_lds_dwordx4 v[148:149], off
	v_lshl_add_u64 v[148:149], v[224:225], 0, s[12:13]
	s_mov_b32 m0, s48
	s_nop 0
	global_load_lds_dwordx4 v[148:149], off
	s_waitcnt vmcnt(8) lgkmcnt(0)
	s_barrier
	v_mfma_f32_16x16x32_bf16 v[60:63], v[144:147], v[188:191], v[60:63]
	v_mfma_f32_16x16x32_bf16 v[56:59], v[162:165], v[188:191], v[56:59]
	v_mfma_f32_16x16x32_bf16 v[44:47], v[144:147], v[196:199], v[44:47]
	v_mfma_f32_16x16x32_bf16 v[40:43], v[162:165], v[196:199], v[40:43]
	v_mfma_f32_16x16x32_bf16 v[28:31], v[144:147], v[204:207], v[28:31]
	v_mfma_f32_16x16x32_bf16 v[24:27], v[162:165], v[204:207], v[24:27]
	v_mfma_f32_16x16x32_bf16 v[12:15], v[144:147], v[212:215], v[12:15]
	v_mfma_f32_16x16x32_bf16 v[8:11], v[162:165], v[212:215], v[8:11]
	v_mfma_f32_16x16x32_bf16 v[60:63], v[158:161], v[192:195], v[60:63]
	v_mfma_f32_16x16x32_bf16 v[56:59], v[166:169], v[192:195], v[56:59]
	v_mfma_f32_16x16x32_bf16 v[44:47], v[158:161], v[200:203], v[44:47]
	v_mfma_f32_16x16x32_bf16 v[40:43], v[166:169], v[200:203], v[40:43]
	v_mfma_f32_16x16x32_bf16 v[28:31], v[158:161], v[208:211], v[28:31]
	v_mfma_f32_16x16x32_bf16 v[24:27], v[166:169], v[208:211], v[24:27]
	v_mfma_f32_16x16x32_bf16 v[12:15], v[158:161], v[216:219], v[12:15]
	v_mfma_f32_16x16x32_bf16 v[8:11], v[166:169], v[216:219], v[8:11]
	v_mfma_f32_16x16x32_bf16 v[52:55], v[170:173], v[188:191], v[52:55]
	v_mfma_f32_16x16x32_bf16 v[48:51], v[178:181], v[188:191], v[48:51]
	v_mfma_f32_16x16x32_bf16 v[36:39], v[170:173], v[196:199], v[36:39]
	v_mfma_f32_16x16x32_bf16 v[32:35], v[178:181], v[196:199], v[32:35]
	v_mfma_f32_16x16x32_bf16 v[20:23], v[170:173], v[204:207], v[20:23]
	v_mfma_f32_16x16x32_bf16 v[16:19], v[178:181], v[204:207], v[16:19]
	v_mfma_f32_16x16x32_bf16 v[4:7], v[170:173], v[212:215], v[4:7]
	v_mfma_f32_16x16x32_bf16 v[0:3], v[178:181], v[212:215], v[0:3]
	v_mfma_f32_16x16x32_bf16 v[52:55], v[174:177], v[192:195], v[52:55]
	v_mfma_f32_16x16x32_bf16 v[48:51], v[182:185], v[192:195], v[48:51]
	v_mfma_f32_16x16x32_bf16 v[36:39], v[174:177], v[200:203], v[36:39]
	v_mfma_f32_16x16x32_bf16 v[32:35], v[182:185], v[200:203], v[32:35]
	v_mfma_f32_16x16x32_bf16 v[20:23], v[174:177], v[208:211], v[20:23]
	v_mfma_f32_16x16x32_bf16 v[16:19], v[182:185], v[208:211], v[16:19]
	v_mfma_f32_16x16x32_bf16 v[4:7], v[174:177], v[216:219], v[4:7]
	v_mfma_f32_16x16x32_bf16 v[0:3], v[182:185], v[216:219], v[0:3]
	s_barrier
	s_add_i32 s76, s76, 2
	s_add_u32 s74, s74, 0x100
	s_addc_u32 s75, s75, 0
	s_cmp_gt_u32 s76, 3
	s_mov_b64 s[28:29], s[30:31]
	s_cbranch_scc0 .LBB0_524
	s_and_b64 vcc, exec, s[14:15]
	s_cbranch_vccz .LBB0_527
	s_barrier

; #define PG8_STAGE(bufoff, gbase, voff) do { _Pragma("unroll") for (int _i = 0; _i < 2; ++_i) \
;         __builtin_amdgcn_global_load_lds((const unsigned*)((const char*)(gbase) + (voff)[_i]), (PG8_LAS unsigned*)(lds + (bufoff) + ldsw + _i * 8192), 16, 0, 0); } while (0)
; #define PG8_LDA(dst, b, h) do { _Pragma("unroll") for (int m = 0; m < 4; ++m) _Pragma("unroll") for (int k = 0; k < 2; ++k) dst[m][k] = *(const PG8_LAS bf16x8*)(lds + PG8_SA(b, h) + aoff + m * 2048 + k * 1024); } while (0)
; #define PG8_LDB(dst, b, h) do { _Pragma("unroll") for (int n = 0; n < 2; ++n) _Pragma("unroll") for (int k = 0; k < 2; ++k) dst[n][k] = *(const PG8_LAS bf16x8*)(lds + PG8_SB(b, h) + boff + n * 2048 + k * 1024); } while (0)
; #define PG8_MMA(ai, bj, At, Bt) do { __builtin_amdgcn_s_setprio(1); _Pragma("unroll") for (int m = 0; m < 4; ++m) _Pragma("unroll") for (int n = 0; n < 2; ++n) _Pragma("unroll") for (int k = 0; k < 2; ++k) \
;         acc[ai][bj][m][n] = __builtin_amdgcn_mfma_f32_16x16x32_bf16(Bt[n][k], At[m][k], acc[ai][bj][m][n], 0, 0, 0); __builtin_amdgcn_s_setprio(0); } while (0)
; #define PG8_WAIT_V(n) asm volatile("s_waitcnt vmcnt(" #n ")" ::: "memory")
; #define PG8_WAIT_L(n) asm volatile("s_waitcnt lgkmcnt(" #n ")" ::: "memory")
; #define PG8_BAR __builtin_amdgcn_s_barrier()
; #define PG8_SCHED __builtin_amdgcn_sched_barrier(0)
; template <class Epi, class Sched, bool ALIGN_EPI = false, bool SP2 = false>
; __device__ __forceinline__ void gemm_phase(PG8_LAS unsigned char* lds, const Gemm g, const Sched& S, const Epi& E) {
;     ...
;             if constexpr (SP2) {
;             PG8_LDB(B0, 0, 0); PG8_LDB(B1, 0, 1); PG8_SCHED; PG8_LDA(At, 0, 0); PG8_STAGE(PG8_SA(1, 1), a1 + hstepA, voffA);
;             PG8_WAIT_V(8); PG8_WAIT_L(0); PG8_BAR; PG8_MMA(0, 0, At, B0); PG8_MMA(0, 1, At, B1); PG8_BAR; PG8_SCHED;
;             PG8_LDA(At, 0, 1); PG8_STAGE(PG8_SB(0, 0), b2, voffB); PG8_STAGE(PG8_SB(0, 1), b2 + hstepB, voffB); PG8_STAGE(PG8_SA(0, 0), a2, voffA);
;             PG8_WAIT_V(8); PG8_WAIT_L(0); PG8_BAR; PG8_MMA(1, 0, At, B0); PG8_MMA(1, 1, At, B1); PG8_BAR; PG8_SCHED;
.LBB0_542:
	s_add_u32 s39, s34, s38
	s_addc_u32 s44, s35, 0
	s_add_u32 s42, s39, 0x100
	s_addc_u32 s43, s44, 0
	s_and_b64 s[40:41], s[36:37], exec
	s_cselect_b32 s41, s27, s43
	s_cselect_b32 s40, s26, s42
	s_add_u32 s38, s30, s38
	s_addc_u32 s42, s31, 0
	s_add_u32 s38, s38, 0x100
	s_addc_u32 s42, s42, 0
	s_and_b64 s[36:37], s[36:37], exec
	s_cselect_b32 s43, s25, s42
	s_cselect_b32 s42, s89, s38
	s_add_u32 s46, s39, 0x30080
	ds_read_b128 v[140:143], v149
	ds_read_b128 v[154:157], v149 offset:1024
	ds_read_b128 v[158:161], v149 offset:2048
	ds_read_b128 v[162:165], v149 offset:3072
	ds_read_b128 v[166:169], v150
	ds_read_b128 v[170:173], v150 offset:1024
	ds_read_b128 v[174:177], v150 offset:2048
	ds_read_b128 v[178:181], v150 offset:3072
	s_addc_u32 s47, s44, 0
	s_add_i32 vcc_hi, s78, s68
	s_add_i32 m0, s70, 0xc000
	s_add_i32 s58, s70, 0xe000
	s_add_i32 s96, vcc_hi, 0x2000
	s_add_u32 s44, s42, 0x10000
	s_addc_u32 s45, s43, 0
	s_add_i32 vcc_lo, s79, s68
	s_add_i32 s97, vcc_lo, 0x2000
	s_add_i32 s95, 0, 0x18000
	s_add_i32 s94, 0, 0x1c000
	s_add_u32 s38, s40, 0x30000
	s_addc_u32 s39, s41, 0
	s_add_i32 s93, s95, s68
	s_add_i32 s91, s93, 0x2000
	s_add_u32 s36, s42, 0x10080
	s_addc_u32 s37, s43, 0
	s_add_i32 s92, s94, s68
	s_add_i32 s90, s92, 0x2000
	v_lshl_add_u64 v[144:145], s[46:47], 0, v[134:135]
	ds_read_b128 v[182:185], v151
	ds_read_b128 v[188:191], v151 offset:1024
	ds_read_b128 v[192:195], v151 offset:2048
	ds_read_b128 v[196:199], v151 offset:3072
	ds_read_b128 v[200:203], v151 offset:4096
	ds_read_b128 v[204:207], v151 offset:5120
	ds_read_b128 v[208:211], v151 offset:6144
	ds_read_b128 v[212:215], v151 offset:7168
	global_load_lds_dwordx4 v[144:145], off
	v_lshl_add_u64 v[144:145], s[46:47], 0, v[130:131]
	s_mov_b32 m0, s58
	s_nop 0
	global_load_lds_dwordx4 v[144:145], off
	s_waitcnt vmcnt(8) lgkmcnt(0)
	s_barrier
	v_mfma_f32_16x16x32_bf16 v[124:127], v[140:143], v[182:185], v[124:127]
	v_mfma_f32_16x16x32_bf16 v[120:123], v[158:161], v[182:185], v[120:123]
	v_mfma_f32_16x16x32_bf16 v[108:111], v[140:143], v[192:195], v[108:111]
	v_mfma_f32_16x16x32_bf16 v[104:107], v[158:161], v[192:195], v[104:107]
	v_mfma_f32_16x16x32_bf16 v[92:95], v[140:143], v[200:203], v[92:95]
	v_mfma_f32_16x16x32_bf16 v[88:91], v[158:161], v[200:203], v[88:91]
	v_mfma_f32_16x16x32_bf16 v[76:79], v[140:143], v[208:211], v[76:79]
	v_mfma_f32_16x16x32_bf16 v[72:75], v[158:161], v[208:211], v[72:75]
	v_mfma_f32_16x16x32_bf16 v[124:127], v[154:157], v[188:191], v[124:127]
	v_mfma_f32_16x16x32_bf16 v[120:123], v[162:165], v[188:191], v[120:123]
	v_mfma_f32_16x16x32_bf16 v[108:111], v[154:157], v[196:199], v[108:111]
	v_mfma_f32_16x16x32_bf16 v[104:107], v[162:165], v[196:199], v[104:107]
	v_mfma_f32_16x16x32_bf16 v[92:95], v[154:157], v[204:207], v[92:95]
	v_mfma_f32_16x16x32_bf16 v[88:91], v[162:165], v[204:207], v[88:91]
	v_mfma_f32_16x16x32_bf16 v[76:79], v[154:157], v[212:215], v[76:79]
	v_mfma_f32_16x16x32_bf16 v[72:75], v[162:165], v[212:215], v[72:75]
	v_mfma_f32_16x16x32_bf16 v[116:119], v[166:169], v[182:185], v[116:119]
	v_mfma_f32_16x16x32_bf16 v[112:115], v[174:177], v[182:185], v[112:115]
	v_mfma_f32_16x16x32_bf16 v[100:103], v[166:169], v[192:195], v[100:103]
	v_mfma_f32_16x16x32_bf16 v[96:99], v[174:177], v[192:195], v[96:99]
	v_mfma_f32_16x16x32_bf16 v[84:87], v[166:169], v[200:203], v[84:87]
	v_mfma_f32_16x16x32_bf16 v[80:83], v[174:177], v[200:203], v[80:83]
	v_mfma_f32_16x16x32_bf16 v[68:71], v[166:169], v[208:211], v[68:71]
	v_mfma_f32_16x16x32_bf16 v[64:67], v[174:177], v[208:211], v[64:67]
	v_mfma_f32_16x16x32_bf16 v[116:119], v[170:173], v[188:191], v[116:119]
	v_mfma_f32_16x16x32_bf16 v[112:115], v[178:181], v[188:191], v[112:115]
	v_mfma_f32_16x16x32_bf16 v[100:103], v[170:173], v[196:199], v[100:103]
	v_mfma_f32_16x16x32_bf16 v[96:99], v[178:181], v[196:199], v[96:99]
	v_mfma_f32_16x16x32_bf16 v[84:87], v[170:173], v[204:207], v[84:87]
	v_mfma_f32_16x16x32_bf16 v[80:83], v[178:181], v[204:207], v[80:83]
	v_mfma_f32_16x16x32_bf16 v[68:71], v[170:173], v[212:215], v[68:71]
	v_mfma_f32_16x16x32_bf16 v[64:67], v[178:181], v[212:215], v[64:67]
	s_barrier
	s_mov_b32 m0, vcc_hi
	v_lshl_add_u64 v[144:145], s[42:43], 0, v[132:133]
	ds_read_b128 v[182:185], v151 offset:16384
	ds_read_b128 v[188:191], v151 offset:17408
	ds_read_b128 v[192:195], v151 offset:18432
	ds_read_b128 v[196:199], v151 offset:19456
	ds_read_b128 v[200:203], v151 offset:20480
	ds_read_b128 v[204:207], v151 offset:21504
	ds_read_b128 v[208:211], v151 offset:22528
	ds_read_b128 v[212:215], v151 offset:23552
	global_load_lds_dwordx4 v[144:145], off
	v_lshl_add_u64 v[216:217], s[42:43], 0, v[128:129]
	s_mov_b32 m0, s96
	v_lshl_add_u64 v[218:219], s[44:45], 0, v[132:133]
	global_load_lds_dwordx4 v[216:217], off
	s_mov_b32 m0, vcc_lo
	v_lshl_add_u64 v[220:221], s[40:41], 0, v[130:131]
	global_load_lds_dwordx4 v[218:219], off
	v_lshl_add_u64 v[218:219], s[44:45], 0, v[128:129]
	s_mov_b32 m0, s97
	s_nop 0
	global_load_lds_dwordx4 v[218:219], off
	v_lshl_add_u64 v[218:219], s[40:41], 0, v[134:135]
	s_mov_b32 m0, s70
	s_nop 0
	global_load_lds_dwordx4 v[218:219], off
	s_mov_b32 m0, s71
	s_nop 0
	global_load_lds_dwordx4 v[220:221], off
	s_waitcnt vmcnt(8) lgkmcnt(0)
	s_barrier
; #define PG8_STAGE(bufoff, gbase, voff) do { _Pragma("unroll") for (int _i = 0; _i < 2; ++_i) \
;         __builtin_amdgcn_global_load_lds((const unsigned*)((const char*)(gbase) + (voff)[_i]), (PG8_LAS unsigned*)(lds + (bufoff) + ldsw + _i * 8192), 16, 0, 0); } while (0)
; #define PG8_LDA(dst, b, h) do { _Pragma("unroll") for (int m = 0; m < 4; ++m) _Pragma("unroll") for (int k = 0; k < 2; ++k) dst[m][k] = *(const PG8_LAS bf16x8*)(lds + PG8_SA(b, h) + aoff + m * 2048 + k * 1024); } while (0)
; #define PG8_LDB(dst, b, h) do { _Pragma("unroll") for (int n = 0; n < 2; ++n) _Pragma("unroll") for (int k = 0; k < 2; ++k) dst[n][k] = *(const PG8_LAS bf16x8*)(lds + PG8_SB(b, h) + boff + n * 2048 + k * 1024); } while (0)
; #define PG8_MMA(ai, bj, At, Bt) do { __builtin_amdgcn_s_setprio(1); _Pragma("unroll") for (int m = 0; m < 4; ++m) _Pragma("unroll") for (int n = 0; n < 2; ++n) _Pragma("unroll") for (int k = 0; k < 2; ++k) \
;         acc[ai][bj][m][n] = __builtin_amdgcn_mfma_f32_16x16x32_bf16(Bt[n][k], At[m][k], acc[ai][bj][m][n], 0, 0, 0); __builtin_amdgcn_s_setprio(0); } while (0)
; #define PG8_WAIT_V(n) asm volatile("s_waitcnt vmcnt(" #n ")" ::: "memory")
; #define PG8_WAIT_L(n) asm volatile("s_waitcnt lgkmcnt(" #n ")" ::: "memory")
; #define PG8_BAR __builtin_amdgcn_s_barrier()
; #define PG8_SCHED __builtin_amdgcn_sched_barrier(0)
; template <class Epi, class Sched, bool ALIGN_EPI = false, bool SP2 = false>
; __device__ __forceinline__ void gemm_phase(PG8_LAS unsigned char* lds, const Gemm g, const Sched& S, const Epi& E) {
;     ...
;             PG8_WAIT_V(8); PG8_WAIT_L(0); PG8_BAR; PG8_MMA(1, 0, At, B0); PG8_MMA(1, 1, At, B1); PG8_BAR; PG8_SCHED;
;             PG8_LDB(B0, 1, 0); PG8_LDB(B1, 1, 1); PG8_SCHED; PG8_LDA(At, 1, 0); PG8_STAGE(PG8_SA(0, 1), a2 + hstepA, voffA);
;             PG8_WAIT_V(8); PG8_WAIT_L(0); PG8_BAR; PG8_MMA(0, 0, At, B0); PG8_MMA(0, 1, At, B1); PG8_BAR; PG8_SCHED;
	v_mfma_f32_16x16x32_bf16 v[60:63], v[140:143], v[182:185], v[60:63]
	v_mfma_f32_16x16x32_bf16 v[56:59], v[158:161], v[182:185], v[56:59]
	v_mfma_f32_16x16x32_bf16 v[44:47], v[140:143], v[192:195], v[44:47]
	v_mfma_f32_16x16x32_bf16 v[40:43], v[158:161], v[192:195], v[40:43]
	v_mfma_f32_16x16x32_bf16 v[28:31], v[140:143], v[200:203], v[28:31]
	v_mfma_f32_16x16x32_bf16 v[24:27], v[158:161], v[200:203], v[24:27]
	v_mfma_f32_16x16x32_bf16 v[12:15], v[140:143], v[208:211], v[12:15]
	v_mfma_f32_16x16x32_bf16 v[8:11], v[158:161], v[208:211], v[8:11]
	v_mfma_f32_16x16x32_bf16 v[60:63], v[154:157], v[188:191], v[60:63]
	v_mfma_f32_16x16x32_bf16 v[56:59], v[162:165], v[188:191], v[56:59]
	v_mfma_f32_16x16x32_bf16 v[44:47], v[154:157], v[196:199], v[44:47]
	v_mfma_f32_16x16x32_bf16 v[40:43], v[162:165], v[196:199], v[40:43]
	v_mfma_f32_16x16x32_bf16 v[28:31], v[154:157], v[204:207], v[28:31]
	v_mfma_f32_16x16x32_bf16 v[24:27], v[162:165], v[204:207], v[24:27]
	v_mfma_f32_16x16x32_bf16 v[12:15], v[154:157], v[212:215], v[12:15]
	v_mfma_f32_16x16x32_bf16 v[8:11], v[162:165], v[212:215], v[8:11]
	v_mfma_f32_16x16x32_bf16 v[52:55], v[166:169], v[182:185], v[52:55]
	v_mfma_f32_16x16x32_bf16 v[48:51], v[174:177], v[182:185], v[48:51]
	v_mfma_f32_16x16x32_bf16 v[36:39], v[166:169], v[192:195], v[36:39]
	v_mfma_f32_16x16x32_bf16 v[32:35], v[174:177], v[192:195], v[32:35]
	v_mfma_f32_16x16x32_bf16 v[20:23], v[166:169], v[200:203], v[20:23]
	v_mfma_f32_16x16x32_bf16 v[16:19], v[174:177], v[200:203], v[16:19]
	v_mfma_f32_16x16x32_bf16 v[4:7], v[166:169], v[208:211], v[4:7]
	v_mfma_f32_16x16x32_bf16 v[0:3], v[174:177], v[208:211], v[0:3]
	v_mfma_f32_16x16x32_bf16 v[52:55], v[170:173], v[188:191], v[52:55]
	v_mfma_f32_16x16x32_bf16 v[48:51], v[178:181], v[188:191], v[48:51]
	v_mfma_f32_16x16x32_bf16 v[36:39], v[170:173], v[196:199], v[36:39]
	v_mfma_f32_16x16x32_bf16 v[32:35], v[178:181], v[196:199], v[32:35]
	v_mfma_f32_16x16x32_bf16 v[20:23], v[170:173], v[204:207], v[20:23]
	v_mfma_f32_16x16x32_bf16 v[16:19], v[178:181], v[204:207], v[16:19]
	v_mfma_f32_16x16x32_bf16 v[4:7], v[170:173], v[212:215], v[4:7]
	v_mfma_f32_16x16x32_bf16 v[0:3], v[178:181], v[212:215], v[0:3]
	s_barrier
	v_add_u32_e32 v153, s95, v147
	ds_read_b128 v[140:143], v153
	ds_read_b128 v[154:157], v153 offset:1024
	ds_read_b128 v[158:161], v153 offset:2048
	ds_read_b128 v[162:165], v153 offset:3072
	v_add_u32_e32 v153, s94, v147
	ds_read_b128 v[166:169], v153
	ds_read_b128 v[170:173], v153 offset:1024
	ds_read_b128 v[174:177], v153 offset:2048
	ds_read_b128 v[178:181], v153 offset:3072
	s_mov_b32 m0, s72
	v_lshl_add_u64 v[222:223], s[38:39], 0, v[134:135]
	ds_read_b128 v[182:185], v151 offset:32768
	ds_read_b128 v[188:191], v151 offset:33792
	ds_read_b128 v[192:195], v151 offset:34816
	ds_read_b128 v[196:199], v151 offset:35840
	ds_read_b128 v[200:203], v151 offset:36864
	ds_read_b128 v[204:207], v151 offset:37888
	ds_read_b128 v[208:211], v151 offset:38912
	ds_read_b128 v[212:215], v151 offset:39936
	global_load_lds_dwordx4 v[222:223], off
	v_lshl_add_u64 v[222:223], s[38:39], 0, v[130:131]
	s_mov_b32 m0, s73
	s_nop 0
	global_load_lds_dwordx4 v[222:223], off
	s_waitcnt vmcnt(8) lgkmcnt(0)
	s_barrier
	v_mfma_f32_16x16x32_bf16 v[124:127], v[140:143], v[182:185], v[124:127]
	v_mfma_f32_16x16x32_bf16 v[120:123], v[158:161], v[182:185], v[120:123]
	v_mfma_f32_16x16x32_bf16 v[108:111], v[140:143], v[192:195], v[108:111]
	v_mfma_f32_16x16x32_bf16 v[104:107], v[158:161], v[192:195], v[104:107]
	v_mfma_f32_16x16x32_bf16 v[92:95], v[140:143], v[200:203], v[92:95]
	v_mfma_f32_16x16x32_bf16 v[88:91], v[158:161], v[200:203], v[88:91]
	v_mfma_f32_16x16x32_bf16 v[76:79], v[140:143], v[208:211], v[76:79]
	v_mfma_f32_16x16x32_bf16 v[72:75], v[158:161], v[208:211], v[72:75]
	v_mfma_f32_16x16x32_bf16 v[124:127], v[154:157], v[188:191], v[124:127]
	v_mfma_f32_16x16x32_bf16 v[120:123], v[162:165], v[188:191], v[120:123]
	v_mfma_f32_16x16x32_bf16 v[108:111], v[154:157], v[196:199], v[108:111]
	v_mfma_f32_16x16x32_bf16 v[104:107], v[162:165], v[196:199], v[104:107]
	v_mfma_f32_16x16x32_bf16 v[92:95], v[154:157], v[204:207], v[92:95]
	v_mfma_f32_16x16x32_bf16 v[88:91], v[162:165], v[204:207], v[88:91]
	v_mfma_f32_16x16x32_bf16 v[76:79], v[154:157], v[212:215], v[76:79]
	v_mfma_f32_16x16x32_bf16 v[72:75], v[162:165], v[212:215], v[72:75]
	v_mfma_f32_16x16x32_bf16 v[116:119], v[166:169], v[182:185], v[116:119]
	v_mfma_f32_16x16x32_bf16 v[112:115], v[174:177], v[182:185], v[112:115]
	v_mfma_f32_16x16x32_bf16 v[100:103], v[166:169], v[192:195], v[100:103]
	v_mfma_f32_16x16x32_bf16 v[96:99], v[174:177], v[192:195], v[96:99]
	v_mfma_f32_16x16x32_bf16 v[84:87], v[166:169], v[200:203], v[84:87]
	v_mfma_f32_16x16x32_bf16 v[80:83], v[174:177], v[200:203], v[80:83]
	v_mfma_f32_16x16x32_bf16 v[68:71], v[166:169], v[208:211], v[68:71]
	v_mfma_f32_16x16x32_bf16 v[64:67], v[174:177], v[208:211], v[64:67]
	v_mfma_f32_16x16x32_bf16 v[116:119], v[170:173], v[188:191], v[116:119]
	v_mfma_f32_16x16x32_bf16 v[112:115], v[178:181], v[188:191], v[112:115]
	v_mfma_f32_16x16x32_bf16 v[100:103], v[170:173], v[196:199], v[100:103]
	v_mfma_f32_16x16x32_bf16 v[96:99], v[178:181], v[196:199], v[96:99]
	v_mfma_f32_16x16x32_bf16 v[84:87], v[170:173], v[204:207], v[84:87]
	v_mfma_f32_16x16x32_bf16 v[80:83], v[178:181], v[204:207], v[80:83]
	v_mfma_f32_16x16x32_bf16 v[68:71], v[170:173], v[212:215], v[68:71]
	v_mfma_f32_16x16x32_bf16 v[64:67], v[178:181], v[212:215], v[64:67]
	s_barrier
; #define PG8_STAGE(bufoff, gbase, voff) do { _Pragma("unroll") for (int _i = 0; _i < 2; ++_i) \
;         __builtin_amdgcn_global_load_lds((const unsigned*)((const char*)(gbase) + (voff)[_i]), (PG8_LAS unsigned*)(lds + (bufoff) + ldsw + _i * 8192), 16, 0, 0); } while (0)
; #define PG8_LDA(dst, b, h) do { _Pragma("unroll") for (int m = 0; m < 4; ++m) _Pragma("unroll") for (int k = 0; k < 2; ++k) dst[m][k] = *(const PG8_LAS bf16x8*)(lds + PG8_SA(b, h) + aoff + m * 2048 + k * 1024); } while (0)
; #define PG8_MMA(ai, bj, At, Bt) do { __builtin_amdgcn_s_setprio(1); _Pragma("unroll") for (int m = 0; m < 4; ++m) _Pragma("unroll") for (int n = 0; n < 2; ++n) _Pragma("unroll") for (int k = 0; k < 2; ++k) \
;         acc[ai][bj][m][n] = __builtin_amdgcn_mfma_f32_16x16x32_bf16(Bt[n][k], At[m][k], acc[ai][bj][m][n], 0, 0, 0); __builtin_amdgcn_s_setprio(0); } while (0)
; #define PG8_WAIT_V(n) asm volatile("s_waitcnt vmcnt(" #n ")" ::: "memory")
; #define PG8_WAIT_L(n) asm volatile("s_waitcnt lgkmcnt(" #n ")" ::: "memory")
; #define PG8_BAR __builtin_amdgcn_s_barrier()
; #define PG8_SCHED __builtin_amdgcn_sched_barrier(0)
; template <class Epi, class Sched, bool ALIGN_EPI = false, bool SP2 = false>
; __device__ __forceinline__ void gemm_phase(PG8_LAS unsigned char* lds, const Gemm g, const Sched& S, const Epi& E) {
;     ...
;             PG8_LDA(At, 1, 1); PG8_STAGE(PG8_SB(1, 0), b3, voffB); PG8_STAGE(PG8_SB(1, 1), b3 + hstepB, voffB); PG8_STAGE(PG8_SA(1, 0), a3, voffA);
;             PG8_WAIT_V(8); PG8_WAIT_L(0); PG8_BAR; PG8_MMA(1, 0, At, B0); PG8_MMA(1, 1, At, B1); PG8_BAR; PG8_SCHED;
	s_mov_b32 m0, s93
	v_lshl_add_u64 v[144:145], v[144:145], 0, s[12:13]
	ds_read_b128 v[182:185], v151 offset:49152
	ds_read_b128 v[188:191], v151 offset:50176
	ds_read_b128 v[192:195], v151 offset:51200
	ds_read_b128 v[196:199], v151 offset:52224
	ds_read_b128 v[200:203], v151 offset:53248
	ds_read_b128 v[204:207], v151 offset:54272
	ds_read_b128 v[208:211], v151 offset:55296
	ds_read_b128 v[212:215], v151 offset:56320
	global_load_lds_dwordx4 v[144:145], off
	v_lshl_add_u64 v[144:145], v[216:217], 0, s[12:13]
	s_mov_b32 m0, s91
	s_nop 0
	global_load_lds_dwordx4 v[144:145], off
	v_lshl_add_u64 v[144:145], s[36:37], 0, v[132:133]
	s_mov_b32 m0, s92
	s_nop 0
	global_load_lds_dwordx4 v[144:145], off
	v_lshl_add_u64 v[144:145], s[36:37], 0, v[128:129]
	s_mov_b32 m0, s90
	s_nop 0
	global_load_lds_dwordx4 v[144:145], off
	v_lshl_add_u64 v[144:145], v[218:219], 0, s[12:13]
	s_mov_b32 m0, s75
	s_nop 0
	global_load_lds_dwordx4 v[144:145], off
	v_lshl_add_u64 v[144:145], v[220:221], 0, s[12:13]
	s_mov_b32 m0, s76
	s_nop 0
	global_load_lds_dwordx4 v[144:145], off
	s_waitcnt vmcnt(8) lgkmcnt(0)
	s_barrier
	v_mfma_f32_16x16x32_bf16 v[60:63], v[140:143], v[182:185], v[60:63]
	v_mfma_f32_16x16x32_bf16 v[56:59], v[158:161], v[182:185], v[56:59]
	v_mfma_f32_16x16x32_bf16 v[44:47], v[140:143], v[192:195], v[44:47]
	v_mfma_f32_16x16x32_bf16 v[40:43], v[158:161], v[192:195], v[40:43]
	v_mfma_f32_16x16x32_bf16 v[28:31], v[140:143], v[200:203], v[28:31]
	v_mfma_f32_16x16x32_bf16 v[24:27], v[158:161], v[200:203], v[24:27]
	v_mfma_f32_16x16x32_bf16 v[12:15], v[140:143], v[208:211], v[12:15]
	v_mfma_f32_16x16x32_bf16 v[8:11], v[158:161], v[208:211], v[8:11]
	v_mfma_f32_16x16x32_bf16 v[60:63], v[154:157], v[188:191], v[60:63]
	v_mfma_f32_16x16x32_bf16 v[56:59], v[162:165], v[188:191], v[56:59]
	v_mfma_f32_16x16x32_bf16 v[44:47], v[154:157], v[196:199], v[44:47]
	v_mfma_f32_16x16x32_bf16 v[40:43], v[162:165], v[196:199], v[40:43]
	v_mfma_f32_16x16x32_bf16 v[28:31], v[154:157], v[204:207], v[28:31]
	v_mfma_f32_16x16x32_bf16 v[24:27], v[162:165], v[204:207], v[24:27]
	v_mfma_f32_16x16x32_bf16 v[12:15], v[154:157], v[212:215], v[12:15]
	v_mfma_f32_16x16x32_bf16 v[8:11], v[162:165], v[212:215], v[8:11]
	v_mfma_f32_16x16x32_bf16 v[52:55], v[166:169], v[182:185], v[52:55]
	v_mfma_f32_16x16x32_bf16 v[48:51], v[174:177], v[182:185], v[48:51]
	v_mfma_f32_16x16x32_bf16 v[36:39], v[166:169], v[192:195], v[36:39]
	v_mfma_f32_16x16x32_bf16 v[32:35], v[174:177], v[192:195], v[32:35]
	v_mfma_f32_16x16x32_bf16 v[20:23], v[166:169], v[200:203], v[20:23]
	v_mfma_f32_16x16x32_bf16 v[16:19], v[174:177], v[200:203], v[16:19]
	v_mfma_f32_16x16x32_bf16 v[4:7], v[166:169], v[208:211], v[4:7]
	v_mfma_f32_16x16x32_bf16 v[0:3], v[174:177], v[208:211], v[0:3]
	v_mfma_f32_16x16x32_bf16 v[52:55], v[170:173], v[188:191], v[52:55]
	v_mfma_f32_16x16x32_bf16 v[48:51], v[178:181], v[188:191], v[48:51]
	v_mfma_f32_16x16x32_bf16 v[36:39], v[170:173], v[196:199], v[36:39]
	v_mfma_f32_16x16x32_bf16 v[32:35], v[178:181], v[196:199], v[32:35]
	v_mfma_f32_16x16x32_bf16 v[20:23], v[170:173], v[204:207], v[20:23]
	v_mfma_f32_16x16x32_bf16 v[16:19], v[178:181], v[204:207], v[16:19]
	v_mfma_f32_16x16x32_bf16 v[4:7], v[170:173], v[212:215], v[4:7]
	v_mfma_f32_16x16x32_bf16 v[0:3], v[178:181], v[212:215], v[0:3]
	s_barrier
	s_movk_i32 s38, 0x100
	s_andn2_b64 vcc, exec, s[8:9]
	s_mov_b64 s[36:37], -1
	s_mov_b64 s[8:9], 0
	s_cbranch_vccz .LBB0_542
	s_and_b64 vcc, exec, s[14:15]
	s_cbranch_vccz .LBB0_545
	s_barrier

; #define PG8_STAGE(bufoff, gbase, voff) do { _Pragma("unroll") for (int _i = 0; _i < 2; ++_i) \
;         __builtin_amdgcn_global_load_lds((const unsigned*)((const char*)(gbase) + (voff)[_i]), (PG8_LAS unsigned*)(lds + (bufoff) + ldsw + _i * 8192), 16, 0, 0); } while (0)
; #define PG8_LDA(dst, b, h) do { _Pragma("unroll") for (int m = 0; m < 4; ++m) _Pragma("unroll") for (int k = 0; k < 2; ++k) dst[m][k] = *(const PG8_LAS bf16x8*)(lds + PG8_SA(b, h) + aoff + m * 2048 + k * 1024); } while (0)
; #define PG8_LDB(dst, b, h) do { _Pragma("unroll") for (int n = 0; n < 2; ++n) _Pragma("unroll") for (int k = 0; k < 2; ++k) dst[n][k] = *(const PG8_LAS bf16x8*)(lds + PG8_SB(b, h) + boff + n * 2048 + k * 1024); } while (0)
; #define PG8_MMA(ai, bj, At, Bt) do { __builtin_amdgcn_s_setprio(1); _Pragma("unroll") for (int m = 0; m < 4; ++m) _Pragma("unroll") for (int n = 0; n < 2; ++n) _Pragma("unroll") for (int k = 0; k < 2; ++k) \
;         acc[ai][bj][m][n] = __builtin_amdgcn_mfma_f32_16x16x32_bf16(Bt[n][k], At[m][k], acc[ai][bj][m][n], 0, 0, 0); __builtin_amdgcn_s_setprio(0); } while (0)
; #define PG8_WAIT_V(n) asm volatile("s_waitcnt vmcnt(" #n ")" ::: "memory")
; #define PG8_WAIT_L(n) asm volatile("s_waitcnt lgkmcnt(" #n ")" ::: "memory")
; #define PG8_BAR __builtin_amdgcn_s_barrier()
; template <class Epi, class Sched, bool ALIGN_EPI = false, bool SP2 = false>
; __device__ __forceinline__ void gemm_phase(PG8_LAS unsigned char* lds, const Gemm g, const Sched& S, const Epi& E) {
;     ...
;             const char* a1 = cA + (size_t)(t + 1) * kstep;
;             const char* a2 = last ? nA : cA + (size_t)(t + 2) * kstep; const char* b2 = last ? nB : cB + (size_t)(t + 2) * kstep;
;             const char* a3 = a2 + kstep; const char* b3 = b2 + kstep;
;             if (last && has_next) S.a_ready(nxt);
;             if constexpr (SP2) {
;             PG8_LDB(B0, 0, 0); PG8_LDB(B1, 0, 1); PG8_SCHED; PG8_LDA(At, 0, 0); PG8_STAGE(PG8_SA(1, 1), a1 + hstepA, voffA);
;             PG8_WAIT_V(8); PG8_WAIT_L(0); PG8_BAR; PG8_MMA(0, 0, At, B0); PG8_MMA(0, 1, At, B1); PG8_BAR; PG8_SCHED;
;             PG8_LDA(At, 0, 1); PG8_STAGE(PG8_SB(0, 0), b2, voffB); PG8_STAGE(PG8_SB(0, 1), b2 + hstepB, voffB); PG8_STAGE(PG8_SA(0, 0), a2, voffA);
;             PG8_WAIT_V(8); PG8_WAIT_L(0); PG8_BAR; PG8_MMA(1, 0, At, B0); PG8_MMA(1, 1, At, B1); PG8_BAR; PG8_SCHED;
.LBB0_971:
	ds_read_b128 v[128:131], v191
	ds_read_b128 v[132:135], v191 offset:1024
	ds_read_b128 v[136:139], v191 offset:2048
	ds_read_b128 v[140:143], v191 offset:3072
	ds_read_b128 v[144:147], v192
	ds_read_b128 v[148:151], v192 offset:1024
	ds_read_b128 v[168:171], v192 offset:2048
	ds_read_b128 v[172:175], v192 offset:3072
	s_add_u32 s34, s30, 0xfffc0080
	s_addc_u32 s35, s31, -1
	s_cmp_eq_u32 s74, 12
	s_cselect_b32 s37, s21, s35
	s_cselect_b32 s36, s27, s34
	s_cselect_b32 s35, s19, s73
	s_cselect_b32 s34, s68, s69
	v_lshl_add_u64 v[184:185], s[30:31], 0, v[160:161]
	s_add_i32 m0, s29, 0xc000
	ds_read_b128 v[176:179], v193
	ds_read_b128 v[180:183], v193 offset:1024
	ds_read_b128 v[196:199], v193 offset:2048
	ds_read_b128 v[200:203], v193 offset:3072
	ds_read_b128 v[204:207], v193 offset:4096
	ds_read_b128 v[208:211], v193 offset:5120
	ds_read_b128 v[212:215], v193 offset:6144
	ds_read_b128 v[216:219], v193 offset:7168
	global_load_lds_dwordx4 v[184:185], off
	v_lshl_add_u64 v[184:185], s[30:31], 0, v[162:163]
	s_add_i32 m0, s29, 0xe000
	s_nop 0
	global_load_lds_dwordx4 v[184:185], off
	s_waitcnt vmcnt(8) lgkmcnt(0)
	s_barrier
	v_mfma_f32_16x16x32_bf16 v[124:127], v[128:131], v[176:179], v[124:127]
	v_mfma_f32_16x16x32_bf16 v[120:123], v[136:139], v[176:179], v[120:123]
	v_mfma_f32_16x16x32_bf16 v[108:111], v[128:131], v[196:199], v[108:111]
	v_mfma_f32_16x16x32_bf16 v[104:107], v[136:139], v[196:199], v[104:107]
	v_mfma_f32_16x16x32_bf16 v[92:95], v[128:131], v[204:207], v[92:95]
	v_mfma_f32_16x16x32_bf16 v[88:91], v[136:139], v[204:207], v[88:91]
	v_mfma_f32_16x16x32_bf16 v[76:79], v[128:131], v[212:215], v[76:79]
	v_mfma_f32_16x16x32_bf16 v[72:75], v[136:139], v[212:215], v[72:75]
	v_mfma_f32_16x16x32_bf16 v[124:127], v[132:135], v[180:183], v[124:127]
	v_mfma_f32_16x16x32_bf16 v[120:123], v[140:143], v[180:183], v[120:123]
	v_mfma_f32_16x16x32_bf16 v[108:111], v[132:135], v[200:203], v[108:111]
	v_mfma_f32_16x16x32_bf16 v[104:107], v[140:143], v[200:203], v[104:107]
	v_mfma_f32_16x16x32_bf16 v[92:95], v[132:135], v[208:211], v[92:95]
	v_mfma_f32_16x16x32_bf16 v[88:91], v[140:143], v[208:211], v[88:91]
	v_mfma_f32_16x16x32_bf16 v[76:79], v[132:135], v[216:219], v[76:79]
	v_mfma_f32_16x16x32_bf16 v[72:75], v[140:143], v[216:219], v[72:75]
	v_mfma_f32_16x16x32_bf16 v[116:119], v[144:147], v[176:179], v[116:119]
	v_mfma_f32_16x16x32_bf16 v[112:115], v[168:171], v[176:179], v[112:115]
	v_mfma_f32_16x16x32_bf16 v[100:103], v[144:147], v[196:199], v[100:103]
	v_mfma_f32_16x16x32_bf16 v[96:99], v[168:171], v[196:199], v[96:99]
	v_mfma_f32_16x16x32_bf16 v[84:87], v[144:147], v[204:207], v[84:87]
	v_mfma_f32_16x16x32_bf16 v[80:83], v[168:171], v[204:207], v[80:83]
	v_mfma_f32_16x16x32_bf16 v[68:71], v[144:147], v[212:215], v[68:71]
	v_mfma_f32_16x16x32_bf16 v[64:67], v[168:171], v[212:215], v[64:67]
	v_mfma_f32_16x16x32_bf16 v[116:119], v[148:151], v[180:183], v[116:119]
	v_mfma_f32_16x16x32_bf16 v[112:115], v[172:175], v[180:183], v[112:115]
	v_mfma_f32_16x16x32_bf16 v[100:103], v[148:151], v[200:203], v[100:103]
	v_mfma_f32_16x16x32_bf16 v[96:99], v[172:175], v[200:203], v[96:99]
	v_mfma_f32_16x16x32_bf16 v[84:87], v[148:151], v[208:211], v[84:87]
	v_mfma_f32_16x16x32_bf16 v[80:83], v[172:175], v[208:211], v[80:83]
	v_mfma_f32_16x16x32_bf16 v[68:71], v[148:151], v[216:219], v[68:71]
	v_mfma_f32_16x16x32_bf16 v[64:67], v[172:175], v[216:219], v[64:67]
	s_barrier
	s_add_i32 s58, s49, s39
	v_lshl_add_u64 v[184:185], s[34:35], 0, v[154:155]
	s_mov_b32 m0, s58
	ds_read_b128 v[176:179], v193 offset:16384
	ds_read_b128 v[180:183], v193 offset:17408
	ds_read_b128 v[196:199], v193 offset:18432
	ds_read_b128 v[200:203], v193 offset:19456
	ds_read_b128 v[204:207], v193 offset:20480
	ds_read_b128 v[208:211], v193 offset:21504
	ds_read_b128 v[212:215], v193 offset:22528
	ds_read_b128 v[216:219], v193 offset:23552
	global_load_lds_dwordx4 v[184:185], off
	s_add_i32 m0, s58, 0x2000
	s_add_u32 s58, s34, 0x40000
	v_lshl_add_u64 v[220:221], s[34:35], 0, v[158:159]
	s_addc_u32 s59, s35, 0
	s_add_i32 s75, s66, s39
	global_load_lds_dwordx4 v[220:221], off
	v_lshl_add_u64 v[222:223], s[58:59], 0, v[154:155]
	s_mov_b32 m0, s75
	v_lshl_add_u64 v[224:225], s[36:37], 0, v[156:157]
	global_load_lds_dwordx4 v[222:223], off
	v_lshl_add_u64 v[222:223], s[58:59], 0, v[158:159]
	s_add_i32 m0, s75, 0x2000
	s_nop 0
	global_load_lds_dwordx4 v[222:223], off
	v_lshl_add_u64 v[222:223], s[36:37], 0, v[152:153]
	s_mov_b32 m0, s29
	s_nop 0
	global_load_lds_dwordx4 v[222:223], off
	s_mov_b32 m0, s40
	s_nop 0
	global_load_lds_dwordx4 v[224:225], off
	s_waitcnt vmcnt(8) lgkmcnt(0)
	s_barrier
; #define PG8_STAGE(bufoff, gbase, voff) do { _Pragma("unroll") for (int _i = 0; _i < 2; ++_i) \
;         __builtin_amdgcn_global_load_lds((const unsigned*)((const char*)(gbase) + (voff)[_i]), (PG8_LAS unsigned*)(lds + (bufoff) + ldsw + _i * 8192), 16, 0, 0); } while (0)
; #define PG8_LDA(dst, b, h) do { _Pragma("unroll") for (int m = 0; m < 4; ++m) _Pragma("unroll") for (int k = 0; k < 2; ++k) dst[m][k] = *(const PG8_LAS bf16x8*)(lds + PG8_SA(b, h) + aoff + m * 2048 + k * 1024); } while (0)
; #define PG8_LDB(dst, b, h) do { _Pragma("unroll") for (int n = 0; n < 2; ++n) _Pragma("unroll") for (int k = 0; k < 2; ++k) dst[n][k] = *(const PG8_LAS bf16x8*)(lds + PG8_SB(b, h) + boff + n * 2048 + k * 1024); } while (0)
; #define PG8_MMA(ai, bj, At, Bt) do { __builtin_amdgcn_s_setprio(1); _Pragma("unroll") for (int m = 0; m < 4; ++m) _Pragma("unroll") for (int n = 0; n < 2; ++n) _Pragma("unroll") for (int k = 0; k < 2; ++k) \
;         acc[ai][bj][m][n] = __builtin_amdgcn_mfma_f32_16x16x32_bf16(Bt[n][k], At[m][k], acc[ai][bj][m][n], 0, 0, 0); __builtin_amdgcn_s_setprio(0); } while (0)
; #define PG8_WAIT_V(n) asm volatile("s_waitcnt vmcnt(" #n ")" ::: "memory")
; #define PG8_WAIT_L(n) asm volatile("s_waitcnt lgkmcnt(" #n ")" ::: "memory")
; #define PG8_BAR __builtin_amdgcn_s_barrier()
; #define PG8_SCHED __builtin_amdgcn_sched_barrier(0)
; template <class Epi, class Sched, bool ALIGN_EPI = false, bool SP2 = false>
; __device__ __forceinline__ void gemm_phase(PG8_LAS unsigned char* lds, const Gemm g, const Sched& S, const Epi& E) {
;     ...
;             PG8_WAIT_V(8); PG8_WAIT_L(0); PG8_BAR; PG8_MMA(1, 0, At, B0); PG8_MMA(1, 1, At, B1); PG8_BAR; PG8_SCHED;
;             PG8_LDB(B0, 1, 0); PG8_LDB(B1, 1, 1); PG8_SCHED; PG8_LDA(At, 1, 0); PG8_STAGE(PG8_SA(0, 1), a2 + hstepA, voffA);
;             PG8_WAIT_V(8); PG8_WAIT_L(0); PG8_BAR; PG8_MMA(0, 0, At, B0); PG8_MMA(0, 1, At, B1); PG8_BAR; PG8_SCHED;
	v_mfma_f32_16x16x32_bf16 v[60:63], v[128:131], v[176:179], v[60:63]
	v_mfma_f32_16x16x32_bf16 v[56:59], v[136:139], v[176:179], v[56:59]
	v_mfma_f32_16x16x32_bf16 v[44:47], v[128:131], v[196:199], v[44:47]
	v_mfma_f32_16x16x32_bf16 v[40:43], v[136:139], v[196:199], v[40:43]
	v_mfma_f32_16x16x32_bf16 v[28:31], v[128:131], v[204:207], v[28:31]
	v_mfma_f32_16x16x32_bf16 v[24:27], v[136:139], v[204:207], v[24:27]
	v_mfma_f32_16x16x32_bf16 v[12:15], v[128:131], v[212:215], v[12:15]
	v_mfma_f32_16x16x32_bf16 v[8:11], v[136:139], v[212:215], v[8:11]
	v_mfma_f32_16x16x32_bf16 v[60:63], v[132:135], v[180:183], v[60:63]
	v_mfma_f32_16x16x32_bf16 v[56:59], v[140:143], v[180:183], v[56:59]
	v_mfma_f32_16x16x32_bf16 v[44:47], v[132:135], v[200:203], v[44:47]
	v_mfma_f32_16x16x32_bf16 v[40:43], v[140:143], v[200:203], v[40:43]
	v_mfma_f32_16x16x32_bf16 v[28:31], v[132:135], v[208:211], v[28:31]
	v_mfma_f32_16x16x32_bf16 v[24:27], v[140:143], v[208:211], v[24:27]
	v_mfma_f32_16x16x32_bf16 v[12:15], v[132:135], v[216:219], v[12:15]
	v_mfma_f32_16x16x32_bf16 v[8:11], v[140:143], v[216:219], v[8:11]
	v_mfma_f32_16x16x32_bf16 v[52:55], v[144:147], v[176:179], v[52:55]
	v_mfma_f32_16x16x32_bf16 v[48:51], v[168:171], v[176:179], v[48:51]
	v_mfma_f32_16x16x32_bf16 v[36:39], v[144:147], v[196:199], v[36:39]
	v_mfma_f32_16x16x32_bf16 v[32:35], v[168:171], v[196:199], v[32:35]
	v_mfma_f32_16x16x32_bf16 v[20:23], v[144:147], v[204:207], v[20:23]
	v_mfma_f32_16x16x32_bf16 v[16:19], v[168:171], v[204:207], v[16:19]
	v_mfma_f32_16x16x32_bf16 v[4:7], v[144:147], v[212:215], v[4:7]
	v_mfma_f32_16x16x32_bf16 v[0:3], v[168:171], v[212:215], v[0:3]
	v_mfma_f32_16x16x32_bf16 v[52:55], v[148:151], v[180:183], v[52:55]
	v_mfma_f32_16x16x32_bf16 v[48:51], v[172:175], v[180:183], v[48:51]
	v_mfma_f32_16x16x32_bf16 v[36:39], v[148:151], v[200:203], v[36:39]
	v_mfma_f32_16x16x32_bf16 v[32:35], v[172:175], v[200:203], v[32:35]
	v_mfma_f32_16x16x32_bf16 v[20:23], v[148:151], v[208:211], v[20:23]
	v_mfma_f32_16x16x32_bf16 v[16:19], v[172:175], v[208:211], v[16:19]
	v_mfma_f32_16x16x32_bf16 v[4:7], v[148:151], v[216:219], v[4:7]
	v_mfma_f32_16x16x32_bf16 v[0:3], v[172:175], v[216:219], v[0:3]
	s_barrier
	s_add_i32 s58, 0, 0x18000
	s_add_i32 s59, 0, 0x1c000
	v_add_u32_e32 v140, s58, v189
	v_add_u32_e32 v172, s59, v189
	ds_read_b128 v[128:131], v140
	ds_read_b128 v[132:135], v140 offset:1024
	ds_read_b128 v[136:139], v140 offset:2048
	ds_read_b128 v[140:143], v140 offset:3072
	ds_read_b128 v[144:147], v172
	ds_read_b128 v[148:151], v172 offset:1024
	ds_read_b128 v[168:171], v172 offset:2048
	ds_read_b128 v[172:175], v172 offset:3072
	s_add_u32 s36, s36, 0x40000
	s_addc_u32 s37, s37, 0
	s_mov_b32 m0, s41
	v_lshl_add_u64 v[226:227], s[36:37], 0, v[152:153]
	ds_read_b128 v[176:179], v193 offset:32768
	ds_read_b128 v[180:183], v193 offset:33792
	ds_read_b128 v[196:199], v193 offset:34816
	ds_read_b128 v[200:203], v193 offset:35840
	ds_read_b128 v[204:207], v193 offset:36864
	ds_read_b128 v[208:211], v193 offset:37888
	ds_read_b128 v[212:215], v193 offset:38912
	ds_read_b128 v[216:219], v193 offset:39936
	global_load_lds_dwordx4 v[226:227], off
	v_lshl_add_u64 v[226:227], s[36:37], 0, v[156:157]
	s_mov_b32 m0, s42
	s_nop 0
	global_load_lds_dwordx4 v[226:227], off
	s_waitcnt vmcnt(8) lgkmcnt(0)
	s_barrier
	v_mfma_f32_16x16x32_bf16 v[124:127], v[128:131], v[176:179], v[124:127]
	v_mfma_f32_16x16x32_bf16 v[120:123], v[136:139], v[176:179], v[120:123]
	v_mfma_f32_16x16x32_bf16 v[108:111], v[128:131], v[196:199], v[108:111]
	v_mfma_f32_16x16x32_bf16 v[104:107], v[136:139], v[196:199], v[104:107]
	v_mfma_f32_16x16x32_bf16 v[92:95], v[128:131], v[204:207], v[92:95]
	v_mfma_f32_16x16x32_bf16 v[88:91], v[136:139], v[204:207], v[88:91]
	v_mfma_f32_16x16x32_bf16 v[76:79], v[128:131], v[212:215], v[76:79]
	v_mfma_f32_16x16x32_bf16 v[72:75], v[136:139], v[212:215], v[72:75]
	v_mfma_f32_16x16x32_bf16 v[124:127], v[132:135], v[180:183], v[124:127]
	v_mfma_f32_16x16x32_bf16 v[120:123], v[140:143], v[180:183], v[120:123]
	v_mfma_f32_16x16x32_bf16 v[108:111], v[132:135], v[200:203], v[108:111]
	v_mfma_f32_16x16x32_bf16 v[104:107], v[140:143], v[200:203], v[104:107]
	v_mfma_f32_16x16x32_bf16 v[92:95], v[132:135], v[208:211], v[92:95]
	v_mfma_f32_16x16x32_bf16 v[88:91], v[140:143], v[208:211], v[88:91]
	v_mfma_f32_16x16x32_bf16 v[76:79], v[132:135], v[216:219], v[76:79]
	v_mfma_f32_16x16x32_bf16 v[72:75], v[140:143], v[216:219], v[72:75]
	v_mfma_f32_16x16x32_bf16 v[116:119], v[144:147], v[176:179], v[116:119]
	v_mfma_f32_16x16x32_bf16 v[112:115], v[168:171], v[176:179], v[112:115]
	v_mfma_f32_16x16x32_bf16 v[100:103], v[144:147], v[196:199], v[100:103]
	v_mfma_f32_16x16x32_bf16 v[96:99], v[168:171], v[196:199], v[96:99]
	v_mfma_f32_16x16x32_bf16 v[84:87], v[144:147], v[204:207], v[84:87]
	v_mfma_f32_16x16x32_bf16 v[80:83], v[168:171], v[204:207], v[80:83]
	v_mfma_f32_16x16x32_bf16 v[68:71], v[144:147], v[212:215], v[68:71]
	v_mfma_f32_16x16x32_bf16 v[64:67], v[168:171], v[212:215], v[64:67]
	v_mfma_f32_16x16x32_bf16 v[116:119], v[148:151], v[180:183], v[116:119]
	v_mfma_f32_16x16x32_bf16 v[112:115], v[172:175], v[180:183], v[112:115]
	v_mfma_f32_16x16x32_bf16 v[100:103], v[148:151], v[200:203], v[100:103]
	v_mfma_f32_16x16x32_bf16 v[96:99], v[172:175], v[200:203], v[96:99]
	v_mfma_f32_16x16x32_bf16 v[84:87], v[148:151], v[208:211], v[84:87]
	v_mfma_f32_16x16x32_bf16 v[80:83], v[172:175], v[208:211], v[80:83]
	v_mfma_f32_16x16x32_bf16 v[68:71], v[148:151], v[216:219], v[68:71]
	v_mfma_f32_16x16x32_bf16 v[64:67], v[172:175], v[216:219], v[64:67]
	s_barrier
; #define PG8_STAGE(bufoff, gbase, voff) do { _Pragma("unroll") for (int _i = 0; _i < 2; ++_i) \
;         __builtin_amdgcn_global_load_lds((const unsigned*)((const char*)(gbase) + (voff)[_i]), (PG8_LAS unsigned*)(lds + (bufoff) + ldsw + _i * 8192), 16, 0, 0); } while (0)
; #define PG8_LDA(dst, b, h) do { _Pragma("unroll") for (int m = 0; m < 4; ++m) _Pragma("unroll") for (int k = 0; k < 2; ++k) dst[m][k] = *(const PG8_LAS bf16x8*)(lds + PG8_SA(b, h) + aoff + m * 2048 + k * 1024); } while (0)
; #define PG8_MMA(ai, bj, At, Bt) do { __builtin_amdgcn_s_setprio(1); _Pragma("unroll") for (int m = 0; m < 4; ++m) _Pragma("unroll") for (int n = 0; n < 2; ++n) _Pragma("unroll") for (int k = 0; k < 2; ++k) \
;         acc[ai][bj][m][n] = __builtin_amdgcn_mfma_f32_16x16x32_bf16(Bt[n][k], At[m][k], acc[ai][bj][m][n], 0, 0, 0); __builtin_amdgcn_s_setprio(0); } while (0)
; #define PG8_WAIT_V(n) asm volatile("s_waitcnt vmcnt(" #n ")" ::: "memory")
; #define PG8_WAIT_L(n) asm volatile("s_waitcnt lgkmcnt(" #n ")" ::: "memory")
; #define PG8_BAR __builtin_amdgcn_s_barrier()
; #define PG8_SCHED __builtin_amdgcn_sched_barrier(0)
; template <class Epi, class Sched, bool ALIGN_EPI = false, bool SP2 = false>
; __device__ __forceinline__ void gemm_phase(PG8_LAS unsigned char* lds, const Gemm g, const Sched& S, const Epi& E) {
;     ...
;             PG8_LDA(At, 1, 1); PG8_STAGE(PG8_SB(1, 0), b3, voffB); PG8_STAGE(PG8_SB(1, 1), b3 + hstepB, voffB); PG8_STAGE(PG8_SA(1, 0), a3, voffA);
;             PG8_WAIT_V(8); PG8_WAIT_L(0); PG8_BAR; PG8_MMA(1, 0, At, B0); PG8_MMA(1, 1, At, B1); PG8_BAR; PG8_SCHED;
	s_add_i32 s36, s58, s39
	v_lshl_add_u64 v[184:185], v[184:185], 0, s[14:15]
	s_mov_b32 m0, s36
	ds_read_b128 v[176:179], v193 offset:49152
	ds_read_b128 v[180:183], v193 offset:50176
	ds_read_b128 v[196:199], v193 offset:51200
	ds_read_b128 v[200:203], v193 offset:52224
	ds_read_b128 v[204:207], v193 offset:53248
	ds_read_b128 v[208:211], v193 offset:54272
	ds_read_b128 v[212:215], v193 offset:55296
	ds_read_b128 v[216:219], v193 offset:56320
	global_load_lds_dwordx4 v[184:185], off
	s_add_i32 m0, s36, 0x2000
	s_add_u32 s34, s34, 0x40080
	v_lshl_add_u64 v[184:185], v[220:221], 0, s[14:15]
	s_addc_u32 s35, s35, 0
	s_add_i32 s36, s59, s39
	global_load_lds_dwordx4 v[184:185], off
	v_lshl_add_u64 v[184:185], s[34:35], 0, v[154:155]
	s_mov_b32 m0, s36
	s_nop 0
	global_load_lds_dwordx4 v[184:185], off
	v_lshl_add_u64 v[184:185], s[34:35], 0, v[158:159]
	s_add_i32 m0, s36, 0x2000
	s_nop 0
	global_load_lds_dwordx4 v[184:185], off
	v_lshl_add_u64 v[184:185], v[222:223], 0, s[14:15]
	s_mov_b32 m0, s44
	s_nop 0
	global_load_lds_dwordx4 v[184:185], off
	v_lshl_add_u64 v[184:185], v[224:225], 0, s[14:15]
	s_mov_b32 m0, s45
	s_nop 0
	global_load_lds_dwordx4 v[184:185], off
	s_waitcnt vmcnt(8) lgkmcnt(0)
	s_barrier
	v_mfma_f32_16x16x32_bf16 v[60:63], v[128:131], v[176:179], v[60:63]
	v_mfma_f32_16x16x32_bf16 v[56:59], v[136:139], v[176:179], v[56:59]
	v_mfma_f32_16x16x32_bf16 v[44:47], v[128:131], v[196:199], v[44:47]
	v_mfma_f32_16x16x32_bf16 v[40:43], v[136:139], v[196:199], v[40:43]
	v_mfma_f32_16x16x32_bf16 v[28:31], v[128:131], v[204:207], v[28:31]
	v_mfma_f32_16x16x32_bf16 v[24:27], v[136:139], v[204:207], v[24:27]
	v_mfma_f32_16x16x32_bf16 v[12:15], v[128:131], v[212:215], v[12:15]
	v_mfma_f32_16x16x32_bf16 v[8:11], v[136:139], v[212:215], v[8:11]
	v_mfma_f32_16x16x32_bf16 v[60:63], v[132:135], v[180:183], v[60:63]
	v_mfma_f32_16x16x32_bf16 v[56:59], v[140:143], v[180:183], v[56:59]
	v_mfma_f32_16x16x32_bf16 v[44:47], v[132:135], v[200:203], v[44:47]
	v_mfma_f32_16x16x32_bf16 v[40:43], v[140:143], v[200:203], v[40:43]
	v_mfma_f32_16x16x32_bf16 v[28:31], v[132:135], v[208:211], v[28:31]
	v_mfma_f32_16x16x32_bf16 v[24:27], v[140:143], v[208:211], v[24:27]
	v_mfma_f32_16x16x32_bf16 v[12:15], v[132:135], v[216:219], v[12:15]
	v_mfma_f32_16x16x32_bf16 v[8:11], v[140:143], v[216:219], v[8:11]
	v_mfma_f32_16x16x32_bf16 v[52:55], v[144:147], v[176:179], v[52:55]
	v_mfma_f32_16x16x32_bf16 v[48:51], v[168:171], v[176:179], v[48:51]
	v_mfma_f32_16x16x32_bf16 v[36:39], v[144:147], v[196:199], v[36:39]
	v_mfma_f32_16x16x32_bf16 v[32:35], v[168:171], v[196:199], v[32:35]
	v_mfma_f32_16x16x32_bf16 v[20:23], v[144:147], v[204:207], v[20:23]
	v_mfma_f32_16x16x32_bf16 v[16:19], v[168:171], v[204:207], v[16:19]
	v_mfma_f32_16x16x32_bf16 v[4:7], v[144:147], v[212:215], v[4:7]
	v_mfma_f32_16x16x32_bf16 v[0:3], v[168:171], v[212:215], v[0:3]
	v_mfma_f32_16x16x32_bf16 v[52:55], v[148:151], v[180:183], v[52:55]
	v_mfma_f32_16x16x32_bf16 v[48:51], v[172:175], v[180:183], v[48:51]
	v_mfma_f32_16x16x32_bf16 v[36:39], v[148:151], v[200:203], v[36:39]
	v_mfma_f32_16x16x32_bf16 v[32:35], v[172:175], v[200:203], v[32:35]
	v_mfma_f32_16x16x32_bf16 v[20:23], v[148:151], v[208:211], v[20:23]
	v_mfma_f32_16x16x32_bf16 v[16:19], v[172:175], v[208:211], v[16:19]
	v_mfma_f32_16x16x32_bf16 v[4:7], v[148:151], v[216:219], v[4:7]
	v_mfma_f32_16x16x32_bf16 v[0:3], v[172:175], v[216:219], v[0:3]
	s_barrier
	s_add_i32 s74, s74, 2
	s_add_u32 s30, s30, 0x100
	s_addc_u32 s31, s31, 0
	s_add_u32 s69, s69, 0x100
	s_addc_u32 s73, s73, 0
	s_cmp_gt_u32 s74, 13
	s_cbranch_scc0 .LBB0_971
	s_and_b64 vcc, exec, s[16:17]
	s_cbranch_vccz .LBB0_974
	s_barrier

; #define PG8_STAGE(bufoff, gbase, voff) do { _Pragma("unroll") for (int _i = 0; _i < 2; ++_i) \
;         __builtin_amdgcn_global_load_lds((const unsigned*)((const char*)(gbase) + (voff)[_i]), (PG8_LAS unsigned*)(lds + (bufoff) + ldsw + _i * 8192), 16, 0, 0); } while (0)
; #define PG8_LDA(dst, b, h) do { _Pragma("unroll") for (int m = 0; m < 4; ++m) _Pragma("unroll") for (int k = 0; k < 2; ++k) dst[m][k] = *(const PG8_LAS bf16x8*)(lds + PG8_SA(b, h) + aoff + m * 2048 + k * 1024); } while (0)
; #define PG8_LDB(dst, b, h) do { _Pragma("unroll") for (int n = 0; n < 2; ++n) _Pragma("unroll") for (int k = 0; k < 2; ++k) dst[n][k] = *(const PG8_LAS bf16x8*)(lds + PG8_SB(b, h) + boff + n * 2048 + k * 1024); } while (0)
; #define PG8_MMA(ai, bj, At, Bt) do { __builtin_amdgcn_s_setprio(1); _Pragma("unroll") for (int m = 0; m < 4; ++m) _Pragma("unroll") for (int n = 0; n < 2; ++n) _Pragma("unroll") for (int k = 0; k < 2; ++k) \
;         acc[ai][bj][m][n] = __builtin_amdgcn_mfma_f32_16x16x32_bf16(Bt[n][k], At[m][k], acc[ai][bj][m][n], 0, 0, 0); __builtin_amdgcn_s_setprio(0); } while (0)
; #define PG8_WAIT_V(n) asm volatile("s_waitcnt vmcnt(" #n ")" ::: "memory")
; #define PG8_WAIT_L(n) asm volatile("s_waitcnt lgkmcnt(" #n ")" ::: "memory")
; #define PG8_BAR __builtin_amdgcn_s_barrier()
; template <class Epi, class Sched, bool ALIGN_EPI = false, bool SP2 = false>
; __device__ __forceinline__ void gemm_phase(PG8_LAS unsigned char* lds, const Gemm g, const Sched& S, const Epi& E) {
;     ...
;             const char* a1 = cA + (size_t)(t + 1) * kstep;
;             const char* a2 = last ? nA : cA + (size_t)(t + 2) * kstep; const char* b2 = last ? nB : cB + (size_t)(t + 2) * kstep;
;             const char* a3 = a2 + kstep; const char* b3 = b2 + kstep;
;             if (last && has_next) S.a_ready(nxt);
;             if constexpr (SP2) {
;             PG8_LDB(B0, 0, 0); PG8_LDB(B1, 0, 1); PG8_SCHED; PG8_LDA(At, 0, 0); PG8_STAGE(PG8_SA(1, 1), a1 + hstepA, voffA);
;             PG8_WAIT_V(8); PG8_WAIT_L(0); PG8_BAR; PG8_MMA(0, 0, At, B0); PG8_MMA(0, 1, At, B1); PG8_BAR; PG8_SCHED;
;             PG8_LDA(At, 0, 1); PG8_STAGE(PG8_SB(0, 0), b2, voffB); PG8_STAGE(PG8_SB(0, 1), b2 + hstepB, voffB); PG8_STAGE(PG8_SA(0, 0), a2, voffA);
;             PG8_WAIT_V(8); PG8_WAIT_L(0); PG8_BAR; PG8_MMA(1, 0, At, B0); PG8_MMA(1, 1, At, B1); PG8_BAR; PG8_SCHED;
.LBB0_1055:
	ds_read_b128 v[144:147], v153
	ds_read_b128 v[158:161], v153 offset:1024
	ds_read_b128 v[162:165], v153 offset:2048
	ds_read_b128 v[166:169], v153 offset:3072
	ds_read_b128 v[170:173], v154
	ds_read_b128 v[174:177], v154 offset:1024
	ds_read_b128 v[178:181], v154 offset:2048
	ds_read_b128 v[182:185], v154 offset:3072
	s_add_u32 s28, s26, 0xfffc0080
	s_addc_u32 s29, s27, -1
	s_cmp_eq_u32 s69, 12
	s_cselect_b32 s31, s19, s29
	s_cselect_b32 s30, s49, s28
	s_cselect_b32 s29, s17, s68
	s_cselect_b32 s28, s66, s67
	v_lshl_add_u64 v[148:149], s[26:27], 0, v[136:137]
	s_add_i32 m0, s25, 0xc000
	ds_read_b128 v[188:191], v155
	ds_read_b128 v[192:195], v155 offset:1024
	ds_read_b128 v[196:199], v155 offset:2048
	ds_read_b128 v[200:203], v155 offset:3072
	ds_read_b128 v[204:207], v155 offset:4096
	ds_read_b128 v[208:211], v155 offset:5120
	ds_read_b128 v[212:215], v155 offset:6144
	ds_read_b128 v[216:219], v155 offset:7168
	global_load_lds_dwordx4 v[148:149], off
	v_lshl_add_u64 v[148:149], s[26:27], 0, v[138:139]
	s_add_i32 m0, s25, 0xe000
	s_nop 0
	global_load_lds_dwordx4 v[148:149], off
	s_waitcnt vmcnt(8) lgkmcnt(0)
	s_barrier
	v_mfma_f32_16x16x32_bf16 v[116:119], v[144:147], v[188:191], v[116:119]
	v_mfma_f32_16x16x32_bf16 v[112:115], v[162:165], v[188:191], v[112:115]
	v_mfma_f32_16x16x32_bf16 v[108:111], v[144:147], v[196:199], v[108:111]
	v_mfma_f32_16x16x32_bf16 v[100:103], v[162:165], v[196:199], v[100:103]
	v_mfma_f32_16x16x32_bf16 v[92:95], v[144:147], v[204:207], v[92:95]
	v_mfma_f32_16x16x32_bf16 v[84:87], v[162:165], v[204:207], v[84:87]
	v_mfma_f32_16x16x32_bf16 v[76:79], v[144:147], v[212:215], v[76:79]
	v_mfma_f32_16x16x32_bf16 v[68:71], v[162:165], v[212:215], v[68:71]
	v_mfma_f32_16x16x32_bf16 v[116:119], v[158:161], v[192:195], v[116:119]
	v_mfma_f32_16x16x32_bf16 v[112:115], v[166:169], v[192:195], v[112:115]
	v_mfma_f32_16x16x32_bf16 v[108:111], v[158:161], v[200:203], v[108:111]
	v_mfma_f32_16x16x32_bf16 v[100:103], v[166:169], v[200:203], v[100:103]
	v_mfma_f32_16x16x32_bf16 v[92:95], v[158:161], v[208:211], v[92:95]
	v_mfma_f32_16x16x32_bf16 v[84:87], v[166:169], v[208:211], v[84:87]
	v_mfma_f32_16x16x32_bf16 v[76:79], v[158:161], v[216:219], v[76:79]
	v_mfma_f32_16x16x32_bf16 v[68:71], v[166:169], v[216:219], v[68:71]
	v_mfma_f32_16x16x32_bf16 v[124:127], v[170:173], v[188:191], v[124:127]
	v_mfma_f32_16x16x32_bf16 v[120:123], v[178:181], v[188:191], v[120:123]
	v_mfma_f32_16x16x32_bf16 v[104:107], v[170:173], v[196:199], v[104:107]
	v_mfma_f32_16x16x32_bf16 v[96:99], v[178:181], v[196:199], v[96:99]
	v_mfma_f32_16x16x32_bf16 v[88:91], v[170:173], v[204:207], v[88:91]
	v_mfma_f32_16x16x32_bf16 v[80:83], v[178:181], v[204:207], v[80:83]
	v_mfma_f32_16x16x32_bf16 v[72:75], v[170:173], v[212:215], v[72:75]
	v_mfma_f32_16x16x32_bf16 v[64:67], v[178:181], v[212:215], v[64:67]
	v_mfma_f32_16x16x32_bf16 v[124:127], v[174:177], v[192:195], v[124:127]
	v_mfma_f32_16x16x32_bf16 v[120:123], v[182:185], v[192:195], v[120:123]
	v_mfma_f32_16x16x32_bf16 v[104:107], v[174:177], v[200:203], v[104:107]
	v_mfma_f32_16x16x32_bf16 v[96:99], v[182:185], v[200:203], v[96:99]
	v_mfma_f32_16x16x32_bf16 v[88:91], v[174:177], v[208:211], v[88:91]
	v_mfma_f32_16x16x32_bf16 v[80:83], v[182:185], v[208:211], v[80:83]
	v_mfma_f32_16x16x32_bf16 v[72:75], v[174:177], v[216:219], v[72:75]
	v_mfma_f32_16x16x32_bf16 v[64:67], v[182:185], v[216:219], v[64:67]
	s_barrier
	s_add_i32 s58, s45, s35
	v_lshl_add_u64 v[148:149], s[28:29], 0, v[132:133]
	s_mov_b32 m0, s58
	ds_read_b128 v[188:191], v155 offset:16384
	ds_read_b128 v[192:195], v155 offset:17408
	ds_read_b128 v[196:199], v155 offset:18432
	ds_read_b128 v[200:203], v155 offset:19456
	ds_read_b128 v[204:207], v155 offset:20480
	ds_read_b128 v[208:211], v155 offset:21504
	ds_read_b128 v[212:215], v155 offset:22528
	ds_read_b128 v[216:219], v155 offset:23552
	global_load_lds_dwordx4 v[148:149], off
	s_add_i32 m0, s58, 0x2000
	s_add_u32 s58, s28, 0x40000
	v_lshl_add_u64 v[220:221], s[28:29], 0, v[128:129]
	s_addc_u32 s59, s29, 0
	s_add_i32 s73, s46, s35
	global_load_lds_dwordx4 v[220:221], off
	v_lshl_add_u64 v[222:223], s[58:59], 0, v[132:133]
	s_mov_b32 m0, s73
	v_lshl_add_u64 v[224:225], s[30:31], 0, v[130:131]
	global_load_lds_dwordx4 v[222:223], off
	v_lshl_add_u64 v[222:223], s[58:59], 0, v[128:129]
	s_add_i32 m0, s73, 0x2000
	s_nop 0
	global_load_lds_dwordx4 v[222:223], off
	v_lshl_add_u64 v[222:223], s[30:31], 0, v[134:135]
	s_mov_b32 m0, s25
	s_nop 0
	global_load_lds_dwordx4 v[222:223], off
	s_mov_b32 m0, s38
	s_nop 0
	global_load_lds_dwordx4 v[224:225], off
	s_waitcnt vmcnt(8) lgkmcnt(0)
	s_barrier
; #define PG8_STAGE(bufoff, gbase, voff) do { _Pragma("unroll") for (int _i = 0; _i < 2; ++_i) \
;         __builtin_amdgcn_global_load_lds((const unsigned*)((const char*)(gbase) + (voff)[_i]), (PG8_LAS unsigned*)(lds + (bufoff) + ldsw + _i * 8192), 16, 0, 0); } while (0)
; #define PG8_LDA(dst, b, h) do { _Pragma("unroll") for (int m = 0; m < 4; ++m) _Pragma("unroll") for (int k = 0; k < 2; ++k) dst[m][k] = *(const PG8_LAS bf16x8*)(lds + PG8_SA(b, h) + aoff + m * 2048 + k * 1024); } while (0)
; #define PG8_LDB(dst, b, h) do { _Pragma("unroll") for (int n = 0; n < 2; ++n) _Pragma("unroll") for (int k = 0; k < 2; ++k) dst[n][k] = *(const PG8_LAS bf16x8*)(lds + PG8_SB(b, h) + boff + n * 2048 + k * 1024); } while (0)
; #define PG8_MMA(ai, bj, At, Bt) do { __builtin_amdgcn_s_setprio(1); _Pragma("unroll") for (int m = 0; m < 4; ++m) _Pragma("unroll") for (int n = 0; n < 2; ++n) _Pragma("unroll") for (int k = 0; k < 2; ++k) \
;         acc[ai][bj][m][n] = __builtin_amdgcn_mfma_f32_16x16x32_bf16(Bt[n][k], At[m][k], acc[ai][bj][m][n], 0, 0, 0); __builtin_amdgcn_s_setprio(0); } while (0)
; #define PG8_WAIT_V(n) asm volatile("s_waitcnt vmcnt(" #n ")" ::: "memory")
; #define PG8_WAIT_L(n) asm volatile("s_waitcnt lgkmcnt(" #n ")" ::: "memory")
; #define PG8_BAR __builtin_amdgcn_s_barrier()
; #define PG8_SCHED __builtin_amdgcn_sched_barrier(0)
; template <class Epi, class Sched, bool ALIGN_EPI = false, bool SP2 = false>
; __device__ __forceinline__ void gemm_phase(PG8_LAS unsigned char* lds, const Gemm g, const Sched& S, const Epi& E) {
;     ...
;             PG8_WAIT_V(8); PG8_WAIT_L(0); PG8_BAR; PG8_MMA(1, 0, At, B0); PG8_MMA(1, 1, At, B1); PG8_BAR; PG8_SCHED;
;             PG8_LDB(B0, 1, 0); PG8_LDB(B1, 1, 1); PG8_SCHED; PG8_LDA(At, 1, 0); PG8_STAGE(PG8_SA(0, 1), a2 + hstepA, voffA);
;             PG8_WAIT_V(8); PG8_WAIT_L(0); PG8_BAR; PG8_MMA(0, 0, At, B0); PG8_MMA(0, 1, At, B1); PG8_BAR; PG8_SCHED;
	v_mfma_f32_16x16x32_bf16 v[60:63], v[144:147], v[188:191], v[60:63]
	v_mfma_f32_16x16x32_bf16 v[52:55], v[162:165], v[188:191], v[52:55]
	v_mfma_f32_16x16x32_bf16 v[44:47], v[144:147], v[196:199], v[44:47]
	v_mfma_f32_16x16x32_bf16 v[36:39], v[162:165], v[196:199], v[36:39]
	v_mfma_f32_16x16x32_bf16 v[28:31], v[144:147], v[204:207], v[28:31]
	v_mfma_f32_16x16x32_bf16 v[20:23], v[162:165], v[204:207], v[20:23]
	v_mfma_f32_16x16x32_bf16 v[12:15], v[144:147], v[212:215], v[12:15]
	v_mfma_f32_16x16x32_bf16 v[4:7], v[162:165], v[212:215], v[4:7]
	v_mfma_f32_16x16x32_bf16 v[60:63], v[158:161], v[192:195], v[60:63]
	v_mfma_f32_16x16x32_bf16 v[52:55], v[166:169], v[192:195], v[52:55]
	v_mfma_f32_16x16x32_bf16 v[44:47], v[158:161], v[200:203], v[44:47]
	v_mfma_f32_16x16x32_bf16 v[36:39], v[166:169], v[200:203], v[36:39]
	v_mfma_f32_16x16x32_bf16 v[28:31], v[158:161], v[208:211], v[28:31]
	v_mfma_f32_16x16x32_bf16 v[20:23], v[166:169], v[208:211], v[20:23]
	v_mfma_f32_16x16x32_bf16 v[12:15], v[158:161], v[216:219], v[12:15]
	v_mfma_f32_16x16x32_bf16 v[4:7], v[166:169], v[216:219], v[4:7]
	v_mfma_f32_16x16x32_bf16 v[56:59], v[170:173], v[188:191], v[56:59]
	v_mfma_f32_16x16x32_bf16 v[48:51], v[178:181], v[188:191], v[48:51]
	v_mfma_f32_16x16x32_bf16 v[40:43], v[170:173], v[196:199], v[40:43]
	v_mfma_f32_16x16x32_bf16 v[32:35], v[178:181], v[196:199], v[32:35]
	v_mfma_f32_16x16x32_bf16 v[24:27], v[170:173], v[204:207], v[24:27]
	v_mfma_f32_16x16x32_bf16 v[16:19], v[178:181], v[204:207], v[16:19]
	v_mfma_f32_16x16x32_bf16 v[8:11], v[170:173], v[212:215], v[8:11]
	v_mfma_f32_16x16x32_bf16 v[0:3], v[178:181], v[212:215], v[0:3]
	v_mfma_f32_16x16x32_bf16 v[56:59], v[174:177], v[192:195], v[56:59]
	v_mfma_f32_16x16x32_bf16 v[48:51], v[182:185], v[192:195], v[48:51]
	v_mfma_f32_16x16x32_bf16 v[40:43], v[174:177], v[200:203], v[40:43]
	v_mfma_f32_16x16x32_bf16 v[32:35], v[182:185], v[200:203], v[32:35]
	v_mfma_f32_16x16x32_bf16 v[24:27], v[174:177], v[208:211], v[24:27]
	v_mfma_f32_16x16x32_bf16 v[16:19], v[182:185], v[208:211], v[16:19]
	v_mfma_f32_16x16x32_bf16 v[8:11], v[174:177], v[216:219], v[8:11]
	v_mfma_f32_16x16x32_bf16 v[0:3], v[182:185], v[216:219], v[0:3]
	s_barrier
	s_add_i32 s58, 0, 0x18000
	v_add_u32_e32 v157, s58, v151
	s_add_i32 s59, 0, 0x1c000
	ds_read_b128 v[144:147], v157
	ds_read_b128 v[158:161], v157 offset:1024
	ds_read_b128 v[162:165], v157 offset:2048
	ds_read_b128 v[166:169], v157 offset:3072
	v_add_u32_e32 v157, s59, v151
	ds_read_b128 v[170:173], v157
	ds_read_b128 v[174:177], v157 offset:1024
	ds_read_b128 v[178:181], v157 offset:2048
	ds_read_b128 v[182:185], v157 offset:3072
	s_add_u32 s30, s30, 0x40000
	s_addc_u32 s31, s31, 0
	s_mov_b32 m0, s39
	v_lshl_add_u64 v[226:227], s[30:31], 0, v[134:135]
	ds_read_b128 v[188:191], v155 offset:32768
	ds_read_b128 v[192:195], v155 offset:33792
	ds_read_b128 v[196:199], v155 offset:34816
	ds_read_b128 v[200:203], v155 offset:35840
	ds_read_b128 v[204:207], v155 offset:36864
	ds_read_b128 v[208:211], v155 offset:37888
	ds_read_b128 v[212:215], v155 offset:38912
	ds_read_b128 v[216:219], v155 offset:39936
	global_load_lds_dwordx4 v[226:227], off
	v_lshl_add_u64 v[226:227], s[30:31], 0, v[130:131]
	s_mov_b32 m0, s40
	s_nop 0
	global_load_lds_dwordx4 v[226:227], off
	s_waitcnt vmcnt(8) lgkmcnt(0)
	s_barrier
	v_mfma_f32_16x16x32_bf16 v[116:119], v[144:147], v[188:191], v[116:119]
	v_mfma_f32_16x16x32_bf16 v[112:115], v[162:165], v[188:191], v[112:115]
	v_mfma_f32_16x16x32_bf16 v[108:111], v[144:147], v[196:199], v[108:111]
	v_mfma_f32_16x16x32_bf16 v[100:103], v[162:165], v[196:199], v[100:103]
	v_mfma_f32_16x16x32_bf16 v[92:95], v[144:147], v[204:207], v[92:95]
	v_mfma_f32_16x16x32_bf16 v[84:87], v[162:165], v[204:207], v[84:87]
	v_mfma_f32_16x16x32_bf16 v[76:79], v[144:147], v[212:215], v[76:79]
	v_mfma_f32_16x16x32_bf16 v[68:71], v[162:165], v[212:215], v[68:71]
	v_mfma_f32_16x16x32_bf16 v[116:119], v[158:161], v[192:195], v[116:119]
	v_mfma_f32_16x16x32_bf16 v[112:115], v[166:169], v[192:195], v[112:115]
	v_mfma_f32_16x16x32_bf16 v[108:111], v[158:161], v[200:203], v[108:111]
	v_mfma_f32_16x16x32_bf16 v[100:103], v[166:169], v[200:203], v[100:103]
	v_mfma_f32_16x16x32_bf16 v[92:95], v[158:161], v[208:211], v[92:95]
	v_mfma_f32_16x16x32_bf16 v[84:87], v[166:169], v[208:211], v[84:87]
	v_mfma_f32_16x16x32_bf16 v[76:79], v[158:161], v[216:219], v[76:79]
	v_mfma_f32_16x16x32_bf16 v[68:71], v[166:169], v[216:219], v[68:71]
	v_mfma_f32_16x16x32_bf16 v[124:127], v[170:173], v[188:191], v[124:127]
	v_mfma_f32_16x16x32_bf16 v[120:123], v[178:181], v[188:191], v[120:123]
	v_mfma_f32_16x16x32_bf16 v[104:107], v[170:173], v[196:199], v[104:107]
	v_mfma_f32_16x16x32_bf16 v[96:99], v[178:181], v[196:199], v[96:99]
	v_mfma_f32_16x16x32_bf16 v[88:91], v[170:173], v[204:207], v[88:91]
	v_mfma_f32_16x16x32_bf16 v[80:83], v[178:181], v[204:207], v[80:83]
	v_mfma_f32_16x16x32_bf16 v[72:75], v[170:173], v[212:215], v[72:75]
	v_mfma_f32_16x16x32_bf16 v[64:67], v[178:181], v[212:215], v[64:67]
	v_mfma_f32_16x16x32_bf16 v[124:127], v[174:177], v[192:195], v[124:127]
	v_mfma_f32_16x16x32_bf16 v[120:123], v[182:185], v[192:195], v[120:123]
	v_mfma_f32_16x16x32_bf16 v[104:107], v[174:177], v[200:203], v[104:107]
	v_mfma_f32_16x16x32_bf16 v[96:99], v[182:185], v[200:203], v[96:99]
	v_mfma_f32_16x16x32_bf16 v[88:91], v[174:177], v[208:211], v[88:91]
	v_mfma_f32_16x16x32_bf16 v[80:83], v[182:185], v[208:211], v[80:83]
	v_mfma_f32_16x16x32_bf16 v[72:75], v[174:177], v[216:219], v[72:75]
	v_mfma_f32_16x16x32_bf16 v[64:67], v[182:185], v[216:219], v[64:67]
	s_barrier
; #define PG8_STAGE(bufoff, gbase, voff) do { _Pragma("unroll") for (int _i = 0; _i < 2; ++_i) \
;         __builtin_amdgcn_global_load_lds((const unsigned*)((const char*)(gbase) + (voff)[_i]), (PG8_LAS unsigned*)(lds + (bufoff) + ldsw + _i * 8192), 16, 0, 0); } while (0)
; #define PG8_LDA(dst, b, h) do { _Pragma("unroll") for (int m = 0; m < 4; ++m) _Pragma("unroll") for (int k = 0; k < 2; ++k) dst[m][k] = *(const PG8_LAS bf16x8*)(lds + PG8_SA(b, h) + aoff + m * 2048 + k * 1024); } while (0)
; #define PG8_MMA(ai, bj, At, Bt) do { __builtin_amdgcn_s_setprio(1); _Pragma("unroll") for (int m = 0; m < 4; ++m) _Pragma("unroll") for (int n = 0; n < 2; ++n) _Pragma("unroll") for (int k = 0; k < 2; ++k) \
;         acc[ai][bj][m][n] = __builtin_amdgcn_mfma_f32_16x16x32_bf16(Bt[n][k], At[m][k], acc[ai][bj][m][n], 0, 0, 0); __builtin_amdgcn_s_setprio(0); } while (0)
; #define PG8_WAIT_V(n) asm volatile("s_waitcnt vmcnt(" #n ")" ::: "memory")
; #define PG8_WAIT_L(n) asm volatile("s_waitcnt lgkmcnt(" #n ")" ::: "memory")
; #define PG8_BAR __builtin_amdgcn_s_barrier()
; #define PG8_SCHED __builtin_amdgcn_sched_barrier(0)
; template <class Epi, class Sched, bool ALIGN_EPI = false, bool SP2 = false>
; __device__ __forceinline__ void gemm_phase(PG8_LAS unsigned char* lds, const Gemm g, const Sched& S, const Epi& E) {
;     ...
;             PG8_LDA(At, 1, 1); PG8_STAGE(PG8_SB(1, 0), b3, voffB); PG8_STAGE(PG8_SB(1, 1), b3 + hstepB, voffB); PG8_STAGE(PG8_SA(1, 0), a3, voffA);
;             PG8_WAIT_V(8); PG8_WAIT_L(0); PG8_BAR; PG8_MMA(1, 0, At, B0); PG8_MMA(1, 1, At, B1); PG8_BAR; PG8_SCHED;
	s_add_i32 s30, s58, s35
	v_lshl_add_u64 v[148:149], v[148:149], 0, s[12:13]
	s_mov_b32 m0, s30
	ds_read_b128 v[188:191], v155 offset:49152
	ds_read_b128 v[192:195], v155 offset:50176
	ds_read_b128 v[196:199], v155 offset:51200
	ds_read_b128 v[200:203], v155 offset:52224
	ds_read_b128 v[204:207], v155 offset:53248
	ds_read_b128 v[208:211], v155 offset:54272
	ds_read_b128 v[212:215], v155 offset:55296
	ds_read_b128 v[216:219], v155 offset:56320
	global_load_lds_dwordx4 v[148:149], off
	s_add_i32 m0, s30, 0x2000
	s_add_u32 s28, s28, 0x40080
	v_lshl_add_u64 v[148:149], v[220:221], 0, s[12:13]
	s_addc_u32 s29, s29, 0
	s_add_i32 s30, s59, s35
	global_load_lds_dwordx4 v[148:149], off
	v_lshl_add_u64 v[148:149], s[28:29], 0, v[132:133]
	s_mov_b32 m0, s30
	s_nop 0
	global_load_lds_dwordx4 v[148:149], off
	v_lshl_add_u64 v[148:149], s[28:29], 0, v[128:129]
	s_add_i32 m0, s30, 0x2000
	s_nop 0
	global_load_lds_dwordx4 v[148:149], off
	v_lshl_add_u64 v[148:149], v[222:223], 0, s[12:13]
	s_mov_b32 m0, s42
	s_nop 0
	global_load_lds_dwordx4 v[148:149], off
	v_lshl_add_u64 v[148:149], v[224:225], 0, s[12:13]
	s_mov_b32 m0, s43
	s_nop 0
	global_load_lds_dwordx4 v[148:149], off
	s_waitcnt vmcnt(8) lgkmcnt(0)
	s_barrier
	v_mfma_f32_16x16x32_bf16 v[60:63], v[144:147], v[188:191], v[60:63]
	v_mfma_f32_16x16x32_bf16 v[52:55], v[162:165], v[188:191], v[52:55]
	v_mfma_f32_16x16x32_bf16 v[44:47], v[144:147], v[196:199], v[44:47]
	v_mfma_f32_16x16x32_bf16 v[36:39], v[162:165], v[196:199], v[36:39]
	v_mfma_f32_16x16x32_bf16 v[28:31], v[144:147], v[204:207], v[28:31]
	v_mfma_f32_16x16x32_bf16 v[20:23], v[162:165], v[204:207], v[20:23]
	v_mfma_f32_16x16x32_bf16 v[12:15], v[144:147], v[212:215], v[12:15]
	v_mfma_f32_16x16x32_bf16 v[4:7], v[162:165], v[212:215], v[4:7]
	v_mfma_f32_16x16x32_bf16 v[60:63], v[158:161], v[192:195], v[60:63]
	v_mfma_f32_16x16x32_bf16 v[52:55], v[166:169], v[192:195], v[52:55]
	v_mfma_f32_16x16x32_bf16 v[44:47], v[158:161], v[200:203], v[44:47]
	v_mfma_f32_16x16x32_bf16 v[36:39], v[166:169], v[200:203], v[36:39]
	v_mfma_f32_16x16x32_bf16 v[28:31], v[158:161], v[208:211], v[28:31]
	v_mfma_f32_16x16x32_bf16 v[20:23], v[166:169], v[208:211], v[20:23]
	v_mfma_f32_16x16x32_bf16 v[12:15], v[158:161], v[216:219], v[12:15]
	v_mfma_f32_16x16x32_bf16 v[4:7], v[166:169], v[216:219], v[4:7]
	v_mfma_f32_16x16x32_bf16 v[56:59], v[170:173], v[188:191], v[56:59]
	v_mfma_f32_16x16x32_bf16 v[48:51], v[178:181], v[188:191], v[48:51]
	v_mfma_f32_16x16x32_bf16 v[40:43], v[170:173], v[196:199], v[40:43]
	v_mfma_f32_16x16x32_bf16 v[32:35], v[178:181], v[196:199], v[32:35]
	v_mfma_f32_16x16x32_bf16 v[24:27], v[170:173], v[204:207], v[24:27]
	v_mfma_f32_16x16x32_bf16 v[16:19], v[178:181], v[204:207], v[16:19]
	v_mfma_f32_16x16x32_bf16 v[8:11], v[170:173], v[212:215], v[8:11]
	v_mfma_f32_16x16x32_bf16 v[0:3], v[178:181], v[212:215], v[0:3]
	v_mfma_f32_16x16x32_bf16 v[56:59], v[174:177], v[192:195], v[56:59]
	v_mfma_f32_16x16x32_bf16 v[48:51], v[182:185], v[192:195], v[48:51]
	v_mfma_f32_16x16x32_bf16 v[40:43], v[174:177], v[200:203], v[40:43]
	v_mfma_f32_16x16x32_bf16 v[32:35], v[182:185], v[200:203], v[32:35]
	v_mfma_f32_16x16x32_bf16 v[24:27], v[174:177], v[208:211], v[24:27]
	v_mfma_f32_16x16x32_bf16 v[16:19], v[182:185], v[208:211], v[16:19]
	v_mfma_f32_16x16x32_bf16 v[8:11], v[174:177], v[216:219], v[8:11]
	v_mfma_f32_16x16x32_bf16 v[0:3], v[182:185], v[216:219], v[0:3]
	s_barrier
	s_add_i32 s69, s69, 2
	s_add_u32 s26, s26, 0x100
	s_addc_u32 s27, s27, 0
	s_add_u32 s67, s67, 0x100
	s_addc_u32 s68, s68, 0
	s_cmp_gt_u32 s69, 13
	s_cbranch_scc0 .LBB0_1055
	s_and_b64 vcc, exec, s[14:15]
	s_cbranch_vccz .LBB0_1058
	s_barrier

; #define PG8_STAGE(bufoff, gbase, voff) do { _Pragma("unroll") for (int _i = 0; _i < 2; ++_i) \
;         __builtin_amdgcn_global_load_lds((const unsigned*)((const char*)(gbase) + (voff)[_i]), (PG8_LAS unsigned*)(lds + (bufoff) + ldsw + _i * 8192), 16, 0, 0); } while (0)
; #define PG8_LDA(dst, b, h) do { _Pragma("unroll") for (int m = 0; m < 4; ++m) _Pragma("unroll") for (int k = 0; k < 2; ++k) dst[m][k] = *(const PG8_LAS bf16x8*)(lds + PG8_SA(b, h) + aoff + m * 2048 + k * 1024); } while (0)
; #define PG8_LDB(dst, b, h) do { _Pragma("unroll") for (int n = 0; n < 2; ++n) _Pragma("unroll") for (int k = 0; k < 2; ++k) dst[n][k] = *(const PG8_LAS bf16x8*)(lds + PG8_SB(b, h) + boff + n * 2048 + k * 1024); } while (0)
; #define PG8_MMA(ai, bj, At, Bt) do { __builtin_amdgcn_s_setprio(1); _Pragma("unroll") for (int m = 0; m < 4; ++m) _Pragma("unroll") for (int n = 0; n < 2; ++n) _Pragma("unroll") for (int k = 0; k < 2; ++k) \
;         acc[ai][bj][m][n] = __builtin_amdgcn_mfma_f32_16x16x32_bf16(Bt[n][k], At[m][k], acc[ai][bj][m][n], 0, 0, 0); __builtin_amdgcn_s_setprio(0); } while (0)
; #define PG8_WAIT_V(n) asm volatile("s_waitcnt vmcnt(" #n ")" ::: "memory")
; #define PG8_WAIT_L(n) asm volatile("s_waitcnt lgkmcnt(" #n ")" ::: "memory")
; #define PG8_BAR __builtin_amdgcn_s_barrier()
; template <class Epi, class Sched, bool ALIGN_EPI = false, bool SP2 = false>
; __device__ __forceinline__ void gemm_phase(PG8_LAS unsigned char* lds, const Gemm g, const Sched& S, const Epi& E) {
;     ...
;             const char* a1 = cA + (size_t)(t + 1) * kstep;
;             const char* a2 = last ? nA : cA + (size_t)(t + 2) * kstep; const char* b2 = last ? nB : cB + (size_t)(t + 2) * kstep;
;             const char* a3 = a2 + kstep; const char* b3 = b2 + kstep;
;             if (last && has_next) S.a_ready(nxt);
;             if constexpr (SP2) {
;             PG8_LDB(B0, 0, 0); PG8_LDB(B1, 0, 1); PG8_SCHED; PG8_LDA(At, 0, 0); PG8_STAGE(PG8_SA(1, 1), a1 + hstepA, voffA);
;             PG8_WAIT_V(8); PG8_WAIT_L(0); PG8_BAR; PG8_MMA(0, 0, At, B0); PG8_MMA(0, 1, At, B1); PG8_BAR; PG8_SCHED;
;             PG8_LDA(At, 0, 1); PG8_STAGE(PG8_SB(0, 0), b2, voffB); PG8_STAGE(PG8_SB(0, 1), b2 + hstepB, voffB); PG8_STAGE(PG8_SA(0, 0), a2, voffA);
;             PG8_WAIT_V(8); PG8_WAIT_L(0); PG8_BAR; PG8_MMA(1, 0, At, B0); PG8_MMA(1, 1, At, B1); PG8_BAR; PG8_SCHED;
.LBB0_1129:
	ds_read_b128 v[128:131], v191
	ds_read_b128 v[132:135], v191 offset:1024
	ds_read_b128 v[136:139], v191 offset:2048
	ds_read_b128 v[140:143], v191 offset:3072
	ds_read_b128 v[144:147], v192
	ds_read_b128 v[148:151], v192 offset:1024
	ds_read_b128 v[168:171], v192 offset:2048
	ds_read_b128 v[172:175], v192 offset:3072
	s_add_u32 s24, s22, 0x100
	s_addc_u32 s25, s23, 0
	s_cmp_eq_u32 s69, 40
	s_cselect_b32 s29, s11, s25
	s_cselect_b32 s28, s10, s24
	s_cselect_b32 s27, s21, s68
	s_cselect_b32 s26, s20, s67
	v_lshl_add_u64 v[184:185], s[22:23], 0, v[160:161]
	s_add_i32 m0, s34, 0xc000
	ds_read_b128 v[176:179], v193
	ds_read_b128 v[180:183], v193 offset:1024
	ds_read_b128 v[196:199], v193 offset:2048
	ds_read_b128 v[200:203], v193 offset:3072
	ds_read_b128 v[204:207], v193 offset:4096
	ds_read_b128 v[208:211], v193 offset:5120
	ds_read_b128 v[212:215], v193 offset:6144
	ds_read_b128 v[216:219], v193 offset:7168
	global_load_lds_dwordx4 v[184:185], off
	v_lshl_add_u64 v[184:185], s[22:23], 0, v[162:163]
	s_add_i32 m0, s34, 0xe000
	s_nop 0
	global_load_lds_dwordx4 v[184:185], off
	s_waitcnt vmcnt(8) lgkmcnt(0)
	s_barrier
	v_mfma_f32_16x16x32_bf16 v[124:127], v[128:131], v[176:179], v[124:127]
	v_mfma_f32_16x16x32_bf16 v[120:123], v[136:139], v[176:179], v[120:123]
	v_mfma_f32_16x16x32_bf16 v[108:111], v[128:131], v[196:199], v[108:111]
	v_mfma_f32_16x16x32_bf16 v[104:107], v[136:139], v[196:199], v[104:107]
	v_mfma_f32_16x16x32_bf16 v[92:95], v[128:131], v[204:207], v[92:95]
	v_mfma_f32_16x16x32_bf16 v[88:91], v[136:139], v[204:207], v[88:91]
	v_mfma_f32_16x16x32_bf16 v[76:79], v[128:131], v[212:215], v[76:79]
	v_mfma_f32_16x16x32_bf16 v[72:75], v[136:139], v[212:215], v[72:75]
	v_mfma_f32_16x16x32_bf16 v[124:127], v[132:135], v[180:183], v[124:127]
	v_mfma_f32_16x16x32_bf16 v[120:123], v[140:143], v[180:183], v[120:123]
	v_mfma_f32_16x16x32_bf16 v[108:111], v[132:135], v[200:203], v[108:111]
	v_mfma_f32_16x16x32_bf16 v[104:107], v[140:143], v[200:203], v[104:107]
	v_mfma_f32_16x16x32_bf16 v[92:95], v[132:135], v[208:211], v[92:95]
	v_mfma_f32_16x16x32_bf16 v[88:91], v[140:143], v[208:211], v[88:91]
	v_mfma_f32_16x16x32_bf16 v[76:79], v[132:135], v[216:219], v[76:79]
	v_mfma_f32_16x16x32_bf16 v[72:75], v[140:143], v[216:219], v[72:75]
	v_mfma_f32_16x16x32_bf16 v[116:119], v[144:147], v[176:179], v[116:119]
	v_mfma_f32_16x16x32_bf16 v[112:115], v[168:171], v[176:179], v[112:115]
	v_mfma_f32_16x16x32_bf16 v[100:103], v[144:147], v[196:199], v[100:103]
	v_mfma_f32_16x16x32_bf16 v[96:99], v[168:171], v[196:199], v[96:99]
	v_mfma_f32_16x16x32_bf16 v[84:87], v[144:147], v[204:207], v[84:87]
	v_mfma_f32_16x16x32_bf16 v[80:83], v[168:171], v[204:207], v[80:83]
	v_mfma_f32_16x16x32_bf16 v[68:71], v[144:147], v[212:215], v[68:71]
	v_mfma_f32_16x16x32_bf16 v[64:67], v[168:171], v[212:215], v[64:67]
	v_mfma_f32_16x16x32_bf16 v[116:119], v[148:151], v[180:183], v[116:119]
	v_mfma_f32_16x16x32_bf16 v[112:115], v[172:175], v[180:183], v[112:115]
	v_mfma_f32_16x16x32_bf16 v[100:103], v[148:151], v[200:203], v[100:103]
	v_mfma_f32_16x16x32_bf16 v[96:99], v[172:175], v[200:203], v[96:99]
	v_mfma_f32_16x16x32_bf16 v[84:87], v[148:151], v[208:211], v[84:87]
	v_mfma_f32_16x16x32_bf16 v[80:83], v[172:175], v[208:211], v[80:83]
	v_mfma_f32_16x16x32_bf16 v[68:71], v[148:151], v[216:219], v[68:71]
	v_mfma_f32_16x16x32_bf16 v[64:67], v[172:175], v[216:219], v[64:67]
	s_barrier
	s_add_i32 s22, s44, s31
	v_lshl_add_u64 v[184:185], s[26:27], 0, v[154:155]
	s_mov_b32 m0, s22
	ds_read_b128 v[176:179], v193 offset:16384
	ds_read_b128 v[180:183], v193 offset:17408
	ds_read_b128 v[196:199], v193 offset:18432
	ds_read_b128 v[200:203], v193 offset:19456
	ds_read_b128 v[204:207], v193 offset:20480
	ds_read_b128 v[208:211], v193 offset:21504
	ds_read_b128 v[212:215], v193 offset:22528
	ds_read_b128 v[216:219], v193 offset:23552
	global_load_lds_dwordx4 v[184:185], off
	s_add_i32 m0, s22, 0x2000
	s_add_u32 s22, s26, 0xb0000
	v_lshl_add_u64 v[220:221], s[26:27], 0, v[158:159]
	s_addc_u32 s23, s27, 0
	s_add_i32 s58, s45, s31
	global_load_lds_dwordx4 v[220:221], off
	v_lshl_add_u64 v[222:223], s[22:23], 0, v[154:155]
	s_mov_b32 m0, s58
	v_lshl_add_u64 v[224:225], s[28:29], 0, v[156:157]
	global_load_lds_dwordx4 v[222:223], off
	v_lshl_add_u64 v[222:223], s[22:23], 0, v[158:159]
	s_add_i32 m0, s58, 0x2000
	s_nop 0
	global_load_lds_dwordx4 v[222:223], off
	v_lshl_add_u64 v[222:223], s[28:29], 0, v[152:153]
	s_mov_b32 m0, s34
	s_nop 0
	global_load_lds_dwordx4 v[222:223], off
	s_mov_b32 m0, s35
	s_nop 0
	global_load_lds_dwordx4 v[224:225], off
	s_waitcnt vmcnt(8) lgkmcnt(0)
	s_barrier
; #define PG8_STAGE(bufoff, gbase, voff) do { _Pragma("unroll") for (int _i = 0; _i < 2; ++_i) \
;         __builtin_amdgcn_global_load_lds((const unsigned*)((const char*)(gbase) + (voff)[_i]), (PG8_LAS unsigned*)(lds + (bufoff) + ldsw + _i * 8192), 16, 0, 0); } while (0)
; #define PG8_LDA(dst, b, h) do { _Pragma("unroll") for (int m = 0; m < 4; ++m) _Pragma("unroll") for (int k = 0; k < 2; ++k) dst[m][k] = *(const PG8_LAS bf16x8*)(lds + PG8_SA(b, h) + aoff + m * 2048 + k * 1024); } while (0)
; #define PG8_LDB(dst, b, h) do { _Pragma("unroll") for (int n = 0; n < 2; ++n) _Pragma("unroll") for (int k = 0; k < 2; ++k) dst[n][k] = *(const PG8_LAS bf16x8*)(lds + PG8_SB(b, h) + boff + n * 2048 + k * 1024); } while (0)
; #define PG8_MMA(ai, bj, At, Bt) do { __builtin_amdgcn_s_setprio(1); _Pragma("unroll") for (int m = 0; m < 4; ++m) _Pragma("unroll") for (int n = 0; n < 2; ++n) _Pragma("unroll") for (int k = 0; k < 2; ++k) \
;         acc[ai][bj][m][n] = __builtin_amdgcn_mfma_f32_16x16x32_bf16(Bt[n][k], At[m][k], acc[ai][bj][m][n], 0, 0, 0); __builtin_amdgcn_s_setprio(0); } while (0)
; #define PG8_WAIT_V(n) asm volatile("s_waitcnt vmcnt(" #n ")" ::: "memory")
; #define PG8_WAIT_L(n) asm volatile("s_waitcnt lgkmcnt(" #n ")" ::: "memory")
; #define PG8_BAR __builtin_amdgcn_s_barrier()
; #define PG8_SCHED __builtin_amdgcn_sched_barrier(0)
; template <class Epi, class Sched, bool ALIGN_EPI = false, bool SP2 = false>
; __device__ __forceinline__ void gemm_phase(PG8_LAS unsigned char* lds, const Gemm g, const Sched& S, const Epi& E) {
;     ...
;             PG8_WAIT_V(8); PG8_WAIT_L(0); PG8_BAR; PG8_MMA(1, 0, At, B0); PG8_MMA(1, 1, At, B1); PG8_BAR; PG8_SCHED;
;             PG8_LDB(B0, 1, 0); PG8_LDB(B1, 1, 1); PG8_SCHED; PG8_LDA(At, 1, 0); PG8_STAGE(PG8_SA(0, 1), a2 + hstepA, voffA);
;             PG8_WAIT_V(8); PG8_WAIT_L(0); PG8_BAR; PG8_MMA(0, 0, At, B0); PG8_MMA(0, 1, At, B1); PG8_BAR; PG8_SCHED;
	v_mfma_f32_16x16x32_bf16 v[60:63], v[128:131], v[176:179], v[60:63]
	v_mfma_f32_16x16x32_bf16 v[56:59], v[136:139], v[176:179], v[56:59]
	v_mfma_f32_16x16x32_bf16 v[44:47], v[128:131], v[196:199], v[44:47]
	v_mfma_f32_16x16x32_bf16 v[40:43], v[136:139], v[196:199], v[40:43]
	v_mfma_f32_16x16x32_bf16 v[28:31], v[128:131], v[204:207], v[28:31]
	v_mfma_f32_16x16x32_bf16 v[24:27], v[136:139], v[204:207], v[24:27]
	v_mfma_f32_16x16x32_bf16 v[12:15], v[128:131], v[212:215], v[12:15]
	v_mfma_f32_16x16x32_bf16 v[8:11], v[136:139], v[212:215], v[8:11]
	v_mfma_f32_16x16x32_bf16 v[60:63], v[132:135], v[180:183], v[60:63]
	v_mfma_f32_16x16x32_bf16 v[56:59], v[140:143], v[180:183], v[56:59]
	v_mfma_f32_16x16x32_bf16 v[44:47], v[132:135], v[200:203], v[44:47]
	v_mfma_f32_16x16x32_bf16 v[40:43], v[140:143], v[200:203], v[40:43]
	v_mfma_f32_16x16x32_bf16 v[28:31], v[132:135], v[208:211], v[28:31]
	v_mfma_f32_16x16x32_bf16 v[24:27], v[140:143], v[208:211], v[24:27]
	v_mfma_f32_16x16x32_bf16 v[12:15], v[132:135], v[216:219], v[12:15]
	v_mfma_f32_16x16x32_bf16 v[8:11], v[140:143], v[216:219], v[8:11]
	v_mfma_f32_16x16x32_bf16 v[52:55], v[144:147], v[176:179], v[52:55]
	v_mfma_f32_16x16x32_bf16 v[48:51], v[168:171], v[176:179], v[48:51]
	v_mfma_f32_16x16x32_bf16 v[36:39], v[144:147], v[196:199], v[36:39]
	v_mfma_f32_16x16x32_bf16 v[32:35], v[168:171], v[196:199], v[32:35]
	v_mfma_f32_16x16x32_bf16 v[20:23], v[144:147], v[204:207], v[20:23]
	v_mfma_f32_16x16x32_bf16 v[16:19], v[168:171], v[204:207], v[16:19]
	v_mfma_f32_16x16x32_bf16 v[4:7], v[144:147], v[212:215], v[4:7]
	v_mfma_f32_16x16x32_bf16 v[0:3], v[168:171], v[212:215], v[0:3]
	v_mfma_f32_16x16x32_bf16 v[52:55], v[148:151], v[180:183], v[52:55]
	v_mfma_f32_16x16x32_bf16 v[48:51], v[172:175], v[180:183], v[48:51]
	v_mfma_f32_16x16x32_bf16 v[36:39], v[148:151], v[200:203], v[36:39]
	v_mfma_f32_16x16x32_bf16 v[32:35], v[172:175], v[200:203], v[32:35]
	v_mfma_f32_16x16x32_bf16 v[20:23], v[148:151], v[208:211], v[20:23]
	v_mfma_f32_16x16x32_bf16 v[16:19], v[172:175], v[208:211], v[16:19]
	v_mfma_f32_16x16x32_bf16 v[4:7], v[148:151], v[216:219], v[4:7]
	v_mfma_f32_16x16x32_bf16 v[0:3], v[172:175], v[216:219], v[0:3]
	s_barrier
	s_add_i32 s58, 0, 0x18000
	s_add_i32 s59, 0, 0x1c000
	v_add_u32_e32 v140, s58, v189
	v_add_u32_e32 v172, s59, v189
	ds_read_b128 v[128:131], v140
	ds_read_b128 v[132:135], v140 offset:1024
	ds_read_b128 v[136:139], v140 offset:2048
	ds_read_b128 v[140:143], v140 offset:3072
	ds_read_b128 v[144:147], v172
	ds_read_b128 v[148:151], v172 offset:1024
	ds_read_b128 v[168:171], v172 offset:2048
	ds_read_b128 v[172:175], v172 offset:3072
	s_add_u32 s22, s28, 0xb0000
	s_addc_u32 s23, s29, 0
	s_mov_b32 m0, s36
	v_lshl_add_u64 v[226:227], s[22:23], 0, v[152:153]
	ds_read_b128 v[176:179], v193 offset:32768
	ds_read_b128 v[180:183], v193 offset:33792
	ds_read_b128 v[196:199], v193 offset:34816
	ds_read_b128 v[200:203], v193 offset:35840
	ds_read_b128 v[204:207], v193 offset:36864
	ds_read_b128 v[208:211], v193 offset:37888
	ds_read_b128 v[212:215], v193 offset:38912
	ds_read_b128 v[216:219], v193 offset:39936
	global_load_lds_dwordx4 v[226:227], off
	v_lshl_add_u64 v[226:227], s[22:23], 0, v[156:157]
	s_mov_b32 m0, s37
	s_nop 0
	global_load_lds_dwordx4 v[226:227], off
	s_waitcnt vmcnt(8) lgkmcnt(0)
	s_barrier
	v_mfma_f32_16x16x32_bf16 v[124:127], v[128:131], v[176:179], v[124:127]
	v_mfma_f32_16x16x32_bf16 v[120:123], v[136:139], v[176:179], v[120:123]
	v_mfma_f32_16x16x32_bf16 v[108:111], v[128:131], v[196:199], v[108:111]
	v_mfma_f32_16x16x32_bf16 v[104:107], v[136:139], v[196:199], v[104:107]
	v_mfma_f32_16x16x32_bf16 v[92:95], v[128:131], v[204:207], v[92:95]
	v_mfma_f32_16x16x32_bf16 v[88:91], v[136:139], v[204:207], v[88:91]
	v_mfma_f32_16x16x32_bf16 v[76:79], v[128:131], v[212:215], v[76:79]
	v_mfma_f32_16x16x32_bf16 v[72:75], v[136:139], v[212:215], v[72:75]
	v_mfma_f32_16x16x32_bf16 v[124:127], v[132:135], v[180:183], v[124:127]
	v_mfma_f32_16x16x32_bf16 v[120:123], v[140:143], v[180:183], v[120:123]
	v_mfma_f32_16x16x32_bf16 v[108:111], v[132:135], v[200:203], v[108:111]
	v_mfma_f32_16x16x32_bf16 v[104:107], v[140:143], v[200:203], v[104:107]
	v_mfma_f32_16x16x32_bf16 v[92:95], v[132:135], v[208:211], v[92:95]
	v_mfma_f32_16x16x32_bf16 v[88:91], v[140:143], v[208:211], v[88:91]
	v_mfma_f32_16x16x32_bf16 v[76:79], v[132:135], v[216:219], v[76:79]
	v_mfma_f32_16x16x32_bf16 v[72:75], v[140:143], v[216:219], v[72:75]
	v_mfma_f32_16x16x32_bf16 v[116:119], v[144:147], v[176:179], v[116:119]
	v_mfma_f32_16x16x32_bf16 v[112:115], v[168:171], v[176:179], v[112:115]
	v_mfma_f32_16x16x32_bf16 v[100:103], v[144:147], v[196:199], v[100:103]
	v_mfma_f32_16x16x32_bf16 v[96:99], v[168:171], v[196:199], v[96:99]
	v_mfma_f32_16x16x32_bf16 v[84:87], v[144:147], v[204:207], v[84:87]
	v_mfma_f32_16x16x32_bf16 v[80:83], v[168:171], v[204:207], v[80:83]
	v_mfma_f32_16x16x32_bf16 v[68:71], v[144:147], v[212:215], v[68:71]
	v_mfma_f32_16x16x32_bf16 v[64:67], v[168:171], v[212:215], v[64:67]
	v_mfma_f32_16x16x32_bf16 v[116:119], v[148:151], v[180:183], v[116:119]
	v_mfma_f32_16x16x32_bf16 v[112:115], v[172:175], v[180:183], v[112:115]
	v_mfma_f32_16x16x32_bf16 v[100:103], v[148:151], v[200:203], v[100:103]
	v_mfma_f32_16x16x32_bf16 v[96:99], v[172:175], v[200:203], v[96:99]
	v_mfma_f32_16x16x32_bf16 v[84:87], v[148:151], v[208:211], v[84:87]
	v_mfma_f32_16x16x32_bf16 v[80:83], v[172:175], v[208:211], v[80:83]
	v_mfma_f32_16x16x32_bf16 v[68:71], v[148:151], v[216:219], v[68:71]
	v_mfma_f32_16x16x32_bf16 v[64:67], v[172:175], v[216:219], v[64:67]
	s_barrier
; #define PG8_STAGE(bufoff, gbase, voff) do { _Pragma("unroll") for (int _i = 0; _i < 2; ++_i) \
;         __builtin_amdgcn_global_load_lds((const unsigned*)((const char*)(gbase) + (voff)[_i]), (PG8_LAS unsigned*)(lds + (bufoff) + ldsw + _i * 8192), 16, 0, 0); } while (0)
; #define PG8_LDA(dst, b, h) do { _Pragma("unroll") for (int m = 0; m < 4; ++m) _Pragma("unroll") for (int k = 0; k < 2; ++k) dst[m][k] = *(const PG8_LAS bf16x8*)(lds + PG8_SA(b, h) + aoff + m * 2048 + k * 1024); } while (0)
; #define PG8_MMA(ai, bj, At, Bt) do { __builtin_amdgcn_s_setprio(1); _Pragma("unroll") for (int m = 0; m < 4; ++m) _Pragma("unroll") for (int n = 0; n < 2; ++n) _Pragma("unroll") for (int k = 0; k < 2; ++k) \
;         acc[ai][bj][m][n] = __builtin_amdgcn_mfma_f32_16x16x32_bf16(Bt[n][k], At[m][k], acc[ai][bj][m][n], 0, 0, 0); __builtin_amdgcn_s_setprio(0); } while (0)
; #define PG8_WAIT_V(n) asm volatile("s_waitcnt vmcnt(" #n ")" ::: "memory")
; #define PG8_WAIT_L(n) asm volatile("s_waitcnt lgkmcnt(" #n ")" ::: "memory")
; #define PG8_BAR __builtin_amdgcn_s_barrier()
; #define PG8_SCHED __builtin_amdgcn_sched_barrier(0)
; template <class Epi, class Sched, bool ALIGN_EPI = false, bool SP2 = false>
; __device__ __forceinline__ void gemm_phase(PG8_LAS unsigned char* lds, const Gemm g, const Sched& S, const Epi& E) {
;     ...
;             PG8_LDA(At, 1, 1); PG8_STAGE(PG8_SB(1, 0), b3, voffB); PG8_STAGE(PG8_SB(1, 1), b3 + hstepB, voffB); PG8_STAGE(PG8_SA(1, 0), a3, voffA);
;             PG8_WAIT_V(8); PG8_WAIT_L(0); PG8_BAR; PG8_MMA(1, 0, At, B0); PG8_MMA(1, 1, At, B1); PG8_BAR; PG8_SCHED;
	s_add_i32 s22, s58, s31
	v_lshl_add_u64 v[184:185], v[184:185], 0, s[16:17]
	s_mov_b32 m0, s22
	ds_read_b128 v[176:179], v193 offset:49152
	ds_read_b128 v[180:183], v193 offset:50176
	ds_read_b128 v[196:199], v193 offset:51200
	ds_read_b128 v[200:203], v193 offset:52224
	ds_read_b128 v[204:207], v193 offset:53248
	ds_read_b128 v[208:211], v193 offset:54272
	ds_read_b128 v[212:215], v193 offset:55296
	ds_read_b128 v[216:219], v193 offset:56320
	global_load_lds_dwordx4 v[184:185], off
	s_add_i32 m0, s22, 0x2000
	s_add_u32 s22, s26, 0xb0080
	v_lshl_add_u64 v[184:185], v[220:221], 0, s[16:17]
	s_addc_u32 s23, s27, 0
	s_add_i32 s26, s59, s31
	global_load_lds_dwordx4 v[184:185], off
	v_lshl_add_u64 v[184:185], s[22:23], 0, v[154:155]
	s_mov_b32 m0, s26
	s_nop 0
	global_load_lds_dwordx4 v[184:185], off
	v_lshl_add_u64 v[184:185], s[22:23], 0, v[158:159]
	s_add_i32 m0, s26, 0x2000
	s_nop 0
	global_load_lds_dwordx4 v[184:185], off
	v_lshl_add_u64 v[184:185], v[222:223], 0, s[16:17]
	s_mov_b32 m0, s39
	s_nop 0
	global_load_lds_dwordx4 v[184:185], off
	v_lshl_add_u64 v[184:185], v[224:225], 0, s[16:17]
	s_mov_b32 m0, s40
	s_nop 0
	global_load_lds_dwordx4 v[184:185], off
	s_waitcnt vmcnt(8) lgkmcnt(0)
	s_barrier
	v_mfma_f32_16x16x32_bf16 v[60:63], v[128:131], v[176:179], v[60:63]
	v_mfma_f32_16x16x32_bf16 v[56:59], v[136:139], v[176:179], v[56:59]
	v_mfma_f32_16x16x32_bf16 v[44:47], v[128:131], v[196:199], v[44:47]
	v_mfma_f32_16x16x32_bf16 v[40:43], v[136:139], v[196:199], v[40:43]
	v_mfma_f32_16x16x32_bf16 v[28:31], v[128:131], v[204:207], v[28:31]
	v_mfma_f32_16x16x32_bf16 v[24:27], v[136:139], v[204:207], v[24:27]
	v_mfma_f32_16x16x32_bf16 v[12:15], v[128:131], v[212:215], v[12:15]
	v_mfma_f32_16x16x32_bf16 v[8:11], v[136:139], v[212:215], v[8:11]
	v_mfma_f32_16x16x32_bf16 v[60:63], v[132:135], v[180:183], v[60:63]
	v_mfma_f32_16x16x32_bf16 v[56:59], v[140:143], v[180:183], v[56:59]
	v_mfma_f32_16x16x32_bf16 v[44:47], v[132:135], v[200:203], v[44:47]
	v_mfma_f32_16x16x32_bf16 v[40:43], v[140:143], v[200:203], v[40:43]
	v_mfma_f32_16x16x32_bf16 v[28:31], v[132:135], v[208:211], v[28:31]
	v_mfma_f32_16x16x32_bf16 v[24:27], v[140:143], v[208:211], v[24:27]
	v_mfma_f32_16x16x32_bf16 v[12:15], v[132:135], v[216:219], v[12:15]
	v_mfma_f32_16x16x32_bf16 v[8:11], v[140:143], v[216:219], v[8:11]
	v_mfma_f32_16x16x32_bf16 v[52:55], v[144:147], v[176:179], v[52:55]
	v_mfma_f32_16x16x32_bf16 v[48:51], v[168:171], v[176:179], v[48:51]
	v_mfma_f32_16x16x32_bf16 v[36:39], v[144:147], v[196:199], v[36:39]
	v_mfma_f32_16x16x32_bf16 v[32:35], v[168:171], v[196:199], v[32:35]
	v_mfma_f32_16x16x32_bf16 v[20:23], v[144:147], v[204:207], v[20:23]
	v_mfma_f32_16x16x32_bf16 v[16:19], v[168:171], v[204:207], v[16:19]
	v_mfma_f32_16x16x32_bf16 v[4:7], v[144:147], v[212:215], v[4:7]
	v_mfma_f32_16x16x32_bf16 v[0:3], v[168:171], v[212:215], v[0:3]
	v_mfma_f32_16x16x32_bf16 v[52:55], v[148:151], v[180:183], v[52:55]
	v_mfma_f32_16x16x32_bf16 v[48:51], v[172:175], v[180:183], v[48:51]
	v_mfma_f32_16x16x32_bf16 v[36:39], v[148:151], v[200:203], v[36:39]
	v_mfma_f32_16x16x32_bf16 v[32:35], v[172:175], v[200:203], v[32:35]
	v_mfma_f32_16x16x32_bf16 v[20:23], v[148:151], v[208:211], v[20:23]
	v_mfma_f32_16x16x32_bf16 v[16:19], v[172:175], v[208:211], v[16:19]
	v_mfma_f32_16x16x32_bf16 v[4:7], v[148:151], v[216:219], v[4:7]
	v_mfma_f32_16x16x32_bf16 v[0:3], v[172:175], v[216:219], v[0:3]
	s_barrier
	s_add_i32 s69, s69, 2
	s_add_u32 s67, s67, 0x100
	s_addc_u32 s68, s68, 0
	s_cmp_gt_u32 s69, 41
	s_mov_b64 s[22:23], s[24:25]
	s_cbranch_scc0 .LBB0_1129
	s_and_b64 vcc, exec, s[18:19]
	s_cbranch_vccz .LBB0_1132
	s_barrier

; #define PG8_STAGE(bufoff, gbase, voff) do { _Pragma("unroll") for (int _i = 0; _i < 2; ++_i) \
;         __builtin_amdgcn_global_load_lds((const unsigned*)((const char*)(gbase) + (voff)[_i]), (PG8_LAS unsigned*)(lds + (bufoff) + ldsw + _i * 8192), 16, 0, 0); } while (0)
; #define PG8_LDA(dst, b, h) do { _Pragma("unroll") for (int m = 0; m < 4; ++m) _Pragma("unroll") for (int k = 0; k < 2; ++k) dst[m][k] = *(const PG8_LAS bf16x8*)(lds + PG8_SA(b, h) + aoff + m * 2048 + k * 1024); } while (0)
; #define PG8_LDB(dst, b, h) do { _Pragma("unroll") for (int n = 0; n < 2; ++n) _Pragma("unroll") for (int k = 0; k < 2; ++k) dst[n][k] = *(const PG8_LAS bf16x8*)(lds + PG8_SB(b, h) + boff + n * 2048 + k * 1024); } while (0)
; #define PG8_MMA(ai, bj, At, Bt) do { __builtin_amdgcn_s_setprio(1); _Pragma("unroll") for (int m = 0; m < 4; ++m) _Pragma("unroll") for (int n = 0; n < 2; ++n) _Pragma("unroll") for (int k = 0; k < 2; ++k) \
;         acc[ai][bj][m][n] = __builtin_amdgcn_mfma_f32_16x16x32_bf16(Bt[n][k], At[m][k], acc[ai][bj][m][n], 0, 0, 0); __builtin_amdgcn_s_setprio(0); } while (0)
; #define PG8_WAIT_V(n) asm volatile("s_waitcnt vmcnt(" #n ")" ::: "memory")
; #define PG8_WAIT_L(n) asm volatile("s_waitcnt lgkmcnt(" #n ")" ::: "memory")
; #define PG8_BAR __builtin_amdgcn_s_barrier()
; template <class Epi, class Sched, bool ALIGN_EPI = false, bool SP2 = false>
; __device__ __forceinline__ void gemm_phase(PG8_LAS unsigned char* lds, const Gemm g, const Sched& S, const Epi& E) {
;     ...
;             const char* a1 = cA + (size_t)(t + 1) * kstep;
;             const char* a2 = last ? nA : cA + (size_t)(t + 2) * kstep; const char* b2 = last ? nB : cB + (size_t)(t + 2) * kstep;
;             const char* a3 = a2 + kstep; const char* b3 = b2 + kstep;
;             if (last && has_next) S.a_ready(nxt);
;             if constexpr (SP2) {
;             PG8_LDB(B0, 0, 0); PG8_LDB(B1, 0, 1); PG8_SCHED; PG8_LDA(At, 0, 0); PG8_STAGE(PG8_SA(1, 1), a1 + hstepA, voffA);
;             PG8_WAIT_V(8); PG8_WAIT_L(0); PG8_BAR; PG8_MMA(0, 0, At, B0); PG8_MMA(0, 1, At, B1); PG8_BAR; PG8_SCHED;
;             PG8_LDA(At, 0, 1); PG8_STAGE(PG8_SB(0, 0), b2, voffB); PG8_STAGE(PG8_SB(0, 1), b2 + hstepB, voffB); PG8_STAGE(PG8_SA(0, 0), a2, voffA);
;             PG8_WAIT_V(8); PG8_WAIT_L(0); PG8_BAR; PG8_MMA(1, 0, At, B0); PG8_MMA(1, 1, At, B1); PG8_BAR; PG8_SCHED;
.LBB0_1161:
	s_add_u32 s43, s36, s42
	s_addc_u32 s48, s37, 0
	s_add_u32 s46, s43, 0x100
	s_addc_u32 s47, s48, 0
	s_and_b64 s[44:45], s[40:41], exec
	s_cselect_b32 s45, s25, s47
	s_cselect_b32 s44, s89, s46
	s_add_u32 s42, s34, s42
	s_addc_u32 s46, s35, 0
	s_add_u32 s42, s42, 0x100
	s_addc_u32 s46, s46, 0
	s_and_b64 s[40:41], s[40:41], exec
	s_cselect_b32 s47, s23, s46
	s_cselect_b32 s46, s90, s42
	s_add_u32 s64, s43, 0x10080
	ds_read_b128 v[146:149], v143
	ds_read_b128 v[150:153], v143 offset:1024
	ds_read_b128 v[154:157], v143 offset:2048
	ds_read_b128 v[158:161], v143 offset:3072
	ds_read_b128 v[162:165], v144
	ds_read_b128 v[166:169], v144 offset:1024
	ds_read_b128 v[170:173], v144 offset:2048
	ds_read_b128 v[174:177], v144 offset:3072
	s_addc_u32 s65, s48, 0
	s_add_i32 s97, s82, s67
	s_add_i32 m0, s31, 0xc000
	s_add_i32 s59, s31, 0xe000
	s_add_i32 s58, s97, 0x2000
	s_add_u32 s48, s46, 0x10000
	s_addc_u32 s49, s47, 0
	s_add_i32 vcc_hi, s83, s67
	s_add_i32 vcc_lo, vcc_hi, 0x2000
	s_add_i32 s96, 0, 0x18000
	s_add_i32 s95, 0, 0x1c000
	s_add_u32 s42, s44, 0x10000
	s_addc_u32 s43, s45, 0
	s_add_i32 s94, s96, s67
	s_add_i32 s92, s94, 0x2000
	s_add_u32 s40, s46, 0x10080
	s_addc_u32 s41, s47, 0
	s_add_i32 s93, s95, s67
	s_add_i32 s91, s93, 0x2000
	v_lshl_add_u64 v[212:213], s[64:65], 0, v[134:135]
	ds_read_b128 v[178:181], v145
	ds_read_b128 v[182:185], v145 offset:1024
	ds_read_b128 v[188:191], v145 offset:2048
	ds_read_b128 v[192:195], v145 offset:3072
	ds_read_b128 v[196:199], v145 offset:4096
	ds_read_b128 v[200:203], v145 offset:5120
	ds_read_b128 v[204:207], v145 offset:6144
	ds_read_b128 v[208:211], v145 offset:7168
	global_load_lds_dwordx4 v[212:213], off
	v_lshl_add_u64 v[212:213], s[64:65], 0, v[130:131]
	s_mov_b32 m0, s59
	s_nop 0
	global_load_lds_dwordx4 v[212:213], off
	s_waitcnt vmcnt(8) lgkmcnt(0)
	s_barrier
	v_mfma_f32_16x16x32_bf16 v[124:127], v[146:149], v[178:181], v[124:127]
	v_mfma_f32_16x16x32_bf16 v[120:123], v[154:157], v[178:181], v[120:123]
	v_mfma_f32_16x16x32_bf16 v[116:119], v[146:149], v[188:191], v[116:119]
	v_mfma_f32_16x16x32_bf16 v[108:111], v[154:157], v[188:191], v[108:111]
	v_mfma_f32_16x16x32_bf16 v[100:103], v[146:149], v[196:199], v[100:103]
	v_mfma_f32_16x16x32_bf16 v[92:95], v[154:157], v[196:199], v[92:95]
	v_mfma_f32_16x16x32_bf16 v[84:87], v[146:149], v[204:207], v[84:87]
	v_mfma_f32_16x16x32_bf16 v[76:79], v[154:157], v[204:207], v[76:79]
	v_mfma_f32_16x16x32_bf16 v[124:127], v[150:153], v[182:185], v[124:127]
	v_mfma_f32_16x16x32_bf16 v[120:123], v[158:161], v[182:185], v[120:123]
	v_mfma_f32_16x16x32_bf16 v[116:119], v[150:153], v[192:195], v[116:119]
	v_mfma_f32_16x16x32_bf16 v[108:111], v[158:161], v[192:195], v[108:111]
	v_mfma_f32_16x16x32_bf16 v[100:103], v[150:153], v[200:203], v[100:103]
	v_mfma_f32_16x16x32_bf16 v[92:95], v[158:161], v[200:203], v[92:95]
	v_mfma_f32_16x16x32_bf16 v[84:87], v[150:153], v[208:211], v[84:87]
	v_mfma_f32_16x16x32_bf16 v[76:79], v[158:161], v[208:211], v[76:79]
	v_mfma_f32_16x16x32_bf16 v[112:115], v[162:165], v[178:181], v[112:115]
	v_mfma_f32_16x16x32_bf16 v[104:107], v[170:173], v[178:181], v[104:107]
	v_mfma_f32_16x16x32_bf16 v[96:99], v[162:165], v[188:191], v[96:99]
	v_mfma_f32_16x16x32_bf16 v[88:91], v[170:173], v[188:191], v[88:91]
	v_mfma_f32_16x16x32_bf16 v[80:83], v[162:165], v[196:199], v[80:83]
	v_mfma_f32_16x16x32_bf16 v[72:75], v[170:173], v[196:199], v[72:75]
	v_mfma_f32_16x16x32_bf16 v[68:71], v[162:165], v[204:207], v[68:71]
	v_mfma_f32_16x16x32_bf16 v[64:67], v[170:173], v[204:207], v[64:67]
	v_mfma_f32_16x16x32_bf16 v[112:115], v[166:169], v[182:185], v[112:115]
	v_mfma_f32_16x16x32_bf16 v[104:107], v[174:177], v[182:185], v[104:107]
	v_mfma_f32_16x16x32_bf16 v[96:99], v[166:169], v[192:195], v[96:99]
	v_mfma_f32_16x16x32_bf16 v[88:91], v[174:177], v[192:195], v[88:91]
	v_mfma_f32_16x16x32_bf16 v[80:83], v[166:169], v[200:203], v[80:83]
	v_mfma_f32_16x16x32_bf16 v[72:75], v[174:177], v[200:203], v[72:75]
	v_mfma_f32_16x16x32_bf16 v[68:71], v[166:169], v[208:211], v[68:71]
	v_mfma_f32_16x16x32_bf16 v[64:67], v[174:177], v[208:211], v[64:67]
	s_barrier
	s_mov_b32 m0, s97
	v_lshl_add_u64 v[212:213], s[46:47], 0, v[132:133]
	ds_read_b128 v[178:181], v145 offset:16384
	ds_read_b128 v[182:185], v145 offset:17408
	ds_read_b128 v[188:191], v145 offset:18432
	ds_read_b128 v[192:195], v145 offset:19456
	ds_read_b128 v[196:199], v145 offset:20480
	ds_read_b128 v[200:203], v145 offset:21504
	ds_read_b128 v[204:207], v145 offset:22528
	ds_read_b128 v[208:211], v145 offset:23552
	global_load_lds_dwordx4 v[212:213], off
	v_lshl_add_u64 v[214:215], s[46:47], 0, v[128:129]
	s_mov_b32 m0, s58
	v_lshl_add_u64 v[216:217], s[48:49], 0, v[132:133]
	global_load_lds_dwordx4 v[214:215], off
	s_mov_b32 m0, vcc_hi
	v_lshl_add_u64 v[218:219], s[44:45], 0, v[130:131]
	global_load_lds_dwordx4 v[216:217], off
	v_lshl_add_u64 v[216:217], s[48:49], 0, v[128:129]
	s_mov_b32 m0, vcc_lo
	s_nop 0
	global_load_lds_dwordx4 v[216:217], off
	v_lshl_add_u64 v[216:217], s[44:45], 0, v[134:135]
	s_mov_b32 m0, s31
	s_nop 0
	global_load_lds_dwordx4 v[216:217], off
	s_mov_b32 m0, s74
	s_nop 0
	global_load_lds_dwordx4 v[218:219], off
	s_waitcnt vmcnt(8) lgkmcnt(0)
	s_barrier
; #define PG8_STAGE(bufoff, gbase, voff) do { _Pragma("unroll") for (int _i = 0; _i < 2; ++_i) \
;         __builtin_amdgcn_global_load_lds((const unsigned*)((const char*)(gbase) + (voff)[_i]), (PG8_LAS unsigned*)(lds + (bufoff) + ldsw + _i * 8192), 16, 0, 0); } while (0)
; #define PG8_LDA(dst, b, h) do { _Pragma("unroll") for (int m = 0; m < 4; ++m) _Pragma("unroll") for (int k = 0; k < 2; ++k) dst[m][k] = *(const PG8_LAS bf16x8*)(lds + PG8_SA(b, h) + aoff + m * 2048 + k * 1024); } while (0)
; #define PG8_LDB(dst, b, h) do { _Pragma("unroll") for (int n = 0; n < 2; ++n) _Pragma("unroll") for (int k = 0; k < 2; ++k) dst[n][k] = *(const PG8_LAS bf16x8*)(lds + PG8_SB(b, h) + boff + n * 2048 + k * 1024); } while (0)
; #define PG8_MMA(ai, bj, At, Bt) do { __builtin_amdgcn_s_setprio(1); _Pragma("unroll") for (int m = 0; m < 4; ++m) _Pragma("unroll") for (int n = 0; n < 2; ++n) _Pragma("unroll") for (int k = 0; k < 2; ++k) \
;         acc[ai][bj][m][n] = __builtin_amdgcn_mfma_f32_16x16x32_bf16(Bt[n][k], At[m][k], acc[ai][bj][m][n], 0, 0, 0); __builtin_amdgcn_s_setprio(0); } while (0)
; #define PG8_WAIT_V(n) asm volatile("s_waitcnt vmcnt(" #n ")" ::: "memory")
; #define PG8_WAIT_L(n) asm volatile("s_waitcnt lgkmcnt(" #n ")" ::: "memory")
; #define PG8_BAR __builtin_amdgcn_s_barrier()
; #define PG8_SCHED __builtin_amdgcn_sched_barrier(0)
; template <class Epi, class Sched, bool ALIGN_EPI = false, bool SP2 = false>
; __device__ __forceinline__ void gemm_phase(PG8_LAS unsigned char* lds, const Gemm g, const Sched& S, const Epi& E) {
;     ...
;             PG8_WAIT_V(8); PG8_WAIT_L(0); PG8_BAR; PG8_MMA(1, 0, At, B0); PG8_MMA(1, 1, At, B1); PG8_BAR; PG8_SCHED;
;             PG8_LDB(B0, 1, 0); PG8_LDB(B1, 1, 1); PG8_SCHED; PG8_LDA(At, 1, 0); PG8_STAGE(PG8_SA(0, 1), a2 + hstepA, voffA);
;             PG8_WAIT_V(8); PG8_WAIT_L(0); PG8_BAR; PG8_MMA(0, 0, At, B0); PG8_MMA(0, 1, At, B1); PG8_BAR; PG8_SCHED;
	v_mfma_f32_16x16x32_bf16 v[60:63], v[146:149], v[178:181], v[60:63]
	v_mfma_f32_16x16x32_bf16 v[56:59], v[154:157], v[178:181], v[56:59]
	v_mfma_f32_16x16x32_bf16 v[52:55], v[146:149], v[188:191], v[52:55]
	v_mfma_f32_16x16x32_bf16 v[44:47], v[154:157], v[188:191], v[44:47]
	v_mfma_f32_16x16x32_bf16 v[36:39], v[146:149], v[196:199], v[36:39]
	v_mfma_f32_16x16x32_bf16 v[28:31], v[154:157], v[196:199], v[28:31]
	v_mfma_f32_16x16x32_bf16 v[20:23], v[146:149], v[204:207], v[20:23]
	v_mfma_f32_16x16x32_bf16 v[12:15], v[154:157], v[204:207], v[12:15]
	v_mfma_f32_16x16x32_bf16 v[60:63], v[150:153], v[182:185], v[60:63]
	v_mfma_f32_16x16x32_bf16 v[56:59], v[158:161], v[182:185], v[56:59]
	v_mfma_f32_16x16x32_bf16 v[52:55], v[150:153], v[192:195], v[52:55]
	v_mfma_f32_16x16x32_bf16 v[44:47], v[158:161], v[192:195], v[44:47]
	v_mfma_f32_16x16x32_bf16 v[36:39], v[150:153], v[200:203], v[36:39]
	v_mfma_f32_16x16x32_bf16 v[28:31], v[158:161], v[200:203], v[28:31]
	v_mfma_f32_16x16x32_bf16 v[20:23], v[150:153], v[208:211], v[20:23]
	v_mfma_f32_16x16x32_bf16 v[12:15], v[158:161], v[208:211], v[12:15]
	v_mfma_f32_16x16x32_bf16 v[48:51], v[162:165], v[178:181], v[48:51]
	v_mfma_f32_16x16x32_bf16 v[40:43], v[170:173], v[178:181], v[40:43]
	v_mfma_f32_16x16x32_bf16 v[32:35], v[162:165], v[188:191], v[32:35]
	v_mfma_f32_16x16x32_bf16 v[24:27], v[170:173], v[188:191], v[24:27]
	v_mfma_f32_16x16x32_bf16 v[16:19], v[162:165], v[196:199], v[16:19]
	v_mfma_f32_16x16x32_bf16 v[8:11], v[170:173], v[196:199], v[8:11]
	v_mfma_f32_16x16x32_bf16 v[4:7], v[162:165], v[204:207], v[4:7]
	v_mfma_f32_16x16x32_bf16 v[0:3], v[170:173], v[204:207], v[0:3]
	v_mfma_f32_16x16x32_bf16 v[48:51], v[166:169], v[182:185], v[48:51]
	v_mfma_f32_16x16x32_bf16 v[40:43], v[174:177], v[182:185], v[40:43]
	v_mfma_f32_16x16x32_bf16 v[32:35], v[166:169], v[192:195], v[32:35]
	v_mfma_f32_16x16x32_bf16 v[24:27], v[174:177], v[192:195], v[24:27]
	v_mfma_f32_16x16x32_bf16 v[16:19], v[166:169], v[200:203], v[16:19]
	v_mfma_f32_16x16x32_bf16 v[8:11], v[174:177], v[200:203], v[8:11]
	v_mfma_f32_16x16x32_bf16 v[4:7], v[166:169], v[208:211], v[4:7]
	v_mfma_f32_16x16x32_bf16 v[0:3], v[174:177], v[208:211], v[0:3]
	s_barrier
	v_add_u32_e32 v158, s96, v141
	v_add_u32_e32 v174, s95, v141
	ds_read_b128 v[146:149], v158
	ds_read_b128 v[150:153], v158 offset:1024
	ds_read_b128 v[154:157], v158 offset:2048
	ds_read_b128 v[158:161], v158 offset:3072
	ds_read_b128 v[162:165], v174
	ds_read_b128 v[166:169], v174 offset:1024
	ds_read_b128 v[170:173], v174 offset:2048
	ds_read_b128 v[174:177], v174 offset:3072
	s_mov_b32 m0, s75
	v_lshl_add_u64 v[220:221], s[42:43], 0, v[134:135]
	ds_read_b128 v[178:181], v145 offset:32768
	ds_read_b128 v[182:185], v145 offset:33792
	ds_read_b128 v[188:191], v145 offset:34816
	ds_read_b128 v[192:195], v145 offset:35840
	ds_read_b128 v[196:199], v145 offset:36864
	ds_read_b128 v[200:203], v145 offset:37888
	ds_read_b128 v[204:207], v145 offset:38912
	ds_read_b128 v[208:211], v145 offset:39936
	global_load_lds_dwordx4 v[220:221], off
	v_lshl_add_u64 v[220:221], s[42:43], 0, v[130:131]
	s_mov_b32 m0, s76
	s_nop 0
	global_load_lds_dwordx4 v[220:221], off
	s_waitcnt vmcnt(8) lgkmcnt(0)
	s_barrier
	v_mfma_f32_16x16x32_bf16 v[124:127], v[146:149], v[178:181], v[124:127]
	v_mfma_f32_16x16x32_bf16 v[120:123], v[154:157], v[178:181], v[120:123]
	v_mfma_f32_16x16x32_bf16 v[116:119], v[146:149], v[188:191], v[116:119]
	v_mfma_f32_16x16x32_bf16 v[108:111], v[154:157], v[188:191], v[108:111]
	v_mfma_f32_16x16x32_bf16 v[100:103], v[146:149], v[196:199], v[100:103]
	v_mfma_f32_16x16x32_bf16 v[92:95], v[154:157], v[196:199], v[92:95]
	v_mfma_f32_16x16x32_bf16 v[84:87], v[146:149], v[204:207], v[84:87]
	v_mfma_f32_16x16x32_bf16 v[76:79], v[154:157], v[204:207], v[76:79]
	v_mfma_f32_16x16x32_bf16 v[124:127], v[150:153], v[182:185], v[124:127]
	v_mfma_f32_16x16x32_bf16 v[120:123], v[158:161], v[182:185], v[120:123]
	v_mfma_f32_16x16x32_bf16 v[116:119], v[150:153], v[192:195], v[116:119]
	v_mfma_f32_16x16x32_bf16 v[108:111], v[158:161], v[192:195], v[108:111]
	v_mfma_f32_16x16x32_bf16 v[100:103], v[150:153], v[200:203], v[100:103]
	v_mfma_f32_16x16x32_bf16 v[92:95], v[158:161], v[200:203], v[92:95]
	v_mfma_f32_16x16x32_bf16 v[84:87], v[150:153], v[208:211], v[84:87]
	v_mfma_f32_16x16x32_bf16 v[76:79], v[158:161], v[208:211], v[76:79]
	v_mfma_f32_16x16x32_bf16 v[112:115], v[162:165], v[178:181], v[112:115]
	v_mfma_f32_16x16x32_bf16 v[104:107], v[170:173], v[178:181], v[104:107]
	v_mfma_f32_16x16x32_bf16 v[96:99], v[162:165], v[188:191], v[96:99]
	v_mfma_f32_16x16x32_bf16 v[88:91], v[170:173], v[188:191], v[88:91]
	v_mfma_f32_16x16x32_bf16 v[80:83], v[162:165], v[196:199], v[80:83]
	v_mfma_f32_16x16x32_bf16 v[72:75], v[170:173], v[196:199], v[72:75]
	v_mfma_f32_16x16x32_bf16 v[68:71], v[162:165], v[204:207], v[68:71]
	v_mfma_f32_16x16x32_bf16 v[64:67], v[170:173], v[204:207], v[64:67]
	v_mfma_f32_16x16x32_bf16 v[112:115], v[166:169], v[182:185], v[112:115]
	v_mfma_f32_16x16x32_bf16 v[104:107], v[174:177], v[182:185], v[104:107]
	v_mfma_f32_16x16x32_bf16 v[96:99], v[166:169], v[192:195], v[96:99]
	v_mfma_f32_16x16x32_bf16 v[88:91], v[174:177], v[192:195], v[88:91]
	v_mfma_f32_16x16x32_bf16 v[80:83], v[166:169], v[200:203], v[80:83]
	v_mfma_f32_16x16x32_bf16 v[72:75], v[174:177], v[200:203], v[72:75]
	v_mfma_f32_16x16x32_bf16 v[68:71], v[166:169], v[208:211], v[68:71]
	v_mfma_f32_16x16x32_bf16 v[64:67], v[174:177], v[208:211], v[64:67]
	s_barrier
; #define PG8_STAGE(bufoff, gbase, voff) do { _Pragma("unroll") for (int _i = 0; _i < 2; ++_i) \
;         __builtin_amdgcn_global_load_lds((const unsigned*)((const char*)(gbase) + (voff)[_i]), (PG8_LAS unsigned*)(lds + (bufoff) + ldsw + _i * 8192), 16, 0, 0); } while (0)
; #define PG8_LDA(dst, b, h) do { _Pragma("unroll") for (int m = 0; m < 4; ++m) _Pragma("unroll") for (int k = 0; k < 2; ++k) dst[m][k] = *(const PG8_LAS bf16x8*)(lds + PG8_SA(b, h) + aoff + m * 2048 + k * 1024); } while (0)
; #define PG8_MMA(ai, bj, At, Bt) do { __builtin_amdgcn_s_setprio(1); _Pragma("unroll") for (int m = 0; m < 4; ++m) _Pragma("unroll") for (int n = 0; n < 2; ++n) _Pragma("unroll") for (int k = 0; k < 2; ++k) \
;         acc[ai][bj][m][n] = __builtin_amdgcn_mfma_f32_16x16x32_bf16(Bt[n][k], At[m][k], acc[ai][bj][m][n], 0, 0, 0); __builtin_amdgcn_s_setprio(0); } while (0)
; #define PG8_WAIT_V(n) asm volatile("s_waitcnt vmcnt(" #n ")" ::: "memory")
; #define PG8_WAIT_L(n) asm volatile("s_waitcnt lgkmcnt(" #n ")" ::: "memory")
; #define PG8_BAR __builtin_amdgcn_s_barrier()
; #define PG8_SCHED __builtin_amdgcn_sched_barrier(0)
; template <class Epi, class Sched, bool ALIGN_EPI = false, bool SP2 = false>
; __device__ __forceinline__ void gemm_phase(PG8_LAS unsigned char* lds, const Gemm g, const Sched& S, const Epi& E) {
;     ...
;             PG8_LDA(At, 1, 1); PG8_STAGE(PG8_SB(1, 0), b3, voffB); PG8_STAGE(PG8_SB(1, 1), b3 + hstepB, voffB); PG8_STAGE(PG8_SA(1, 0), a3, voffA);
;             PG8_WAIT_V(8); PG8_WAIT_L(0); PG8_BAR; PG8_MMA(1, 0, At, B0); PG8_MMA(1, 1, At, B1); PG8_BAR; PG8_SCHED;
	s_mov_b32 m0, s94
	v_lshl_add_u64 v[212:213], v[212:213], 0, s[10:11]
	ds_read_b128 v[178:181], v145 offset:49152
	ds_read_b128 v[182:185], v145 offset:50176
	ds_read_b128 v[188:191], v145 offset:51200
	ds_read_b128 v[192:195], v145 offset:52224
	ds_read_b128 v[196:199], v145 offset:53248
	ds_read_b128 v[200:203], v145 offset:54272
	ds_read_b128 v[204:207], v145 offset:55296
	ds_read_b128 v[208:211], v145 offset:56320
	global_load_lds_dwordx4 v[212:213], off
	v_lshl_add_u64 v[212:213], v[214:215], 0, s[10:11]
	s_mov_b32 m0, s92
	s_nop 0
	global_load_lds_dwordx4 v[212:213], off
	v_lshl_add_u64 v[212:213], s[40:41], 0, v[132:133]
	s_mov_b32 m0, s93
	s_nop 0
	global_load_lds_dwordx4 v[212:213], off
	v_lshl_add_u64 v[212:213], s[40:41], 0, v[128:129]
	s_mov_b32 m0, s91
	s_nop 0
	global_load_lds_dwordx4 v[212:213], off
	v_lshl_add_u64 v[212:213], v[216:217], 0, s[10:11]
	s_mov_b32 m0, s78
	s_nop 0
	global_load_lds_dwordx4 v[212:213], off
	v_lshl_add_u64 v[212:213], v[218:219], 0, s[10:11]
	s_mov_b32 m0, s79
	s_nop 0
	global_load_lds_dwordx4 v[212:213], off
	s_waitcnt vmcnt(8) lgkmcnt(0)
	s_barrier
	v_mfma_f32_16x16x32_bf16 v[60:63], v[146:149], v[178:181], v[60:63]
	v_mfma_f32_16x16x32_bf16 v[56:59], v[154:157], v[178:181], v[56:59]
	v_mfma_f32_16x16x32_bf16 v[52:55], v[146:149], v[188:191], v[52:55]
	v_mfma_f32_16x16x32_bf16 v[44:47], v[154:157], v[188:191], v[44:47]
	v_mfma_f32_16x16x32_bf16 v[36:39], v[146:149], v[196:199], v[36:39]
	v_mfma_f32_16x16x32_bf16 v[28:31], v[154:157], v[196:199], v[28:31]
	v_mfma_f32_16x16x32_bf16 v[20:23], v[146:149], v[204:207], v[20:23]
	v_mfma_f32_16x16x32_bf16 v[12:15], v[154:157], v[204:207], v[12:15]
	v_mfma_f32_16x16x32_bf16 v[60:63], v[150:153], v[182:185], v[60:63]
	v_mfma_f32_16x16x32_bf16 v[56:59], v[158:161], v[182:185], v[56:59]
	v_mfma_f32_16x16x32_bf16 v[52:55], v[150:153], v[192:195], v[52:55]
	v_mfma_f32_16x16x32_bf16 v[44:47], v[158:161], v[192:195], v[44:47]
	v_mfma_f32_16x16x32_bf16 v[36:39], v[150:153], v[200:203], v[36:39]
	v_mfma_f32_16x16x32_bf16 v[28:31], v[158:161], v[200:203], v[28:31]
	v_mfma_f32_16x16x32_bf16 v[20:23], v[150:153], v[208:211], v[20:23]
	v_mfma_f32_16x16x32_bf16 v[12:15], v[158:161], v[208:211], v[12:15]
	v_mfma_f32_16x16x32_bf16 v[48:51], v[162:165], v[178:181], v[48:51]
	v_mfma_f32_16x16x32_bf16 v[40:43], v[170:173], v[178:181], v[40:43]
	v_mfma_f32_16x16x32_bf16 v[32:35], v[162:165], v[188:191], v[32:35]
	v_mfma_f32_16x16x32_bf16 v[24:27], v[170:173], v[188:191], v[24:27]
	v_mfma_f32_16x16x32_bf16 v[16:19], v[162:165], v[196:199], v[16:19]
	v_mfma_f32_16x16x32_bf16 v[8:11], v[170:173], v[196:199], v[8:11]
	v_mfma_f32_16x16x32_bf16 v[4:7], v[162:165], v[204:207], v[4:7]
	v_mfma_f32_16x16x32_bf16 v[0:3], v[170:173], v[204:207], v[0:3]
	v_mfma_f32_16x16x32_bf16 v[48:51], v[166:169], v[182:185], v[48:51]
	v_mfma_f32_16x16x32_bf16 v[40:43], v[174:177], v[182:185], v[40:43]
	v_mfma_f32_16x16x32_bf16 v[32:35], v[166:169], v[192:195], v[32:35]
	v_mfma_f32_16x16x32_bf16 v[24:27], v[174:177], v[192:195], v[24:27]
	v_mfma_f32_16x16x32_bf16 v[16:19], v[166:169], v[200:203], v[16:19]
	v_mfma_f32_16x16x32_bf16 v[8:11], v[174:177], v[200:203], v[8:11]
	v_mfma_f32_16x16x32_bf16 v[4:7], v[166:169], v[208:211], v[4:7]
	v_mfma_f32_16x16x32_bf16 v[0:3], v[174:177], v[208:211], v[0:3]
	s_barrier
	s_movk_i32 s42, 0x100
	s_andn2_b64 vcc, exec, s[38:39]
	s_mov_b64 s[40:41], -1
	s_mov_b64 s[38:39], 0
	s_cbranch_vccz .LBB0_1161
	s_and_b64 vcc, exec, s[14:15]
	s_cbranch_vccz .LBB0_1164
	s_barrier

; #define PG8_STAGE(bufoff, gbase, voff) do { _Pragma("unroll") for (int _i = 0; _i < 2; ++_i) \
;         __builtin_amdgcn_global_load_lds((const unsigned*)((const char*)(gbase) + (voff)[_i]), (PG8_LAS unsigned*)(lds + (bufoff) + ldsw + _i * 8192), 16, 0, 0); } while (0)
; #define PG8_LDA(dst, b, h) do { _Pragma("unroll") for (int m = 0; m < 4; ++m) _Pragma("unroll") for (int k = 0; k < 2; ++k) dst[m][k] = *(const PG8_LAS bf16x8*)(lds + PG8_SA(b, h) + aoff + m * 2048 + k * 1024); } while (0)
; #define PG8_LDB(dst, b, h) do { _Pragma("unroll") for (int n = 0; n < 2; ++n) _Pragma("unroll") for (int k = 0; k < 2; ++k) dst[n][k] = *(const PG8_LAS bf16x8*)(lds + PG8_SB(b, h) + boff + n * 2048 + k * 1024); } while (0)
; #define PG8_MMA(ai, bj, At, Bt) do { __builtin_amdgcn_s_setprio(1); _Pragma("unroll") for (int m = 0; m < 4; ++m) _Pragma("unroll") for (int n = 0; n < 2; ++n) _Pragma("unroll") for (int k = 0; k < 2; ++k) \
;         acc[ai][bj][m][n] = __builtin_amdgcn_mfma_f32_16x16x32_bf16(Bt[n][k], At[m][k], acc[ai][bj][m][n], 0, 0, 0); __builtin_amdgcn_s_setprio(0); } while (0)
; #define PG8_WAIT_V(n) asm volatile("s_waitcnt vmcnt(" #n ")" ::: "memory")
; #define PG8_WAIT_L(n) asm volatile("s_waitcnt lgkmcnt(" #n ")" ::: "memory")
; #define PG8_BAR __builtin_amdgcn_s_barrier()
; template <class Epi, class Sched, bool ALIGN_EPI = false, bool SP2 = false>
; __device__ __forceinline__ void gemm_phase(PG8_LAS unsigned char* lds, const Gemm g, const Sched& S, const Epi& E) {
;     ...
;             const char* a1 = cA + (size_t)(t + 1) * kstep;
;             const char* a2 = last ? nA : cA + (size_t)(t + 2) * kstep; const char* b2 = last ? nB : cB + (size_t)(t + 2) * kstep;
;             const char* a3 = a2 + kstep; const char* b3 = b2 + kstep;
;             if (last && has_next) S.a_ready(nxt);
;             if constexpr (SP2) {
;             PG8_LDB(B0, 0, 0); PG8_LDB(B1, 0, 1); PG8_SCHED; PG8_LDA(At, 0, 0); PG8_STAGE(PG8_SA(1, 1), a1 + hstepA, voffA);
;             PG8_WAIT_V(8); PG8_WAIT_L(0); PG8_BAR; PG8_MMA(0, 0, At, B0); PG8_MMA(0, 1, At, B1); PG8_BAR; PG8_SCHED;
;             PG8_LDA(At, 0, 1); PG8_STAGE(PG8_SB(0, 0), b2, voffB); PG8_STAGE(PG8_SB(0, 1), b2 + hstepB, voffB); PG8_STAGE(PG8_SA(0, 0), a2, voffA);
;             PG8_WAIT_V(8); PG8_WAIT_L(0); PG8_BAR; PG8_MMA(1, 0, At, B0); PG8_MMA(1, 1, At, B1); PG8_BAR; PG8_SCHED;
.LBB0_1231:
	ds_read_b128 v[112:115], v185
	ds_read_b128 v[116:119], v185 offset:1024
	ds_read_b128 v[128:131], v185 offset:2048
	ds_read_b128 v[140:143], v185 offset:3072
	ds_read_b128 v[144:147], v188
	ds_read_b128 v[148:151], v188 offset:1024
	ds_read_b128 v[168:171], v188 offset:2048
	ds_read_b128 v[172:175], v188 offset:3072
	s_add_u32 s34, s30, 0xfffc0080
	s_addc_u32 s35, s31, -1
	s_cmp_eq_u32 s69, 12
	s_cselect_b32 s37, s21, s35
	s_cselect_b32 s36, s27, s34
	s_cselect_b32 s35, s19, s68
	s_cselect_b32 s34, s66, s67
	v_lshl_add_u64 v[180:181], s[30:31], 0, v[160:161]
	s_add_i32 m0, s29, 0xc000
	ds_read_b128 v[176:179], v189
	ds_read_b128 v[192:195], v189 offset:1024
	ds_read_b128 v[196:199], v189 offset:2048
	ds_read_b128 v[200:203], v189 offset:3072
	ds_read_b128 v[204:207], v189 offset:4096
	ds_read_b128 v[208:211], v189 offset:5120
	ds_read_b128 v[212:215], v189 offset:6144
	ds_read_b128 v[216:219], v189 offset:7168
	global_load_lds_dwordx4 v[180:181], off
	v_lshl_add_u64 v[180:181], s[30:31], 0, v[162:163]
	s_add_i32 m0, s29, 0xe000
	s_nop 0
	global_load_lds_dwordx4 v[180:181], off
	s_waitcnt vmcnt(8) lgkmcnt(0)
	s_barrier
	v_mfma_f32_16x16x32_bf16 v[136:139], v[112:115], v[176:179], v[136:139]
	v_mfma_f32_16x16x32_bf16 v[132:135], v[128:131], v[176:179], v[132:135]
	v_mfma_f32_16x16x32_bf16 v[108:111], v[112:115], v[196:199], v[108:111]
	v_mfma_f32_16x16x32_bf16 v[104:107], v[128:131], v[196:199], v[104:107]
	v_mfma_f32_16x16x32_bf16 v[92:95], v[112:115], v[204:207], v[92:95]
	v_mfma_f32_16x16x32_bf16 v[88:91], v[128:131], v[204:207], v[88:91]
	v_mfma_f32_16x16x32_bf16 v[76:79], v[112:115], v[212:215], v[76:79]
	v_mfma_f32_16x16x32_bf16 v[72:75], v[128:131], v[212:215], v[72:75]
	v_mfma_f32_16x16x32_bf16 v[136:139], v[116:119], v[192:195], v[136:139]
	v_mfma_f32_16x16x32_bf16 v[132:135], v[140:143], v[192:195], v[132:135]
	v_mfma_f32_16x16x32_bf16 v[108:111], v[116:119], v[200:203], v[108:111]
	v_mfma_f32_16x16x32_bf16 v[104:107], v[140:143], v[200:203], v[104:107]
	v_mfma_f32_16x16x32_bf16 v[92:95], v[116:119], v[208:211], v[92:95]
	v_mfma_f32_16x16x32_bf16 v[88:91], v[140:143], v[208:211], v[88:91]
	v_mfma_f32_16x16x32_bf16 v[76:79], v[116:119], v[216:219], v[76:79]
	v_mfma_f32_16x16x32_bf16 v[72:75], v[140:143], v[216:219], v[72:75]
	v_mfma_f32_16x16x32_bf16 v[124:127], v[144:147], v[176:179], v[124:127]
	v_mfma_f32_16x16x32_bf16 v[120:123], v[168:171], v[176:179], v[120:123]
	v_mfma_f32_16x16x32_bf16 v[100:103], v[144:147], v[196:199], v[100:103]
	v_mfma_f32_16x16x32_bf16 v[96:99], v[168:171], v[196:199], v[96:99]
	v_mfma_f32_16x16x32_bf16 v[84:87], v[144:147], v[204:207], v[84:87]
	v_mfma_f32_16x16x32_bf16 v[80:83], v[168:171], v[204:207], v[80:83]
	v_mfma_f32_16x16x32_bf16 v[68:71], v[144:147], v[212:215], v[68:71]
	v_mfma_f32_16x16x32_bf16 v[64:67], v[168:171], v[212:215], v[64:67]
	v_mfma_f32_16x16x32_bf16 v[124:127], v[148:151], v[192:195], v[124:127]
	v_mfma_f32_16x16x32_bf16 v[120:123], v[172:175], v[192:195], v[120:123]
	v_mfma_f32_16x16x32_bf16 v[100:103], v[148:151], v[200:203], v[100:103]
	v_mfma_f32_16x16x32_bf16 v[96:99], v[172:175], v[200:203], v[96:99]
	v_mfma_f32_16x16x32_bf16 v[84:87], v[148:151], v[208:211], v[84:87]
	v_mfma_f32_16x16x32_bf16 v[80:83], v[172:175], v[208:211], v[80:83]
	v_mfma_f32_16x16x32_bf16 v[68:71], v[148:151], v[216:219], v[68:71]
	v_mfma_f32_16x16x32_bf16 v[64:67], v[172:175], v[216:219], v[64:67]
	s_barrier
	s_add_i32 s58, s49, s39
	v_lshl_add_u64 v[180:181], s[34:35], 0, v[154:155]
	s_mov_b32 m0, s58
	ds_read_b128 v[176:179], v189 offset:16384
	ds_read_b128 v[192:195], v189 offset:17408
	ds_read_b128 v[196:199], v189 offset:18432
	ds_read_b128 v[200:203], v189 offset:19456
	ds_read_b128 v[204:207], v189 offset:20480
	ds_read_b128 v[208:211], v189 offset:21504
	ds_read_b128 v[212:215], v189 offset:22528
	ds_read_b128 v[216:219], v189 offset:23552
	global_load_lds_dwordx4 v[180:181], off
	s_add_i32 m0, s58, 0x2000
	s_add_u32 s58, s34, 0x40000
	v_lshl_add_u64 v[220:221], s[34:35], 0, v[158:159]
	s_addc_u32 s59, s35, 0
	s_add_i32 s73, s64, s39
	global_load_lds_dwordx4 v[220:221], off
	v_lshl_add_u64 v[222:223], s[58:59], 0, v[154:155]
	s_mov_b32 m0, s73
	v_lshl_add_u64 v[224:225], s[36:37], 0, v[156:157]
	global_load_lds_dwordx4 v[222:223], off
	v_lshl_add_u64 v[222:223], s[58:59], 0, v[158:159]
	s_add_i32 m0, s73, 0x2000
	s_nop 0
	global_load_lds_dwordx4 v[222:223], off
	v_lshl_add_u64 v[222:223], s[36:37], 0, v[152:153]
	s_mov_b32 m0, s29
	s_nop 0
	global_load_lds_dwordx4 v[222:223], off
	s_mov_b32 m0, s40
	s_nop 0
	global_load_lds_dwordx4 v[224:225], off
	s_waitcnt vmcnt(8) lgkmcnt(0)
	s_barrier
; #define PG8_STAGE(bufoff, gbase, voff) do { _Pragma("unroll") for (int _i = 0; _i < 2; ++_i) \
;         __builtin_amdgcn_global_load_lds((const unsigned*)((const char*)(gbase) + (voff)[_i]), (PG8_LAS unsigned*)(lds + (bufoff) + ldsw + _i * 8192), 16, 0, 0); } while (0)
; #define PG8_LDA(dst, b, h) do { _Pragma("unroll") for (int m = 0; m < 4; ++m) _Pragma("unroll") for (int k = 0; k < 2; ++k) dst[m][k] = *(const PG8_LAS bf16x8*)(lds + PG8_SA(b, h) + aoff + m * 2048 + k * 1024); } while (0)
; #define PG8_LDB(dst, b, h) do { _Pragma("unroll") for (int n = 0; n < 2; ++n) _Pragma("unroll") for (int k = 0; k < 2; ++k) dst[n][k] = *(const PG8_LAS bf16x8*)(lds + PG8_SB(b, h) + boff + n * 2048 + k * 1024); } while (0)
; #define PG8_MMA(ai, bj, At, Bt) do { __builtin_amdgcn_s_setprio(1); _Pragma("unroll") for (int m = 0; m < 4; ++m) _Pragma("unroll") for (int n = 0; n < 2; ++n) _Pragma("unroll") for (int k = 0; k < 2; ++k) \
;         acc[ai][bj][m][n] = __builtin_amdgcn_mfma_f32_16x16x32_bf16(Bt[n][k], At[m][k], acc[ai][bj][m][n], 0, 0, 0); __builtin_amdgcn_s_setprio(0); } while (0)
; #define PG8_WAIT_V(n) asm volatile("s_waitcnt vmcnt(" #n ")" ::: "memory")
; #define PG8_WAIT_L(n) asm volatile("s_waitcnt lgkmcnt(" #n ")" ::: "memory")
; #define PG8_BAR __builtin_amdgcn_s_barrier()
; #define PG8_SCHED __builtin_amdgcn_sched_barrier(0)
; template <class Epi, class Sched, bool ALIGN_EPI = false, bool SP2 = false>
; __device__ __forceinline__ void gemm_phase(PG8_LAS unsigned char* lds, const Gemm g, const Sched& S, const Epi& E) {
;     ...
;             PG8_WAIT_V(8); PG8_WAIT_L(0); PG8_BAR; PG8_MMA(1, 0, At, B0); PG8_MMA(1, 1, At, B1); PG8_BAR; PG8_SCHED;
;             PG8_LDB(B0, 1, 0); PG8_LDB(B1, 1, 1); PG8_SCHED; PG8_LDA(At, 1, 0); PG8_STAGE(PG8_SA(0, 1), a2 + hstepA, voffA);
;             PG8_WAIT_V(8); PG8_WAIT_L(0); PG8_BAR; PG8_MMA(0, 0, At, B0); PG8_MMA(0, 1, At, B1); PG8_BAR; PG8_SCHED;
	v_mfma_f32_16x16x32_bf16 v[60:63], v[112:115], v[176:179], v[60:63]
	v_mfma_f32_16x16x32_bf16 v[56:59], v[128:131], v[176:179], v[56:59]
	v_mfma_f32_16x16x32_bf16 v[44:47], v[112:115], v[196:199], v[44:47]
	v_mfma_f32_16x16x32_bf16 v[40:43], v[128:131], v[196:199], v[40:43]
	v_mfma_f32_16x16x32_bf16 v[28:31], v[112:115], v[204:207], v[28:31]
	v_mfma_f32_16x16x32_bf16 v[24:27], v[128:131], v[204:207], v[24:27]
	v_mfma_f32_16x16x32_bf16 v[12:15], v[112:115], v[212:215], v[12:15]
	v_mfma_f32_16x16x32_bf16 v[8:11], v[128:131], v[212:215], v[8:11]
	v_mfma_f32_16x16x32_bf16 v[60:63], v[116:119], v[192:195], v[60:63]
	v_mfma_f32_16x16x32_bf16 v[56:59], v[140:143], v[192:195], v[56:59]
	v_mfma_f32_16x16x32_bf16 v[44:47], v[116:119], v[200:203], v[44:47]
	v_mfma_f32_16x16x32_bf16 v[40:43], v[140:143], v[200:203], v[40:43]
	v_mfma_f32_16x16x32_bf16 v[28:31], v[116:119], v[208:211], v[28:31]
	v_mfma_f32_16x16x32_bf16 v[24:27], v[140:143], v[208:211], v[24:27]
	v_mfma_f32_16x16x32_bf16 v[12:15], v[116:119], v[216:219], v[12:15]
	v_mfma_f32_16x16x32_bf16 v[8:11], v[140:143], v[216:219], v[8:11]
	v_mfma_f32_16x16x32_bf16 v[52:55], v[144:147], v[176:179], v[52:55]
	v_mfma_f32_16x16x32_bf16 v[48:51], v[168:171], v[176:179], v[48:51]
	v_mfma_f32_16x16x32_bf16 v[36:39], v[144:147], v[196:199], v[36:39]
	v_mfma_f32_16x16x32_bf16 v[32:35], v[168:171], v[196:199], v[32:35]
	v_mfma_f32_16x16x32_bf16 v[20:23], v[144:147], v[204:207], v[20:23]
	v_mfma_f32_16x16x32_bf16 v[16:19], v[168:171], v[204:207], v[16:19]
	v_mfma_f32_16x16x32_bf16 v[4:7], v[144:147], v[212:215], v[4:7]
	v_mfma_f32_16x16x32_bf16 v[0:3], v[168:171], v[212:215], v[0:3]
	v_mfma_f32_16x16x32_bf16 v[52:55], v[148:151], v[192:195], v[52:55]
	v_mfma_f32_16x16x32_bf16 v[48:51], v[172:175], v[192:195], v[48:51]
	v_mfma_f32_16x16x32_bf16 v[36:39], v[148:151], v[200:203], v[36:39]
	v_mfma_f32_16x16x32_bf16 v[32:35], v[172:175], v[200:203], v[32:35]
	v_mfma_f32_16x16x32_bf16 v[20:23], v[148:151], v[208:211], v[20:23]
	v_mfma_f32_16x16x32_bf16 v[16:19], v[172:175], v[208:211], v[16:19]
	v_mfma_f32_16x16x32_bf16 v[4:7], v[148:151], v[216:219], v[4:7]
	v_mfma_f32_16x16x32_bf16 v[0:3], v[172:175], v[216:219], v[0:3]
	s_barrier
	s_add_i32 s58, 0, 0x18000
	s_add_i32 s59, 0, 0x1c000
	v_add_u32_e32 v140, s58, v183
	v_add_u32_e32 v172, s59, v183
	ds_read_b128 v[112:115], v140
	ds_read_b128 v[116:119], v140 offset:1024
	ds_read_b128 v[128:131], v140 offset:2048
	ds_read_b128 v[140:143], v140 offset:3072
	ds_read_b128 v[144:147], v172
	ds_read_b128 v[148:151], v172 offset:1024
	ds_read_b128 v[168:171], v172 offset:2048
	ds_read_b128 v[172:175], v172 offset:3072
	s_add_u32 s36, s36, 0x40000
	s_addc_u32 s37, s37, 0
	s_mov_b32 m0, s41
	v_lshl_add_u64 v[226:227], s[36:37], 0, v[152:153]
	ds_read_b128 v[176:179], v189 offset:32768
	ds_read_b128 v[192:195], v189 offset:33792
	ds_read_b128 v[196:199], v189 offset:34816
	ds_read_b128 v[200:203], v189 offset:35840
	ds_read_b128 v[204:207], v189 offset:36864
	ds_read_b128 v[208:211], v189 offset:37888
	ds_read_b128 v[212:215], v189 offset:38912
	ds_read_b128 v[216:219], v189 offset:39936
	global_load_lds_dwordx4 v[226:227], off
	v_lshl_add_u64 v[226:227], s[36:37], 0, v[156:157]
	s_mov_b32 m0, s42
	s_nop 0
	global_load_lds_dwordx4 v[226:227], off
	s_waitcnt vmcnt(8) lgkmcnt(0)
	s_barrier
	v_mfma_f32_16x16x32_bf16 v[136:139], v[112:115], v[176:179], v[136:139]
	v_mfma_f32_16x16x32_bf16 v[132:135], v[128:131], v[176:179], v[132:135]
	v_mfma_f32_16x16x32_bf16 v[108:111], v[112:115], v[196:199], v[108:111]
	v_mfma_f32_16x16x32_bf16 v[104:107], v[128:131], v[196:199], v[104:107]
	v_mfma_f32_16x16x32_bf16 v[92:95], v[112:115], v[204:207], v[92:95]
	v_mfma_f32_16x16x32_bf16 v[88:91], v[128:131], v[204:207], v[88:91]
	v_mfma_f32_16x16x32_bf16 v[76:79], v[112:115], v[212:215], v[76:79]
	v_mfma_f32_16x16x32_bf16 v[72:75], v[128:131], v[212:215], v[72:75]
	v_mfma_f32_16x16x32_bf16 v[136:139], v[116:119], v[192:195], v[136:139]
	v_mfma_f32_16x16x32_bf16 v[132:135], v[140:143], v[192:195], v[132:135]
	v_mfma_f32_16x16x32_bf16 v[108:111], v[116:119], v[200:203], v[108:111]
	v_mfma_f32_16x16x32_bf16 v[104:107], v[140:143], v[200:203], v[104:107]
	v_mfma_f32_16x16x32_bf16 v[92:95], v[116:119], v[208:211], v[92:95]
	v_mfma_f32_16x16x32_bf16 v[88:91], v[140:143], v[208:211], v[88:91]
	v_mfma_f32_16x16x32_bf16 v[76:79], v[116:119], v[216:219], v[76:79]
	v_mfma_f32_16x16x32_bf16 v[72:75], v[140:143], v[216:219], v[72:75]
	v_mfma_f32_16x16x32_bf16 v[124:127], v[144:147], v[176:179], v[124:127]
	v_mfma_f32_16x16x32_bf16 v[120:123], v[168:171], v[176:179], v[120:123]
	v_mfma_f32_16x16x32_bf16 v[100:103], v[144:147], v[196:199], v[100:103]
	v_mfma_f32_16x16x32_bf16 v[96:99], v[168:171], v[196:199], v[96:99]
	v_mfma_f32_16x16x32_bf16 v[84:87], v[144:147], v[204:207], v[84:87]
	v_mfma_f32_16x16x32_bf16 v[80:83], v[168:171], v[204:207], v[80:83]
	v_mfma_f32_16x16x32_bf16 v[68:71], v[144:147], v[212:215], v[68:71]
	v_mfma_f32_16x16x32_bf16 v[64:67], v[168:171], v[212:215], v[64:67]
	v_mfma_f32_16x16x32_bf16 v[124:127], v[148:151], v[192:195], v[124:127]
	v_mfma_f32_16x16x32_bf16 v[120:123], v[172:175], v[192:195], v[120:123]
	v_mfma_f32_16x16x32_bf16 v[100:103], v[148:151], v[200:203], v[100:103]
	v_mfma_f32_16x16x32_bf16 v[96:99], v[172:175], v[200:203], v[96:99]
	v_mfma_f32_16x16x32_bf16 v[84:87], v[148:151], v[208:211], v[84:87]
	v_mfma_f32_16x16x32_bf16 v[80:83], v[172:175], v[208:211], v[80:83]
	v_mfma_f32_16x16x32_bf16 v[68:71], v[148:151], v[216:219], v[68:71]
	v_mfma_f32_16x16x32_bf16 v[64:67], v[172:175], v[216:219], v[64:67]
	s_barrier
; #define PG8_STAGE(bufoff, gbase, voff) do { _Pragma("unroll") for (int _i = 0; _i < 2; ++_i) \
;         __builtin_amdgcn_global_load_lds((const unsigned*)((const char*)(gbase) + (voff)[_i]), (PG8_LAS unsigned*)(lds + (bufoff) + ldsw + _i * 8192), 16, 0, 0); } while (0)
; #define PG8_LDA(dst, b, h) do { _Pragma("unroll") for (int m = 0; m < 4; ++m) _Pragma("unroll") for (int k = 0; k < 2; ++k) dst[m][k] = *(const PG8_LAS bf16x8*)(lds + PG8_SA(b, h) + aoff + m * 2048 + k * 1024); } while (0)
; #define PG8_MMA(ai, bj, At, Bt) do { __builtin_amdgcn_s_setprio(1); _Pragma("unroll") for (int m = 0; m < 4; ++m) _Pragma("unroll") for (int n = 0; n < 2; ++n) _Pragma("unroll") for (int k = 0; k < 2; ++k) \
;         acc[ai][bj][m][n] = __builtin_amdgcn_mfma_f32_16x16x32_bf16(Bt[n][k], At[m][k], acc[ai][bj][m][n], 0, 0, 0); __builtin_amdgcn_s_setprio(0); } while (0)
; #define PG8_WAIT_V(n) asm volatile("s_waitcnt vmcnt(" #n ")" ::: "memory")
; #define PG8_WAIT_L(n) asm volatile("s_waitcnt lgkmcnt(" #n ")" ::: "memory")
; #define PG8_BAR __builtin_amdgcn_s_barrier()
; #define PG8_SCHED __builtin_amdgcn_sched_barrier(0)
; template <class Epi, class Sched, bool ALIGN_EPI = false, bool SP2 = false>
; __device__ __forceinline__ void gemm_phase(PG8_LAS unsigned char* lds, const Gemm g, const Sched& S, const Epi& E) {
;     ...
;             PG8_LDA(At, 1, 1); PG8_STAGE(PG8_SB(1, 0), b3, voffB); PG8_STAGE(PG8_SB(1, 1), b3 + hstepB, voffB); PG8_STAGE(PG8_SA(1, 0), a3, voffA);
;             PG8_WAIT_V(8); PG8_WAIT_L(0); PG8_BAR; PG8_MMA(1, 0, At, B0); PG8_MMA(1, 1, At, B1); PG8_BAR; PG8_SCHED;
	s_add_i32 s36, s58, s39
	v_lshl_add_u64 v[180:181], v[180:181], 0, s[14:15]
	s_mov_b32 m0, s36
	ds_read_b128 v[176:179], v189 offset:49152
	ds_read_b128 v[192:195], v189 offset:50176
	ds_read_b128 v[196:199], v189 offset:51200
	ds_read_b128 v[200:203], v189 offset:52224
	ds_read_b128 v[204:207], v189 offset:53248
	ds_read_b128 v[208:211], v189 offset:54272
	ds_read_b128 v[212:215], v189 offset:55296
	ds_read_b128 v[216:219], v189 offset:56320
	global_load_lds_dwordx4 v[180:181], off
	s_add_i32 m0, s36, 0x2000
	s_add_u32 s34, s34, 0x40080
	v_lshl_add_u64 v[180:181], v[220:221], 0, s[14:15]
	s_addc_u32 s35, s35, 0
	s_add_i32 s36, s59, s39
	global_load_lds_dwordx4 v[180:181], off
	v_lshl_add_u64 v[180:181], s[34:35], 0, v[154:155]
	s_mov_b32 m0, s36
	s_nop 0
	global_load_lds_dwordx4 v[180:181], off
	v_lshl_add_u64 v[180:181], s[34:35], 0, v[158:159]
	s_add_i32 m0, s36, 0x2000
	s_nop 0
	global_load_lds_dwordx4 v[180:181], off
	v_lshl_add_u64 v[180:181], v[222:223], 0, s[14:15]
	s_mov_b32 m0, s44
	s_nop 0
	global_load_lds_dwordx4 v[180:181], off
	v_lshl_add_u64 v[180:181], v[224:225], 0, s[14:15]
	s_mov_b32 m0, s45
	s_nop 0
	global_load_lds_dwordx4 v[180:181], off
	s_waitcnt vmcnt(8) lgkmcnt(0)
	s_barrier
	v_mfma_f32_16x16x32_bf16 v[60:63], v[112:115], v[176:179], v[60:63]
	v_mfma_f32_16x16x32_bf16 v[56:59], v[128:131], v[176:179], v[56:59]
	v_mfma_f32_16x16x32_bf16 v[44:47], v[112:115], v[196:199], v[44:47]
	v_mfma_f32_16x16x32_bf16 v[40:43], v[128:131], v[196:199], v[40:43]
	v_mfma_f32_16x16x32_bf16 v[28:31], v[112:115], v[204:207], v[28:31]
	v_mfma_f32_16x16x32_bf16 v[24:27], v[128:131], v[204:207], v[24:27]
	v_mfma_f32_16x16x32_bf16 v[12:15], v[112:115], v[212:215], v[12:15]
	v_mfma_f32_16x16x32_bf16 v[8:11], v[128:131], v[212:215], v[8:11]
	v_mfma_f32_16x16x32_bf16 v[60:63], v[116:119], v[192:195], v[60:63]
	v_mfma_f32_16x16x32_bf16 v[56:59], v[140:143], v[192:195], v[56:59]
	v_mfma_f32_16x16x32_bf16 v[44:47], v[116:119], v[200:203], v[44:47]
	v_mfma_f32_16x16x32_bf16 v[40:43], v[140:143], v[200:203], v[40:43]
	v_mfma_f32_16x16x32_bf16 v[28:31], v[116:119], v[208:211], v[28:31]
	v_mfma_f32_16x16x32_bf16 v[24:27], v[140:143], v[208:211], v[24:27]
	v_mfma_f32_16x16x32_bf16 v[12:15], v[116:119], v[216:219], v[12:15]
	v_mfma_f32_16x16x32_bf16 v[8:11], v[140:143], v[216:219], v[8:11]
	v_mfma_f32_16x16x32_bf16 v[52:55], v[144:147], v[176:179], v[52:55]
	v_mfma_f32_16x16x32_bf16 v[48:51], v[168:171], v[176:179], v[48:51]
	v_mfma_f32_16x16x32_bf16 v[36:39], v[144:147], v[196:199], v[36:39]
	v_mfma_f32_16x16x32_bf16 v[32:35], v[168:171], v[196:199], v[32:35]
	v_mfma_f32_16x16x32_bf16 v[20:23], v[144:147], v[204:207], v[20:23]
	v_mfma_f32_16x16x32_bf16 v[16:19], v[168:171], v[204:207], v[16:19]
	v_mfma_f32_16x16x32_bf16 v[4:7], v[144:147], v[212:215], v[4:7]
	v_mfma_f32_16x16x32_bf16 v[0:3], v[168:171], v[212:215], v[0:3]
	v_mfma_f32_16x16x32_bf16 v[52:55], v[148:151], v[192:195], v[52:55]
	v_mfma_f32_16x16x32_bf16 v[48:51], v[172:175], v[192:195], v[48:51]
	v_mfma_f32_16x16x32_bf16 v[36:39], v[148:151], v[200:203], v[36:39]
	v_mfma_f32_16x16x32_bf16 v[32:35], v[172:175], v[200:203], v[32:35]
	v_mfma_f32_16x16x32_bf16 v[20:23], v[148:151], v[208:211], v[20:23]
	v_mfma_f32_16x16x32_bf16 v[16:19], v[172:175], v[208:211], v[16:19]
	v_mfma_f32_16x16x32_bf16 v[4:7], v[148:151], v[216:219], v[4:7]
	v_mfma_f32_16x16x32_bf16 v[0:3], v[172:175], v[216:219], v[0:3]
	s_barrier
	s_add_i32 s69, s69, 2
	s_add_u32 s30, s30, 0x100
	s_addc_u32 s31, s31, 0
	s_add_u32 s67, s67, 0x100
	s_addc_u32 s68, s68, 0
	s_cmp_gt_u32 s69, 13
	s_cbranch_scc0 .LBB0_1231
	s_and_b64 vcc, exec, s[16:17]
	s_cbranch_vccz .LBB0_1234
	s_barrier
